# removed the redundant lgkmcnt waits and back-to-back setprio pairs inside the GEMM MFMA runs (an explicit lgkmcnt(0) precedes each run); on top of gate re-layout
# speedup vs baseline: 1.0049x; 1.0049x over previous
; #define PG8_STAGEX(rs, bufoff, soff, voff) do { _Pragma("unroll") for (int _i = 0; _i < 2; ++_i) \
;         __builtin_amdgcn_raw_ptr_buffer_load_lds(rs, (LAS unsigned*)(lds + (bufoff) + ldsw + _i * 8192), 16, (voff)[_i], (soff), 0, 0); } while (0)
; #define PG8_LDA(dst, b, h) do { _Pragma("unroll") for (int m = 0; m < 4; ++m) _Pragma("unroll") for (int k = 0; k < 2; ++k) dst[m][k] = *(const LAS bf16x8*)(lds + PG8_SA(b, h) + aoff + m * 2048 + k * 1024); } while (0)
; #define PG8_LDB(dst, b, h) do { _Pragma("unroll") for (int n = 0; n < 2; ++n) _Pragma("unroll") for (int k = 0; k < 2; ++k) dst[n][k] = *(const LAS bf16x8*)(lds + PG8_SB(b, h) + boff + n * 2048 + k * 1024); } while (0)
; #define PG8_WAIT_V(n) asm volatile("s_waitcnt vmcnt(" #n ")" ::: "memory")
; #define PG8_WAIT_L(n) asm volatile("s_waitcnt lgkmcnt(" #n ")" ::: "memory")
; #define PG8_BAR __builtin_amdgcn_s_barrier()
; #define PG8_SCHED __builtin_amdgcn_sched_barrier(0)
;     ...
;             PG8_LDB(B0, 0, 0); PG8_LDB(B1, 0, 1); PG8_SCHED; PG8_LDA(At, 0, 0); PG8_STAGEX(rsA, PG8_SA(1, 1), a1 + hstepA, voffA);
;             PG8_WAIT_V(8); PG8_WAIT_L(0); PG8_BAR; PG8_MMA(0, 0, At, B0); PG8_MMA(0, 1, At, B1); PG8_BAR; PG8_SCHED;
;             PG8_LDA(At, 0, 1); PG8_STAGEX(rsB, PG8_SB(0, 0), b2, voffB); PG8_STAGEX(rsB, PG8_SB(0, 1), b2 + hstepB, voffB); PG8_STAGEX(rsA, PG8_SA(0, 0), a2, voffA);
;             PG8_WAIT_V(8); PG8_WAIT_L(0); PG8_BAR; PG8_MMA(1, 0, At, B0); PG8_MMA(1, 1, At, B1); PG8_BAR; PG8_SCHED;
.LBB0_223:
	v_add_u32_e32 v102, 0x10000, v172
	v_add_u32_e32 v146, 0x14000, v172
	ds_read_b128 v[82:85], v102
	ds_read_b128 v[86:89], v102 offset:1024
	ds_read_b128 v[98:101], v102 offset:2048
	ds_read_b128 v[102:105], v102 offset:3072
	ds_read_b128 v[150:153], v146
	ds_read_b128 v[154:157], v146 offset:1024
	ds_read_b128 v[182:185], v146 offset:2048
	ds_read_b128 v[186:189], v146 offset:3072
	s_add_i32 s42, s50, 0xfff80080
	s_cmp_eq_u32 s52, 28
	s_cselect_b32 s55, s30, s42
	s_cselect_b32 s54, s31, s51
	s_or_b32 s53, s55, 0x80
	s_mov_b32 m0, s22
	ds_read_b128 v[190:193], v173
	ds_read_b128 v[194:197], v173 offset:1024
	ds_read_b128 v[198:201], v173 offset:2048
	ds_read_b128 v[202:205], v173 offset:3072
	ds_read_b128 v[206:209], v173 offset:4096
	ds_read_b128 v[210:213], v173 offset:5120
	ds_read_b128 v[214:217], v173 offset:6144
	ds_read_b128 v[218:221], v173 offset:7168
	buffer_load_dwordx4 v159, s[76:79], s50 offen lds
	s_mov_b32 m0, s23
	s_nop 0
	buffer_load_dwordx4 v163, s[76:79], s50 offen lds
	s_waitcnt vmcnt(8)
	s_waitcnt lgkmcnt(0)
	s_barrier
	s_setprio 1
	v_mfma_f32_16x16x32_bf16 v[142:145], v[82:85], v[190:193], v[142:145]
	v_mfma_f32_16x16x32_bf16 v[134:137], v[98:101], v[190:193], v[134:137]
	v_mfma_f32_16x16x32_bf16 v[126:129], v[82:85], v[198:201], v[126:129]
	v_mfma_f32_16x16x32_bf16 v[118:121], v[98:101], v[198:201], v[118:121]
	v_mfma_f32_16x16x32_bf16 v[110:113], v[82:85], v[206:209], v[110:113]
	v_mfma_f32_16x16x32_bf16 v[94:97], v[98:101], v[206:209], v[94:97]
	v_mfma_f32_16x16x32_bf16 v[78:81], v[82:85], v[214:217], v[78:81]
	v_mfma_f32_16x16x32_bf16 v[70:73], v[98:101], v[214:217], v[70:73]
	v_mfma_f32_16x16x32_bf16 v[142:145], v[86:89], v[194:197], v[142:145]
	v_mfma_f32_16x16x32_bf16 v[134:137], v[102:105], v[194:197], v[134:137]
	v_mfma_f32_16x16x32_bf16 v[126:129], v[86:89], v[202:205], v[126:129]
	v_mfma_f32_16x16x32_bf16 v[118:121], v[102:105], v[202:205], v[118:121]
	v_mfma_f32_16x16x32_bf16 v[110:113], v[86:89], v[210:213], v[110:113]
	v_mfma_f32_16x16x32_bf16 v[94:97], v[102:105], v[210:213], v[94:97]
	v_mfma_f32_16x16x32_bf16 v[78:81], v[86:89], v[218:221], v[78:81]
	v_mfma_f32_16x16x32_bf16 v[70:73], v[102:105], v[218:221], v[70:73]
	v_mfma_f32_16x16x32_bf16 v[138:141], v[150:153], v[190:193], v[138:141]
	v_mfma_f32_16x16x32_bf16 v[130:133], v[182:185], v[190:193], v[130:133]
	v_mfma_f32_16x16x32_bf16 v[122:125], v[150:153], v[198:201], v[122:125]
	v_mfma_f32_16x16x32_bf16 v[114:117], v[182:185], v[198:201], v[114:117]
	v_mfma_f32_16x16x32_bf16 v[106:109], v[150:153], v[206:209], v[106:109]
	v_mfma_f32_16x16x32_bf16 v[90:93], v[182:185], v[206:209], v[90:93]
	v_mfma_f32_16x16x32_bf16 v[74:77], v[150:153], v[214:217], v[74:77]
	v_mfma_f32_16x16x32_bf16 v[66:69], v[182:185], v[214:217], v[66:69]
	v_mfma_f32_16x16x32_bf16 v[138:141], v[154:157], v[194:197], v[138:141]
	v_mfma_f32_16x16x32_bf16 v[130:133], v[186:189], v[194:197], v[130:133]
	v_mfma_f32_16x16x32_bf16 v[122:125], v[154:157], v[202:205], v[122:125]
	v_mfma_f32_16x16x32_bf16 v[114:117], v[186:189], v[202:205], v[114:117]
	v_mfma_f32_16x16x32_bf16 v[106:109], v[154:157], v[210:213], v[106:109]
	v_mfma_f32_16x16x32_bf16 v[90:93], v[186:189], v[210:213], v[90:93]
	v_mfma_f32_16x16x32_bf16 v[74:77], v[154:157], v[218:221], v[74:77]
	v_mfma_f32_16x16x32_bf16 v[66:69], v[186:189], v[218:221], v[66:69]
	s_setprio 0
	s_barrier
	s_mov_b32 m0, s9
	s_mov_b32 s42, s78
	s_mov_b32 s43, s79
	ds_read_b128 v[190:193], v173 offset:16384
	ds_read_b128 v[194:197], v173 offset:17408
	ds_read_b128 v[198:201], v173 offset:18432
	ds_read_b128 v[202:205], v173 offset:19456
	ds_read_b128 v[206:209], v173 offset:20480
	ds_read_b128 v[210:213], v173 offset:21504
	ds_read_b128 v[214:217], v173 offset:22528
	ds_read_b128 v[218:221], v173 offset:23552
	buffer_load_dwordx4 v161, s[40:43], s54 offen lds
	s_mov_b32 m0, s10
	s_add_i32 s56, s54, 0x80000
	buffer_load_dwordx4 v165, s[40:43], s54 offen lds
	s_mov_b32 m0, s11
	s_nop 0
	buffer_load_dwordx4 v161, s[40:43], s56 offen lds
	s_mov_b32 m0, s12
	s_nop 0
	buffer_load_dwordx4 v165, s[40:43], s56 offen lds
	s_mov_b32 m0, s8
	s_nop 0
	buffer_load_dwordx4 v159, s[76:79], s55 offen lds
	s_mov_b32 m0, s13
	s_nop 0
	buffer_load_dwordx4 v163, s[76:79], s55 offen lds
	s_waitcnt vmcnt(8)
	s_waitcnt lgkmcnt(0)
	s_barrier
	s_setprio 1
	v_mfma_f32_16x16x32_bf16 v[62:65], v[82:85], v[190:193], v[62:65]
	v_mfma_f32_16x16x32_bf16 v[54:57], v[98:101], v[190:193], v[54:57]
	v_mfma_f32_16x16x32_bf16 v[46:49], v[82:85], v[198:201], v[46:49]
	v_mfma_f32_16x16x32_bf16 v[38:41], v[98:101], v[198:201], v[38:41]
	v_mfma_f32_16x16x32_bf16 v[30:33], v[82:85], v[206:209], v[30:33]
	v_mfma_f32_16x16x32_bf16 v[22:25], v[98:101], v[206:209], v[22:25]
	v_mfma_f32_16x16x32_bf16 v[14:17], v[82:85], v[214:217], v[14:17]
	v_mfma_f32_16x16x32_bf16 v[6:9], v[98:101], v[214:217], v[6:9]
	v_mfma_f32_16x16x32_bf16 v[62:65], v[86:89], v[194:197], v[62:65]
	v_mfma_f32_16x16x32_bf16 v[54:57], v[102:105], v[194:197], v[54:57]
	v_mfma_f32_16x16x32_bf16 v[46:49], v[86:89], v[202:205], v[46:49]
	v_mfma_f32_16x16x32_bf16 v[38:41], v[102:105], v[202:205], v[38:41]
	v_mfma_f32_16x16x32_bf16 v[30:33], v[86:89], v[210:213], v[30:33]
	v_mfma_f32_16x16x32_bf16 v[22:25], v[102:105], v[210:213], v[22:25]
	v_mfma_f32_16x16x32_bf16 v[14:17], v[86:89], v[218:221], v[14:17]
	v_mfma_f32_16x16x32_bf16 v[6:9], v[102:105], v[218:221], v[6:9]
	v_mfma_f32_16x16x32_bf16 v[58:61], v[150:153], v[190:193], v[58:61]
	v_mfma_f32_16x16x32_bf16 v[50:53], v[182:185], v[190:193], v[50:53]
	v_mfma_f32_16x16x32_bf16 v[42:45], v[150:153], v[198:201], v[42:45]
	v_mfma_f32_16x16x32_bf16 v[34:37], v[182:185], v[198:201], v[34:37]
	v_mfma_f32_16x16x32_bf16 v[26:29], v[150:153], v[206:209], v[26:29]
	v_mfma_f32_16x16x32_bf16 v[18:21], v[182:185], v[206:209], v[18:21]
	v_mfma_f32_16x16x32_bf16 v[10:13], v[150:153], v[214:217], v[10:13]
	v_mfma_f32_16x16x32_bf16 v[2:5], v[182:185], v[214:217], v[2:5]
	v_mfma_f32_16x16x32_bf16 v[58:61], v[154:157], v[194:197], v[58:61]
	v_mfma_f32_16x16x32_bf16 v[50:53], v[186:189], v[194:197], v[50:53]
	v_mfma_f32_16x16x32_bf16 v[42:45], v[154:157], v[202:205], v[42:45]
	v_mfma_f32_16x16x32_bf16 v[34:37], v[186:189], v[202:205], v[34:37]
	v_mfma_f32_16x16x32_bf16 v[26:29], v[154:157], v[210:213], v[26:29]
	v_mfma_f32_16x16x32_bf16 v[18:21], v[186:189], v[210:213], v[18:21]
	v_mfma_f32_16x16x32_bf16 v[10:13], v[154:157], v[218:221], v[10:13]
	v_mfma_f32_16x16x32_bf16 v[2:5], v[186:189], v[218:221], v[2:5]
	s_setprio 0
	s_barrier
; #define PG8_STAGEX(rs, bufoff, soff, voff) do { _Pragma("unroll") for (int _i = 0; _i < 2; ++_i) \
;         __builtin_amdgcn_raw_ptr_buffer_load_lds(rs, (LAS unsigned*)(lds + (bufoff) + ldsw + _i * 8192), 16, (voff)[_i], (soff), 0, 0); } while (0)
; #define PG8_LDA(dst, b, h) do { _Pragma("unroll") for (int m = 0; m < 4; ++m) _Pragma("unroll") for (int k = 0; k < 2; ++k) dst[m][k] = *(const LAS bf16x8*)(lds + PG8_SA(b, h) + aoff + m * 2048 + k * 1024); } while (0)
; #define PG8_LDB(dst, b, h) do { _Pragma("unroll") for (int n = 0; n < 2; ++n) _Pragma("unroll") for (int k = 0; k < 2; ++k) dst[n][k] = *(const LAS bf16x8*)(lds + PG8_SB(b, h) + boff + n * 2048 + k * 1024); } while (0)
; #define PG8_WAIT_V(n) asm volatile("s_waitcnt vmcnt(" #n ")" ::: "memory")
; #define PG8_WAIT_L(n) asm volatile("s_waitcnt lgkmcnt(" #n ")" ::: "memory")
; #define PG8_BAR __builtin_amdgcn_s_barrier()
; #define PG8_SCHED __builtin_amdgcn_sched_barrier(0)
;     ...
;             PG8_LDB(B0, 1, 0); PG8_LDB(B1, 1, 1); PG8_SCHED; PG8_LDA(At, 1, 0); PG8_STAGEX(rsA, PG8_SA(0, 1), a2 + hstepA, voffA);
;             PG8_WAIT_V(8); PG8_WAIT_L(0); PG8_BAR; PG8_MMA(0, 0, At, B0); PG8_MMA(0, 1, At, B1); PG8_BAR; PG8_SCHED;
;             PG8_LDA(At, 1, 1); PG8_STAGEX(rsB, PG8_SB(1, 0), b3, voffB); PG8_STAGEX(rsB, PG8_SB(1, 1), b3 + hstepB, voffB); PG8_STAGEX(rsA, PG8_SA(1, 0), a3, voffA);
;             PG8_WAIT_V(8); PG8_WAIT_L(0); PG8_BAR; PG8_MMA(1, 0, At, B0); PG8_MMA(1, 1, At, B1); PG8_BAR; PG8_SCHED;
;         }
	v_add_u32_e32 v102, 0x18000, v172
	v_add_u32_e32 v146, 0x1c000, v172
	ds_read_b128 v[82:85], v102
	ds_read_b128 v[86:89], v102 offset:1024
	ds_read_b128 v[98:101], v102 offset:2048
	ds_read_b128 v[102:105], v102 offset:3072
	ds_read_b128 v[150:153], v146
	ds_read_b128 v[154:157], v146 offset:1024
	ds_read_b128 v[182:185], v146 offset:2048
	ds_read_b128 v[186:189], v146 offset:3072
	s_add_i32 s55, s55, 0x80000
	s_mov_b32 m0, s14
	ds_read_b128 v[190:193], v173 offset:32768
	ds_read_b128 v[194:197], v173 offset:33792
	ds_read_b128 v[198:201], v173 offset:34816
	ds_read_b128 v[202:205], v173 offset:35840
	ds_read_b128 v[206:209], v173 offset:36864
	ds_read_b128 v[210:213], v173 offset:37888
	ds_read_b128 v[214:217], v173 offset:38912
	ds_read_b128 v[218:221], v173 offset:39936
	buffer_load_dwordx4 v159, s[76:79], s55 offen lds
	s_mov_b32 m0, s15
	s_nop 0
	buffer_load_dwordx4 v163, s[76:79], s55 offen lds
	s_waitcnt vmcnt(8)
	s_waitcnt lgkmcnt(0)
	s_barrier
	s_setprio 1
	v_mfma_f32_16x16x32_bf16 v[142:145], v[82:85], v[190:193], v[142:145]
	v_mfma_f32_16x16x32_bf16 v[134:137], v[98:101], v[190:193], v[134:137]
	v_mfma_f32_16x16x32_bf16 v[126:129], v[82:85], v[198:201], v[126:129]
	v_mfma_f32_16x16x32_bf16 v[118:121], v[98:101], v[198:201], v[118:121]
	v_mfma_f32_16x16x32_bf16 v[110:113], v[82:85], v[206:209], v[110:113]
	v_mfma_f32_16x16x32_bf16 v[94:97], v[98:101], v[206:209], v[94:97]
	v_mfma_f32_16x16x32_bf16 v[78:81], v[82:85], v[214:217], v[78:81]
	v_mfma_f32_16x16x32_bf16 v[70:73], v[98:101], v[214:217], v[70:73]
	v_mfma_f32_16x16x32_bf16 v[142:145], v[86:89], v[194:197], v[142:145]
	v_mfma_f32_16x16x32_bf16 v[134:137], v[102:105], v[194:197], v[134:137]
	v_mfma_f32_16x16x32_bf16 v[126:129], v[86:89], v[202:205], v[126:129]
	v_mfma_f32_16x16x32_bf16 v[118:121], v[102:105], v[202:205], v[118:121]
	v_mfma_f32_16x16x32_bf16 v[110:113], v[86:89], v[210:213], v[110:113]
	v_mfma_f32_16x16x32_bf16 v[94:97], v[102:105], v[210:213], v[94:97]
	v_mfma_f32_16x16x32_bf16 v[78:81], v[86:89], v[218:221], v[78:81]
	v_mfma_f32_16x16x32_bf16 v[70:73], v[102:105], v[218:221], v[70:73]
	v_mfma_f32_16x16x32_bf16 v[138:141], v[150:153], v[190:193], v[138:141]
	v_mfma_f32_16x16x32_bf16 v[130:133], v[182:185], v[190:193], v[130:133]
	v_mfma_f32_16x16x32_bf16 v[122:125], v[150:153], v[198:201], v[122:125]
	v_mfma_f32_16x16x32_bf16 v[114:117], v[182:185], v[198:201], v[114:117]
	v_mfma_f32_16x16x32_bf16 v[106:109], v[150:153], v[206:209], v[106:109]
	v_mfma_f32_16x16x32_bf16 v[90:93], v[182:185], v[206:209], v[90:93]
	v_mfma_f32_16x16x32_bf16 v[74:77], v[150:153], v[214:217], v[74:77]
	v_mfma_f32_16x16x32_bf16 v[66:69], v[182:185], v[214:217], v[66:69]
	v_mfma_f32_16x16x32_bf16 v[138:141], v[154:157], v[194:197], v[138:141]
	v_mfma_f32_16x16x32_bf16 v[130:133], v[186:189], v[194:197], v[130:133]
	v_mfma_f32_16x16x32_bf16 v[122:125], v[154:157], v[202:205], v[122:125]
	v_mfma_f32_16x16x32_bf16 v[114:117], v[186:189], v[202:205], v[114:117]
	v_mfma_f32_16x16x32_bf16 v[106:109], v[154:157], v[210:213], v[106:109]
	v_mfma_f32_16x16x32_bf16 v[90:93], v[186:189], v[210:213], v[90:93]
	v_mfma_f32_16x16x32_bf16 v[74:77], v[154:157], v[218:221], v[74:77]
	v_mfma_f32_16x16x32_bf16 v[66:69], v[186:189], v[218:221], v[66:69]
	s_setprio 0
	s_barrier
	s_mov_b32 m0, s16
	s_or_b32 s55, s54, 0x80
	ds_read_b128 v[190:193], v173 offset:49152
	ds_read_b128 v[194:197], v173 offset:50176
	ds_read_b128 v[198:201], v173 offset:51200
	ds_read_b128 v[202:205], v173 offset:52224
	ds_read_b128 v[206:209], v173 offset:53248
	ds_read_b128 v[210:213], v173 offset:54272
	ds_read_b128 v[214:217], v173 offset:55296
	ds_read_b128 v[218:221], v173 offset:56320
	buffer_load_dwordx4 v161, s[40:43], s55 offen lds
	s_mov_b32 m0, s17
	s_add_i32 s54, s54, 0x80080
	buffer_load_dwordx4 v165, s[40:43], s55 offen lds
	s_mov_b32 m0, s20
	s_nop 0
	buffer_load_dwordx4 v161, s[40:43], s54 offen lds
	s_mov_b32 m0, s21
	s_nop 0
	buffer_load_dwordx4 v165, s[40:43], s54 offen lds
	s_mov_b32 m0, s18
	s_nop 0
	buffer_load_dwordx4 v159, s[76:79], s53 offen lds
	s_mov_b32 m0, s19
	s_nop 0
	buffer_load_dwordx4 v163, s[76:79], s53 offen lds
	s_waitcnt vmcnt(8)
	s_waitcnt lgkmcnt(0)
	s_barrier
	s_setprio 1
	v_mfma_f32_16x16x32_bf16 v[62:65], v[82:85], v[190:193], v[62:65]
	v_mfma_f32_16x16x32_bf16 v[54:57], v[98:101], v[190:193], v[54:57]
	v_mfma_f32_16x16x32_bf16 v[46:49], v[82:85], v[198:201], v[46:49]
	v_mfma_f32_16x16x32_bf16 v[38:41], v[98:101], v[198:201], v[38:41]
	v_mfma_f32_16x16x32_bf16 v[30:33], v[82:85], v[206:209], v[30:33]
	v_mfma_f32_16x16x32_bf16 v[22:25], v[98:101], v[206:209], v[22:25]
	v_mfma_f32_16x16x32_bf16 v[14:17], v[82:85], v[214:217], v[14:17]
	v_mfma_f32_16x16x32_bf16 v[6:9], v[98:101], v[214:217], v[6:9]
	v_mfma_f32_16x16x32_bf16 v[62:65], v[86:89], v[194:197], v[62:65]
	v_mfma_f32_16x16x32_bf16 v[54:57], v[102:105], v[194:197], v[54:57]
	v_mfma_f32_16x16x32_bf16 v[46:49], v[86:89], v[202:205], v[46:49]
	v_mfma_f32_16x16x32_bf16 v[38:41], v[102:105], v[202:205], v[38:41]
	v_mfma_f32_16x16x32_bf16 v[30:33], v[86:89], v[210:213], v[30:33]
	v_mfma_f32_16x16x32_bf16 v[22:25], v[102:105], v[210:213], v[22:25]
	v_mfma_f32_16x16x32_bf16 v[14:17], v[86:89], v[218:221], v[14:17]
	v_mfma_f32_16x16x32_bf16 v[6:9], v[102:105], v[218:221], v[6:9]
	v_mfma_f32_16x16x32_bf16 v[58:61], v[150:153], v[190:193], v[58:61]
	v_mfma_f32_16x16x32_bf16 v[50:53], v[182:185], v[190:193], v[50:53]
	v_mfma_f32_16x16x32_bf16 v[42:45], v[150:153], v[198:201], v[42:45]
	v_mfma_f32_16x16x32_bf16 v[34:37], v[182:185], v[198:201], v[34:37]
	v_mfma_f32_16x16x32_bf16 v[26:29], v[150:153], v[206:209], v[26:29]
	v_mfma_f32_16x16x32_bf16 v[18:21], v[182:185], v[206:209], v[18:21]
	v_mfma_f32_16x16x32_bf16 v[10:13], v[150:153], v[214:217], v[10:13]
	v_mfma_f32_16x16x32_bf16 v[2:5], v[182:185], v[214:217], v[2:5]
	v_mfma_f32_16x16x32_bf16 v[58:61], v[154:157], v[194:197], v[58:61]
	v_mfma_f32_16x16x32_bf16 v[50:53], v[186:189], v[194:197], v[50:53]
	v_mfma_f32_16x16x32_bf16 v[42:45], v[154:157], v[202:205], v[42:45]
	v_mfma_f32_16x16x32_bf16 v[34:37], v[186:189], v[202:205], v[34:37]
	v_mfma_f32_16x16x32_bf16 v[26:29], v[154:157], v[210:213], v[26:29]
	v_mfma_f32_16x16x32_bf16 v[18:21], v[186:189], v[210:213], v[18:21]
	v_mfma_f32_16x16x32_bf16 v[10:13], v[154:157], v[218:221], v[10:13]
	v_mfma_f32_16x16x32_bf16 v[2:5], v[186:189], v[218:221], v[2:5]
	s_setprio 0
	s_barrier
	s_add_i32 s52, s52, 2
	s_addk_i32 s50, 0x100
	s_addk_i32 s51, 0x100
	s_cmp_gt_u32 s52, 29
	s_cbranch_scc0 .LBB0_223
	s_and_b64 vcc, exec, s[46:47]
	s_cbranch_vccz .LBB0_226
	s_barrier

; #define PG8_STAGEX(rs, bufoff, soff, voff) do { _Pragma("unroll") for (int _i = 0; _i < 2; ++_i) \
;         __builtin_amdgcn_raw_ptr_buffer_load_lds(rs, (LAS unsigned*)(lds + (bufoff) + ldsw + _i * 8192), 16, (voff)[_i], (soff), 0, 0); } while (0)
; #define PG8_LDA(dst, b, h) do { _Pragma("unroll") for (int m = 0; m < 4; ++m) _Pragma("unroll") for (int k = 0; k < 2; ++k) dst[m][k] = *(const LAS bf16x8*)(lds + PG8_SA(b, h) + aoff + m * 2048 + k * 1024); } while (0)
; #define PG8_LDB(dst, b, h) do { _Pragma("unroll") for (int n = 0; n < 2; ++n) _Pragma("unroll") for (int k = 0; k < 2; ++k) dst[n][k] = *(const LAS bf16x8*)(lds + PG8_SB(b, h) + boff + n * 2048 + k * 1024); } while (0)
; #define PG8_WAIT_V(n) asm volatile("s_waitcnt vmcnt(" #n ")" ::: "memory")
; #define PG8_WAIT_L(n) asm volatile("s_waitcnt lgkmcnt(" #n ")" ::: "memory")
; #define PG8_BAR __builtin_amdgcn_s_barrier()
; #define PG8_SCHED __builtin_amdgcn_sched_barrier(0)
;     ...
;                 if (w0) { PG8_LDB(B0, 0, 0); PG8_LDB(B1, 0, 1); PG8_SCHED; PG8_LDA(At, 0, 0); }
;                 PG8_WAIT_L(0); PG8_BAR; if (w0) { PG8_MMA(0, 0, At, B0); PG8_MMA(0, 1, At, B1); } PG8_BAR; PG8_SCHED;
;                 PG8_STAGEX(rsB, PG8_SB(0, 0), b2, voffB); PG8_STAGEX(rsB, PG8_SB(0, 1), b2 + hstepB, voffB); PG8_STAGEX(rsA, PG8_SA(0, 0), a2, voffA);
;                 PG8_WAIT_V(6); PG8_BAR; PG8_BAR; PG8_SCHED;
.LBB0_240:
	v_add_u32_e32 v86, 0x10000, v72
	v_add_u32_e32 v102, 0x14000, v72
	ds_read_b128 v[74:77], v86
	ds_read_b128 v[78:81], v86 offset:1024
	ds_read_b128 v[82:85], v86 offset:2048
	ds_read_b128 v[86:89], v86 offset:3072
	ds_read_b128 v[90:93], v102
	ds_read_b128 v[94:97], v102 offset:1024
	ds_read_b128 v[98:101], v102 offset:2048
	ds_read_b128 v[102:105], v102 offset:3072
	s_cmp_lg_u32 s27, 28
	s_cselect_b32 s28, s26, 0
	s_add_i32 s29, s28, s17
	s_or_b32 s30, s29, 0x80
	s_add_i32 s28, s28, s11
	ds_read_b128 v[106:109], v73
	ds_read_b128 v[110:113], v73 offset:1024
	ds_read_b128 v[114:117], v73 offset:2048
	ds_read_b128 v[118:121], v73 offset:3072
	ds_read_b128 v[122:125], v73 offset:4096
	ds_read_b128 v[126:129], v73 offset:5120
	ds_read_b128 v[130:133], v73 offset:6144
	ds_read_b128 v[134:137], v73 offset:7168
	s_waitcnt lgkmcnt(0)
	s_barrier
	s_setprio 1
	v_mfma_f32_16x16x32_bf16 v[62:65], v[74:77], v[106:109], v[62:65]
	v_mfma_f32_16x16x32_bf16 v[58:61], v[82:85], v[106:109], v[58:61]
	v_mfma_f32_16x16x32_bf16 v[54:57], v[74:77], v[114:117], v[54:57]
	v_mfma_f32_16x16x32_bf16 v[38:41], v[82:85], v[114:117], v[38:41]
	v_mfma_f32_16x16x32_bf16 v[30:33], v[74:77], v[122:125], v[30:33]
	v_mfma_f32_16x16x32_bf16 v[22:25], v[82:85], v[122:125], v[22:25]
	v_mfma_f32_16x16x32_bf16 v[14:17], v[74:77], v[130:133], v[14:17]
	v_mfma_f32_16x16x32_bf16 v[6:9], v[82:85], v[130:133], v[6:9]
	v_mfma_f32_16x16x32_bf16 v[62:65], v[78:81], v[110:113], v[62:65]
	v_mfma_f32_16x16x32_bf16 v[58:61], v[86:89], v[110:113], v[58:61]
	v_mfma_f32_16x16x32_bf16 v[54:57], v[78:81], v[118:121], v[54:57]
	v_mfma_f32_16x16x32_bf16 v[38:41], v[86:89], v[118:121], v[38:41]
	v_mfma_f32_16x16x32_bf16 v[30:33], v[78:81], v[126:129], v[30:33]
	v_mfma_f32_16x16x32_bf16 v[22:25], v[86:89], v[126:129], v[22:25]
	v_mfma_f32_16x16x32_bf16 v[14:17], v[78:81], v[134:137], v[14:17]
	v_mfma_f32_16x16x32_bf16 v[6:9], v[86:89], v[134:137], v[6:9]
	v_mfma_f32_16x16x32_bf16 v[50:53], v[90:93], v[106:109], v[50:53]
	v_mfma_f32_16x16x32_bf16 v[46:49], v[98:101], v[106:109], v[46:49]
	v_mfma_f32_16x16x32_bf16 v[42:45], v[90:93], v[114:117], v[42:45]
	v_mfma_f32_16x16x32_bf16 v[34:37], v[98:101], v[114:117], v[34:37]
	v_mfma_f32_16x16x32_bf16 v[26:29], v[90:93], v[122:125], v[26:29]
	v_mfma_f32_16x16x32_bf16 v[18:21], v[98:101], v[122:125], v[18:21]
	v_mfma_f32_16x16x32_bf16 v[10:13], v[90:93], v[130:133], v[10:13]
	v_mfma_f32_16x16x32_bf16 v[2:5], v[98:101], v[130:133], v[2:5]
	v_mfma_f32_16x16x32_bf16 v[50:53], v[94:97], v[110:113], v[50:53]
	v_mfma_f32_16x16x32_bf16 v[46:49], v[102:105], v[110:113], v[46:49]
	v_mfma_f32_16x16x32_bf16 v[42:45], v[94:97], v[118:121], v[42:45]
	v_mfma_f32_16x16x32_bf16 v[34:37], v[102:105], v[118:121], v[34:37]
	v_mfma_f32_16x16x32_bf16 v[26:29], v[94:97], v[126:129], v[26:29]
	v_mfma_f32_16x16x32_bf16 v[18:21], v[102:105], v[126:129], v[18:21]
	v_mfma_f32_16x16x32_bf16 v[10:13], v[94:97], v[134:137], v[10:13]
	v_mfma_f32_16x16x32_bf16 v[2:5], v[102:105], v[134:137], v[2:5]
	s_setprio 0
	s_barrier
	s_mov_b32 m0, s13
	s_mov_b32 s42, s78
	s_mov_b32 s43, s79
	buffer_load_dwordx4 v67, s[40:43], s28 offen lds
	s_mov_b32 m0, s14
	s_add_i32 s31, s28, 0x80000
	buffer_load_dwordx4 v69, s[40:43], s28 offen lds
	s_mov_b32 m0, s15
	s_nop 0
	buffer_load_dwordx4 v67, s[40:43], s31 offen lds
	s_mov_b32 m0, s16
	s_nop 0
	buffer_load_dwordx4 v69, s[40:43], s31 offen lds
	s_mov_b32 m0, s12
	s_nop 0
	buffer_load_dwordx4 v66, s[76:79], s29 offen lds
	s_mov_b32 m0, s18
	s_nop 0
	buffer_load_dwordx4 v68, s[76:79], s29 offen lds
	s_waitcnt vmcnt(6)
	s_barrier
	s_barrier
; #define PG8_STAGEX(rs, bufoff, soff, voff) do { _Pragma("unroll") for (int _i = 0; _i < 2; ++_i) \
;         __builtin_amdgcn_raw_ptr_buffer_load_lds(rs, (LAS unsigned*)(lds + (bufoff) + ldsw + _i * 8192), 16, (voff)[_i], (soff), 0, 0); } while (0)
; #define PG8_LDA(dst, b, h) do { _Pragma("unroll") for (int m = 0; m < 4; ++m) _Pragma("unroll") for (int k = 0; k < 2; ++k) dst[m][k] = *(const LAS bf16x8*)(lds + PG8_SA(b, h) + aoff + m * 2048 + k * 1024); } while (0)
; #define PG8_LDB(dst, b, h) do { _Pragma("unroll") for (int n = 0; n < 2; ++n) _Pragma("unroll") for (int k = 0; k < 2; ++k) dst[n][k] = *(const LAS bf16x8*)(lds + PG8_SB(b, h) + boff + n * 2048 + k * 1024); } while (0)
; #define PG8_WAIT_V(n) asm volatile("s_waitcnt vmcnt(" #n ")" ::: "memory")
; #define PG8_WAIT_L(n) asm volatile("s_waitcnt lgkmcnt(" #n ")" ::: "memory")
; #define PG8_BAR __builtin_amdgcn_s_barrier()
; #define PG8_SCHED __builtin_amdgcn_sched_barrier(0)
;     ...
;                 if (w0) { PG8_LDB(B0, 1, 0); PG8_LDB(B1, 1, 1); PG8_SCHED; PG8_LDA(At, 1, 0); }
;                 PG8_WAIT_L(0); PG8_BAR; if (w0) { PG8_MMA(0, 0, At, B0); PG8_MMA(0, 1, At, B1); } PG8_BAR; PG8_SCHED;
;                 PG8_STAGEX(rsB, PG8_SB(1, 0), b3, voffB); PG8_STAGEX(rsB, PG8_SB(1, 1), b3 + hstepB, voffB); PG8_STAGEX(rsA, PG8_SA(1, 0), a3, voffA);
;                 PG8_WAIT_V(6); PG8_BAR; PG8_BAR; PG8_SCHED;
;             }
	v_add_u32_e32 v86, 0x18000, v72
	v_add_u32_e32 v102, 0x1c000, v72
	ds_read_b128 v[74:77], v86
	ds_read_b128 v[78:81], v86 offset:1024
	ds_read_b128 v[82:85], v86 offset:2048
	ds_read_b128 v[86:89], v86 offset:3072
	ds_read_b128 v[90:93], v102
	ds_read_b128 v[94:97], v102 offset:1024
	ds_read_b128 v[98:101], v102 offset:2048
	ds_read_b128 v[102:105], v102 offset:3072
	ds_read_b128 v[106:109], v73 offset:32768
	ds_read_b128 v[110:113], v73 offset:33792
	ds_read_b128 v[114:117], v73 offset:34816
	ds_read_b128 v[118:121], v73 offset:35840
	ds_read_b128 v[122:125], v73 offset:36864
	ds_read_b128 v[126:129], v73 offset:37888
	ds_read_b128 v[130:133], v73 offset:38912
	ds_read_b128 v[134:137], v73 offset:39936
	s_waitcnt lgkmcnt(0)
	s_barrier
	s_setprio 1
	v_mfma_f32_16x16x32_bf16 v[62:65], v[74:77], v[106:109], v[62:65]
	v_mfma_f32_16x16x32_bf16 v[58:61], v[82:85], v[106:109], v[58:61]
	v_mfma_f32_16x16x32_bf16 v[54:57], v[74:77], v[114:117], v[54:57]
	v_mfma_f32_16x16x32_bf16 v[38:41], v[82:85], v[114:117], v[38:41]
	v_mfma_f32_16x16x32_bf16 v[30:33], v[74:77], v[122:125], v[30:33]
	v_mfma_f32_16x16x32_bf16 v[22:25], v[82:85], v[122:125], v[22:25]
	v_mfma_f32_16x16x32_bf16 v[14:17], v[74:77], v[130:133], v[14:17]
	v_mfma_f32_16x16x32_bf16 v[6:9], v[82:85], v[130:133], v[6:9]
	v_mfma_f32_16x16x32_bf16 v[62:65], v[78:81], v[110:113], v[62:65]
	v_mfma_f32_16x16x32_bf16 v[58:61], v[86:89], v[110:113], v[58:61]
	v_mfma_f32_16x16x32_bf16 v[54:57], v[78:81], v[118:121], v[54:57]
	v_mfma_f32_16x16x32_bf16 v[38:41], v[86:89], v[118:121], v[38:41]
	v_mfma_f32_16x16x32_bf16 v[30:33], v[78:81], v[126:129], v[30:33]
	v_mfma_f32_16x16x32_bf16 v[22:25], v[86:89], v[126:129], v[22:25]
	v_mfma_f32_16x16x32_bf16 v[14:17], v[78:81], v[134:137], v[14:17]
	v_mfma_f32_16x16x32_bf16 v[6:9], v[86:89], v[134:137], v[6:9]
	v_mfma_f32_16x16x32_bf16 v[50:53], v[90:93], v[106:109], v[50:53]
	s_or_b32 s29, s28, 0x80
	v_mfma_f32_16x16x32_bf16 v[46:49], v[98:101], v[106:109], v[46:49]
	v_mfma_f32_16x16x32_bf16 v[42:45], v[90:93], v[114:117], v[42:45]
	v_mfma_f32_16x16x32_bf16 v[34:37], v[98:101], v[114:117], v[34:37]
	v_mfma_f32_16x16x32_bf16 v[26:29], v[90:93], v[122:125], v[26:29]
	v_mfma_f32_16x16x32_bf16 v[18:21], v[98:101], v[122:125], v[18:21]
	v_mfma_f32_16x16x32_bf16 v[10:13], v[90:93], v[130:133], v[10:13]
	v_mfma_f32_16x16x32_bf16 v[2:5], v[98:101], v[130:133], v[2:5]
	v_mfma_f32_16x16x32_bf16 v[50:53], v[94:97], v[110:113], v[50:53]
	v_mfma_f32_16x16x32_bf16 v[46:49], v[102:105], v[110:113], v[46:49]
	v_mfma_f32_16x16x32_bf16 v[42:45], v[94:97], v[118:121], v[42:45]
	v_mfma_f32_16x16x32_bf16 v[34:37], v[102:105], v[118:121], v[34:37]
	v_mfma_f32_16x16x32_bf16 v[26:29], v[94:97], v[126:129], v[26:29]
	v_mfma_f32_16x16x32_bf16 v[18:21], v[102:105], v[126:129], v[18:21]
	v_mfma_f32_16x16x32_bf16 v[10:13], v[94:97], v[134:137], v[10:13]
	v_mfma_f32_16x16x32_bf16 v[2:5], v[102:105], v[134:137], v[2:5]
	s_setprio 0
	s_barrier
	s_mov_b32 m0, s20
	s_add_i32 s28, s28, 0x80080
	buffer_load_dwordx4 v67, s[40:43], s29 offen lds
	s_mov_b32 m0, s21
	s_nop 0
	buffer_load_dwordx4 v69, s[40:43], s29 offen lds
	s_mov_b32 m0, s24
	s_nop 0
	buffer_load_dwordx4 v67, s[40:43], s28 offen lds
	s_mov_b32 m0, s25
	s_nop 0
	buffer_load_dwordx4 v69, s[40:43], s28 offen lds
	s_mov_b32 m0, s22
	s_nop 0
	buffer_load_dwordx4 v66, s[76:79], s30 offen lds
	s_mov_b32 m0, s23
	s_nop 0
	buffer_load_dwordx4 v68, s[76:79], s30 offen lds
	s_waitcnt vmcnt(6)
	s_barrier
	s_barrier
	s_addk_i32 s26, 0x100
	s_add_i32 s27, s27, 2
	s_cmp_gt_u32 s27, 29
	s_cbranch_scc0 .LBB0_240
	s_cmpk_lt_u32 s8, 0x100
	s_cbranch_scc0 .LBB0_243
	s_barrier

; #define PG8_STAGEX(rs, bufoff, soff, voff) do { _Pragma("unroll") for (int _i = 0; _i < 2; ++_i) \
;         __builtin_amdgcn_raw_ptr_buffer_load_lds(rs, (LAS unsigned*)(lds + (bufoff) + ldsw + _i * 8192), 16, (voff)[_i], (soff), 0, 0); } while (0)
; #define PG8_LDA(dst, b, h) do { _Pragma("unroll") for (int m = 0; m < 4; ++m) _Pragma("unroll") for (int k = 0; k < 2; ++k) dst[m][k] = *(const LAS bf16x8*)(lds + PG8_SA(b, h) + aoff + m * 2048 + k * 1024); } while (0)
; #define PG8_LDB(dst, b, h) do { _Pragma("unroll") for (int n = 0; n < 2; ++n) _Pragma("unroll") for (int k = 0; k < 2; ++k) dst[n][k] = *(const LAS bf16x8*)(lds + PG8_SB(b, h) + boff + n * 2048 + k * 1024); } while (0)
; #define PG8_WAIT_V(n) asm volatile("s_waitcnt vmcnt(" #n ")" ::: "memory")
; #define PG8_WAIT_L(n) asm volatile("s_waitcnt lgkmcnt(" #n ")" ::: "memory")
; #define PG8_BAR __builtin_amdgcn_s_barrier()
; #define PG8_SCHED __builtin_amdgcn_sched_barrier(0)
;     ...
;             PG8_LDB(B0, 0, 0); PG8_LDB(B1, 0, 1); PG8_SCHED; PG8_LDA(At, 0, 0); PG8_STAGEX(rsA, PG8_SA(1, 1), a1 + hstepA, voffA);
;             PG8_WAIT_V(8); PG8_WAIT_L(0); PG8_BAR; PG8_MMA(0, 0, At, B0); PG8_MMA(0, 1, At, B1); PG8_BAR; PG8_SCHED;
;             PG8_LDA(At, 0, 1); PG8_STAGEX(rsB, PG8_SB(0, 0), b2, voffB); PG8_STAGEX(rsB, PG8_SB(0, 1), b2 + hstepB, voffB); PG8_STAGEX(rsA, PG8_SA(0, 0), a2, voffA);
;             PG8_WAIT_V(8); PG8_WAIT_L(0); PG8_BAR; PG8_MMA(1, 0, At, B0); PG8_MMA(1, 1, At, B1); PG8_BAR; PG8_SCHED;
.LBB0_323:
	v_add_u32_e32 v118, 0x10000, v210
	v_add_u32_e32 v160, 0x14000, v210
	ds_read_b128 v[106:109], v118
	ds_read_b128 v[110:113], v118 offset:1024
	ds_read_b128 v[114:117], v118 offset:2048
	ds_read_b128 v[118:121], v118 offset:3072
	ds_read_b128 v[122:125], v160
	ds_read_b128 v[134:137], v160 offset:1024
	ds_read_b128 v[156:159], v160 offset:2048
	ds_read_b128 v[160:163], v160 offset:3072
	s_add_i32 s42, s51, 0xffea8080
	s_cmpk_eq_i32 s58, 0x52
	s_cselect_b32 s61, s30, s42
	s_cselect_b32 s60, s31, s57
	s_or_b32 s59, s61, 0x80
	s_mov_b32 m0, s68
	ds_read_b128 v[164:167], v211
	ds_read_b128 v[168:171], v211 offset:1024
	ds_read_b128 v[182:185], v211 offset:2048
	ds_read_b128 v[186:189], v211 offset:3072
	ds_read_b128 v[190:193], v211 offset:4096
	ds_read_b128 v[194:197], v211 offset:5120
	ds_read_b128 v[198:201], v211 offset:6144
	ds_read_b128 v[202:205], v211 offset:7168
	buffer_load_dwordx4 v178, s[76:79], s51 offen lds
	s_mov_b32 m0, s69
	s_nop 0
	buffer_load_dwordx4 v206, s[76:79], s51 offen lds
	s_waitcnt vmcnt(8)
	s_waitcnt lgkmcnt(0)
	s_barrier
	s_setprio 1
	v_mfma_f32_16x16x32_bf16 v[150:153], v[106:109], v[164:167], v[150:153]
	v_mfma_f32_16x16x32_bf16 v[146:149], v[114:117], v[164:167], v[146:149]
	v_mfma_f32_16x16x32_bf16 v[142:145], v[106:109], v[182:185], v[142:145]
	v_mfma_f32_16x16x32_bf16 v[138:141], v[114:117], v[182:185], v[138:141]
	v_mfma_f32_16x16x32_bf16 v[130:133], v[106:109], v[190:193], v[130:133]
	v_mfma_f32_16x16x32_bf16 v[126:129], v[114:117], v[190:193], v[126:129]
	v_mfma_f32_16x16x32_bf16 v[102:105], v[106:109], v[198:201], v[102:105]
	v_mfma_f32_16x16x32_bf16 v[98:101], v[114:117], v[198:201], v[98:101]
	v_mfma_f32_16x16x32_bf16 v[150:153], v[110:113], v[168:171], v[150:153]
	v_mfma_f32_16x16x32_bf16 v[146:149], v[118:121], v[168:171], v[146:149]
	v_mfma_f32_16x16x32_bf16 v[142:145], v[110:113], v[186:189], v[142:145]
	v_mfma_f32_16x16x32_bf16 v[138:141], v[118:121], v[186:189], v[138:141]
	v_mfma_f32_16x16x32_bf16 v[130:133], v[110:113], v[194:197], v[130:133]
	v_mfma_f32_16x16x32_bf16 v[126:129], v[118:121], v[194:197], v[126:129]
	v_mfma_f32_16x16x32_bf16 v[102:105], v[110:113], v[202:205], v[102:105]
	v_mfma_f32_16x16x32_bf16 v[98:101], v[118:121], v[202:205], v[98:101]
	v_mfma_f32_16x16x32_bf16 v[62:65], v[122:125], v[164:167], v[62:65]
	v_mfma_f32_16x16x32_bf16 v[58:61], v[156:159], v[164:167], v[58:61]
	v_mfma_f32_16x16x32_bf16 v[54:57], v[122:125], v[182:185], v[54:57]
	v_mfma_f32_16x16x32_bf16 v[50:53], v[156:159], v[182:185], v[50:53]
	v_mfma_f32_16x16x32_bf16 v[46:49], v[122:125], v[190:193], v[46:49]
	v_mfma_f32_16x16x32_bf16 v[42:45], v[156:159], v[190:193], v[42:45]
	v_mfma_f32_16x16x32_bf16 v[38:41], v[122:125], v[198:201], v[38:41]
	v_mfma_f32_16x16x32_bf16 v[34:37], v[156:159], v[198:201], v[34:37]
	v_mfma_f32_16x16x32_bf16 v[62:65], v[134:137], v[168:171], v[62:65]
	v_mfma_f32_16x16x32_bf16 v[58:61], v[160:163], v[168:171], v[58:61]
	v_mfma_f32_16x16x32_bf16 v[54:57], v[134:137], v[186:189], v[54:57]
	v_mfma_f32_16x16x32_bf16 v[50:53], v[160:163], v[186:189], v[50:53]
	v_mfma_f32_16x16x32_bf16 v[46:49], v[134:137], v[194:197], v[46:49]
	v_mfma_f32_16x16x32_bf16 v[42:45], v[160:163], v[194:197], v[42:45]
	v_mfma_f32_16x16x32_bf16 v[38:41], v[134:137], v[202:205], v[38:41]
	v_mfma_f32_16x16x32_bf16 v[34:37], v[160:163], v[202:205], v[34:37]
	s_setprio 0
	s_barrier
	s_mov_b32 m0, s15
	s_mov_b32 s42, s78
	s_mov_b32 s43, s79
	ds_read_b128 v[164:167], v211 offset:16384
	ds_read_b128 v[168:171], v211 offset:17408
	ds_read_b128 v[182:185], v211 offset:18432
	ds_read_b128 v[186:189], v211 offset:19456
	ds_read_b128 v[190:193], v211 offset:20480
	ds_read_b128 v[194:197], v211 offset:21504
	ds_read_b128 v[198:201], v211 offset:22528
	ds_read_b128 v[202:205], v211 offset:23552
	buffer_load_dwordx4 v179, s[40:43], s60 offen lds
	s_mov_b32 m0, s16
	s_add_i32 s62, s60, 0x158000
	buffer_load_dwordx4 v207, s[40:43], s60 offen lds
	s_mov_b32 m0, s17
	s_nop 0
	buffer_load_dwordx4 v179, s[40:43], s62 offen lds
	s_mov_b32 m0, s18
	s_nop 0
	buffer_load_dwordx4 v207, s[40:43], s62 offen lds
	s_mov_b32 m0, s14
	s_nop 0
	buffer_load_dwordx4 v178, s[76:79], s61 offen lds
	s_mov_b32 m0, s19
	s_nop 0
	buffer_load_dwordx4 v206, s[76:79], s61 offen lds
	s_waitcnt vmcnt(8)
	s_waitcnt lgkmcnt(0)
	s_barrier
	s_setprio 1
	v_mfma_f32_16x16x32_bf16 v[94:97], v[106:109], v[164:167], v[94:97]
	v_mfma_f32_16x16x32_bf16 v[90:93], v[114:117], v[164:167], v[90:93]
	v_mfma_f32_16x16x32_bf16 v[86:89], v[106:109], v[182:185], v[86:89]
	v_mfma_f32_16x16x32_bf16 v[82:85], v[114:117], v[182:185], v[82:85]
	v_mfma_f32_16x16x32_bf16 v[78:81], v[106:109], v[190:193], v[78:81]
	v_mfma_f32_16x16x32_bf16 v[74:77], v[114:117], v[190:193], v[74:77]
	v_mfma_f32_16x16x32_bf16 v[70:73], v[106:109], v[198:201], v[70:73]
	v_mfma_f32_16x16x32_bf16 v[66:69], v[114:117], v[198:201], v[66:69]
	v_mfma_f32_16x16x32_bf16 v[94:97], v[110:113], v[168:171], v[94:97]
	v_mfma_f32_16x16x32_bf16 v[90:93], v[118:121], v[168:171], v[90:93]
	v_mfma_f32_16x16x32_bf16 v[86:89], v[110:113], v[186:189], v[86:89]
	v_mfma_f32_16x16x32_bf16 v[82:85], v[118:121], v[186:189], v[82:85]
	v_mfma_f32_16x16x32_bf16 v[78:81], v[110:113], v[194:197], v[78:81]
	v_mfma_f32_16x16x32_bf16 v[74:77], v[118:121], v[194:197], v[74:77]
	v_mfma_f32_16x16x32_bf16 v[70:73], v[110:113], v[202:205], v[70:73]
	v_mfma_f32_16x16x32_bf16 v[66:69], v[118:121], v[202:205], v[66:69]
	v_mfma_f32_16x16x32_bf16 v[30:33], v[122:125], v[164:167], v[30:33]
	v_mfma_f32_16x16x32_bf16 v[26:29], v[156:159], v[164:167], v[26:29]
	v_mfma_f32_16x16x32_bf16 v[22:25], v[122:125], v[182:185], v[22:25]
	v_mfma_f32_16x16x32_bf16 v[18:21], v[156:159], v[182:185], v[18:21]
	v_mfma_f32_16x16x32_bf16 v[14:17], v[122:125], v[190:193], v[14:17]
	v_mfma_f32_16x16x32_bf16 v[10:13], v[156:159], v[190:193], v[10:13]
	v_mfma_f32_16x16x32_bf16 v[6:9], v[122:125], v[198:201], v[6:9]
	v_mfma_f32_16x16x32_bf16 v[2:5], v[156:159], v[198:201], v[2:5]
	v_mfma_f32_16x16x32_bf16 v[30:33], v[134:137], v[168:171], v[30:33]
	v_mfma_f32_16x16x32_bf16 v[26:29], v[160:163], v[168:171], v[26:29]
	v_mfma_f32_16x16x32_bf16 v[22:25], v[134:137], v[186:189], v[22:25]
	v_mfma_f32_16x16x32_bf16 v[18:21], v[160:163], v[186:189], v[18:21]
	v_mfma_f32_16x16x32_bf16 v[14:17], v[134:137], v[194:197], v[14:17]
	v_mfma_f32_16x16x32_bf16 v[10:13], v[160:163], v[194:197], v[10:13]
	v_mfma_f32_16x16x32_bf16 v[6:9], v[134:137], v[202:205], v[6:9]
	v_mfma_f32_16x16x32_bf16 v[2:5], v[160:163], v[202:205], v[2:5]
	s_setprio 0
	s_barrier
; #define PG8_STAGEX(rs, bufoff, soff, voff) do { _Pragma("unroll") for (int _i = 0; _i < 2; ++_i) \
;         __builtin_amdgcn_raw_ptr_buffer_load_lds(rs, (LAS unsigned*)(lds + (bufoff) + ldsw + _i * 8192), 16, (voff)[_i], (soff), 0, 0); } while (0)
; #define PG8_LDA(dst, b, h) do { _Pragma("unroll") for (int m = 0; m < 4; ++m) _Pragma("unroll") for (int k = 0; k < 2; ++k) dst[m][k] = *(const LAS bf16x8*)(lds + PG8_SA(b, h) + aoff + m * 2048 + k * 1024); } while (0)
; #define PG8_LDB(dst, b, h) do { _Pragma("unroll") for (int n = 0; n < 2; ++n) _Pragma("unroll") for (int k = 0; k < 2; ++k) dst[n][k] = *(const LAS bf16x8*)(lds + PG8_SB(b, h) + boff + n * 2048 + k * 1024); } while (0)
; #define PG8_WAIT_V(n) asm volatile("s_waitcnt vmcnt(" #n ")" ::: "memory")
; #define PG8_WAIT_L(n) asm volatile("s_waitcnt lgkmcnt(" #n ")" ::: "memory")
; #define PG8_BAR __builtin_amdgcn_s_barrier()
; #define PG8_SCHED __builtin_amdgcn_sched_barrier(0)
;     ...
;             PG8_LDB(B0, 1, 0); PG8_LDB(B1, 1, 1); PG8_SCHED; PG8_LDA(At, 1, 0); PG8_STAGEX(rsA, PG8_SA(0, 1), a2 + hstepA, voffA);
;             PG8_WAIT_V(8); PG8_WAIT_L(0); PG8_BAR; PG8_MMA(0, 0, At, B0); PG8_MMA(0, 1, At, B1); PG8_BAR; PG8_SCHED;
;             PG8_LDA(At, 1, 1); PG8_STAGEX(rsB, PG8_SB(1, 0), b3, voffB); PG8_STAGEX(rsB, PG8_SB(1, 1), b3 + hstepB, voffB); PG8_STAGEX(rsA, PG8_SA(1, 0), a3, voffA);
;             PG8_WAIT_V(8); PG8_WAIT_L(0); PG8_BAR; PG8_MMA(1, 0, At, B0); PG8_MMA(1, 1, At, B1); PG8_BAR; PG8_SCHED;
;         }
	v_add_u32_e32 v118, 0x18000, v210
	v_add_u32_e32 v160, 0x1c000, v210
	ds_read_b128 v[106:109], v118
	ds_read_b128 v[110:113], v118 offset:1024
	ds_read_b128 v[114:117], v118 offset:2048
	ds_read_b128 v[118:121], v118 offset:3072
	ds_read_b128 v[122:125], v160
	ds_read_b128 v[134:137], v160 offset:1024
	ds_read_b128 v[156:159], v160 offset:2048
	ds_read_b128 v[160:163], v160 offset:3072
	s_add_i32 s61, s61, 0x158000
	s_mov_b32 m0, s20
	ds_read_b128 v[164:167], v211 offset:32768
	ds_read_b128 v[168:171], v211 offset:33792
	ds_read_b128 v[182:185], v211 offset:34816
	ds_read_b128 v[186:189], v211 offset:35840
	ds_read_b128 v[190:193], v211 offset:36864
	ds_read_b128 v[194:197], v211 offset:37888
	ds_read_b128 v[198:201], v211 offset:38912
	ds_read_b128 v[202:205], v211 offset:39936
	buffer_load_dwordx4 v178, s[76:79], s61 offen lds
	s_mov_b32 m0, s21
	s_nop 0
	buffer_load_dwordx4 v206, s[76:79], s61 offen lds
	s_waitcnt vmcnt(8)
	s_waitcnt lgkmcnt(0)
	s_barrier
	s_setprio 1
	v_mfma_f32_16x16x32_bf16 v[150:153], v[106:109], v[164:167], v[150:153]
	v_mfma_f32_16x16x32_bf16 v[146:149], v[114:117], v[164:167], v[146:149]
	v_mfma_f32_16x16x32_bf16 v[142:145], v[106:109], v[182:185], v[142:145]
	v_mfma_f32_16x16x32_bf16 v[138:141], v[114:117], v[182:185], v[138:141]
	v_mfma_f32_16x16x32_bf16 v[130:133], v[106:109], v[190:193], v[130:133]
	v_mfma_f32_16x16x32_bf16 v[126:129], v[114:117], v[190:193], v[126:129]
	v_mfma_f32_16x16x32_bf16 v[102:105], v[106:109], v[198:201], v[102:105]
	v_mfma_f32_16x16x32_bf16 v[98:101], v[114:117], v[198:201], v[98:101]
	v_mfma_f32_16x16x32_bf16 v[150:153], v[110:113], v[168:171], v[150:153]
	v_mfma_f32_16x16x32_bf16 v[146:149], v[118:121], v[168:171], v[146:149]
	v_mfma_f32_16x16x32_bf16 v[142:145], v[110:113], v[186:189], v[142:145]
	v_mfma_f32_16x16x32_bf16 v[138:141], v[118:121], v[186:189], v[138:141]
	v_mfma_f32_16x16x32_bf16 v[130:133], v[110:113], v[194:197], v[130:133]
	v_mfma_f32_16x16x32_bf16 v[126:129], v[118:121], v[194:197], v[126:129]
	v_mfma_f32_16x16x32_bf16 v[102:105], v[110:113], v[202:205], v[102:105]
	v_mfma_f32_16x16x32_bf16 v[98:101], v[118:121], v[202:205], v[98:101]
	v_mfma_f32_16x16x32_bf16 v[62:65], v[122:125], v[164:167], v[62:65]
	v_mfma_f32_16x16x32_bf16 v[58:61], v[156:159], v[164:167], v[58:61]
	v_mfma_f32_16x16x32_bf16 v[54:57], v[122:125], v[182:185], v[54:57]
	v_mfma_f32_16x16x32_bf16 v[50:53], v[156:159], v[182:185], v[50:53]
	v_mfma_f32_16x16x32_bf16 v[46:49], v[122:125], v[190:193], v[46:49]
	v_mfma_f32_16x16x32_bf16 v[42:45], v[156:159], v[190:193], v[42:45]
	v_mfma_f32_16x16x32_bf16 v[38:41], v[122:125], v[198:201], v[38:41]
	v_mfma_f32_16x16x32_bf16 v[34:37], v[156:159], v[198:201], v[34:37]
	v_mfma_f32_16x16x32_bf16 v[62:65], v[134:137], v[168:171], v[62:65]
	v_mfma_f32_16x16x32_bf16 v[58:61], v[160:163], v[168:171], v[58:61]
	v_mfma_f32_16x16x32_bf16 v[54:57], v[134:137], v[186:189], v[54:57]
	v_mfma_f32_16x16x32_bf16 v[50:53], v[160:163], v[186:189], v[50:53]
	v_mfma_f32_16x16x32_bf16 v[46:49], v[134:137], v[194:197], v[46:49]
	v_mfma_f32_16x16x32_bf16 v[42:45], v[160:163], v[194:197], v[42:45]
	v_mfma_f32_16x16x32_bf16 v[38:41], v[134:137], v[202:205], v[38:41]
	v_mfma_f32_16x16x32_bf16 v[34:37], v[160:163], v[202:205], v[34:37]
	s_setprio 0
	s_barrier
	s_mov_b32 m0, s28
	s_or_b32 s61, s60, 0x80
	ds_read_b128 v[164:167], v211 offset:49152
	ds_read_b128 v[168:171], v211 offset:50176
	ds_read_b128 v[182:185], v211 offset:51200
	ds_read_b128 v[186:189], v211 offset:52224
	ds_read_b128 v[190:193], v211 offset:53248
	ds_read_b128 v[194:197], v211 offset:54272
	ds_read_b128 v[198:201], v211 offset:55296
	ds_read_b128 v[202:205], v211 offset:56320
	buffer_load_dwordx4 v179, s[40:43], s61 offen lds
	s_mov_b32 m0, s29
	s_add_i32 s60, s60, 0x158080
	buffer_load_dwordx4 v207, s[40:43], s61 offen lds
	s_mov_b32 m0, s66
	s_nop 0
	buffer_load_dwordx4 v179, s[40:43], s60 offen lds
	s_mov_b32 m0, s67
	s_nop 0
	buffer_load_dwordx4 v207, s[40:43], s60 offen lds
	s_mov_b32 m0, s54
	s_nop 0
	buffer_load_dwordx4 v178, s[76:79], s59 offen lds
	s_mov_b32 m0, s55
	s_nop 0
	buffer_load_dwordx4 v206, s[76:79], s59 offen lds
	s_waitcnt vmcnt(8)
	s_waitcnt lgkmcnt(0)
	s_barrier
	s_setprio 1
	v_mfma_f32_16x16x32_bf16 v[94:97], v[106:109], v[164:167], v[94:97]
	v_mfma_f32_16x16x32_bf16 v[90:93], v[114:117], v[164:167], v[90:93]
	v_mfma_f32_16x16x32_bf16 v[86:89], v[106:109], v[182:185], v[86:89]
	v_mfma_f32_16x16x32_bf16 v[82:85], v[114:117], v[182:185], v[82:85]
	v_mfma_f32_16x16x32_bf16 v[78:81], v[106:109], v[190:193], v[78:81]
	v_mfma_f32_16x16x32_bf16 v[74:77], v[114:117], v[190:193], v[74:77]
	v_mfma_f32_16x16x32_bf16 v[70:73], v[106:109], v[198:201], v[70:73]
	v_mfma_f32_16x16x32_bf16 v[66:69], v[114:117], v[198:201], v[66:69]
	v_mfma_f32_16x16x32_bf16 v[94:97], v[110:113], v[168:171], v[94:97]
	v_mfma_f32_16x16x32_bf16 v[90:93], v[118:121], v[168:171], v[90:93]
	v_mfma_f32_16x16x32_bf16 v[86:89], v[110:113], v[186:189], v[86:89]
	v_mfma_f32_16x16x32_bf16 v[82:85], v[118:121], v[186:189], v[82:85]
	v_mfma_f32_16x16x32_bf16 v[78:81], v[110:113], v[194:197], v[78:81]
	v_mfma_f32_16x16x32_bf16 v[74:77], v[118:121], v[194:197], v[74:77]
	v_mfma_f32_16x16x32_bf16 v[70:73], v[110:113], v[202:205], v[70:73]
	v_mfma_f32_16x16x32_bf16 v[66:69], v[118:121], v[202:205], v[66:69]
	v_mfma_f32_16x16x32_bf16 v[30:33], v[122:125], v[164:167], v[30:33]
	v_mfma_f32_16x16x32_bf16 v[26:29], v[156:159], v[164:167], v[26:29]
	v_mfma_f32_16x16x32_bf16 v[22:25], v[122:125], v[182:185], v[22:25]
	v_mfma_f32_16x16x32_bf16 v[18:21], v[156:159], v[182:185], v[18:21]
	v_mfma_f32_16x16x32_bf16 v[14:17], v[122:125], v[190:193], v[14:17]
	v_mfma_f32_16x16x32_bf16 v[10:13], v[156:159], v[190:193], v[10:13]
	v_mfma_f32_16x16x32_bf16 v[6:9], v[122:125], v[198:201], v[6:9]
	v_mfma_f32_16x16x32_bf16 v[2:5], v[156:159], v[198:201], v[2:5]
	v_mfma_f32_16x16x32_bf16 v[30:33], v[134:137], v[168:171], v[30:33]
	v_mfma_f32_16x16x32_bf16 v[26:29], v[160:163], v[168:171], v[26:29]
	v_mfma_f32_16x16x32_bf16 v[22:25], v[134:137], v[186:189], v[22:25]
	v_mfma_f32_16x16x32_bf16 v[18:21], v[160:163], v[186:189], v[18:21]
	v_mfma_f32_16x16x32_bf16 v[14:17], v[134:137], v[194:197], v[14:17]
	v_mfma_f32_16x16x32_bf16 v[10:13], v[160:163], v[194:197], v[10:13]
	v_mfma_f32_16x16x32_bf16 v[6:9], v[134:137], v[202:205], v[6:9]
	v_mfma_f32_16x16x32_bf16 v[2:5], v[160:163], v[202:205], v[2:5]
	s_setprio 0
	s_barrier
	s_add_i32 s58, s58, 2
	s_addk_i32 s51, 0x100
	s_addk_i32 s57, 0x100
	s_cmpk_gt_u32 s58, 0x53
	s_cbranch_scc0 .LBB0_323
	s_and_b64 vcc, exec, s[48:49]
	s_cbranch_vccz .LBB0_326
	s_barrier

; #define PG8_WAIT_L(n) asm volatile("s_waitcnt lgkmcnt(" #n ")" ::: "memory")
; #define PG8_BAR __builtin_amdgcn_s_barrier()
; #define PG8_SCHED __builtin_amdgcn_sched_barrier(0)
;     ...
;                 PG8_WAIT_L(0); PG8_BAR; if (w0) { PG8_MMA(0, 0, At, B0); PG8_MMA(0, 1, At, B1); } PG8_BAR; PG8_SCHED;
.LBB0_355:
	s_waitcnt lgkmcnt(0)
	s_and_b64 vcc, exec, s[38:39]
	s_barrier
	s_cbranch_vccnz .LBB0_357
	s_setprio 1
	s_waitcnt lgkmcnt(7)
	v_mfma_f32_16x16x32_bf16 v[62:65], v[66:69], v[98:101], v[62:65]
	v_mfma_f32_16x16x32_bf16 v[58:61], v[74:77], v[98:101], v[58:61]
	v_mfma_f32_16x16x32_bf16 v[54:57], v[66:69], v[106:109], v[54:57]
	v_mfma_f32_16x16x32_bf16 v[50:53], v[74:77], v[106:109], v[50:53]
	v_mfma_f32_16x16x32_bf16 v[46:49], v[66:69], v[114:117], v[46:49]
	v_mfma_f32_16x16x32_bf16 v[42:45], v[74:77], v[114:117], v[42:45]
	v_mfma_f32_16x16x32_bf16 v[38:41], v[66:69], v[122:125], v[38:41]
	v_mfma_f32_16x16x32_bf16 v[34:37], v[74:77], v[122:125], v[34:37]
	v_mfma_f32_16x16x32_bf16 v[62:65], v[70:73], v[102:105], v[62:65]
	v_mfma_f32_16x16x32_bf16 v[58:61], v[78:81], v[102:105], v[58:61]
	v_mfma_f32_16x16x32_bf16 v[54:57], v[70:73], v[110:113], v[54:57]
	v_mfma_f32_16x16x32_bf16 v[50:53], v[78:81], v[110:113], v[50:53]
	v_mfma_f32_16x16x32_bf16 v[46:49], v[70:73], v[118:121], v[46:49]
	v_mfma_f32_16x16x32_bf16 v[42:45], v[78:81], v[118:121], v[42:45]
	v_mfma_f32_16x16x32_bf16 v[38:41], v[70:73], v[126:129], v[38:41]
	v_mfma_f32_16x16x32_bf16 v[34:37], v[78:81], v[126:129], v[34:37]
	v_mfma_f32_16x16x32_bf16 v[30:33], v[82:85], v[98:101], v[30:33]
	v_mfma_f32_16x16x32_bf16 v[26:29], v[90:93], v[98:101], v[26:29]
	v_mfma_f32_16x16x32_bf16 v[22:25], v[82:85], v[106:109], v[22:25]
	v_mfma_f32_16x16x32_bf16 v[18:21], v[90:93], v[106:109], v[18:21]
	v_mfma_f32_16x16x32_bf16 v[14:17], v[82:85], v[114:117], v[14:17]
	v_mfma_f32_16x16x32_bf16 v[10:13], v[90:93], v[114:117], v[10:13]
	v_mfma_f32_16x16x32_bf16 v[6:9], v[82:85], v[122:125], v[6:9]
	v_mfma_f32_16x16x32_bf16 v[2:5], v[90:93], v[122:125], v[2:5]
	v_mfma_f32_16x16x32_bf16 v[30:33], v[86:89], v[102:105], v[30:33]
	v_mfma_f32_16x16x32_bf16 v[26:29], v[94:97], v[102:105], v[26:29]
	v_mfma_f32_16x16x32_bf16 v[22:25], v[86:89], v[110:113], v[22:25]
	v_mfma_f32_16x16x32_bf16 v[18:21], v[94:97], v[110:113], v[18:21]
	v_mfma_f32_16x16x32_bf16 v[14:17], v[86:89], v[118:121], v[14:17]
	v_mfma_f32_16x16x32_bf16 v[10:13], v[94:97], v[118:121], v[10:13]
	v_mfma_f32_16x16x32_bf16 v[6:9], v[86:89], v[126:129], v[6:9]
	v_mfma_f32_16x16x32_bf16 v[2:5], v[94:97], v[126:129], v[2:5]
	s_setprio 0

; #define PG8_WAIT_L(n) asm volatile("s_waitcnt lgkmcnt(" #n ")" ::: "memory")
; #define PG8_BAR __builtin_amdgcn_s_barrier()
; #define PG8_SCHED __builtin_amdgcn_sched_barrier(0)
;     ...
;                 PG8_WAIT_L(0); PG8_BAR; if (w0) { PG8_MMA(0, 0, At, B0); PG8_MMA(0, 1, At, B1); } PG8_BAR; PG8_SCHED;
.LBB0_359:
	s_waitcnt lgkmcnt(0)
	s_and_b64 vcc, exec, s[38:39]
	s_barrier
	s_cbranch_vccnz .LBB0_352
	s_setprio 1
	s_waitcnt lgkmcnt(7)
	v_mfma_f32_16x16x32_bf16 v[62:65], v[66:69], v[98:101], v[62:65]
	v_mfma_f32_16x16x32_bf16 v[58:61], v[74:77], v[98:101], v[58:61]
	v_mfma_f32_16x16x32_bf16 v[54:57], v[66:69], v[106:109], v[54:57]
	v_mfma_f32_16x16x32_bf16 v[50:53], v[74:77], v[106:109], v[50:53]
	v_mfma_f32_16x16x32_bf16 v[46:49], v[66:69], v[114:117], v[46:49]
	v_mfma_f32_16x16x32_bf16 v[42:45], v[74:77], v[114:117], v[42:45]
	v_mfma_f32_16x16x32_bf16 v[38:41], v[66:69], v[122:125], v[38:41]
	v_mfma_f32_16x16x32_bf16 v[34:37], v[74:77], v[122:125], v[34:37]
	v_mfma_f32_16x16x32_bf16 v[62:65], v[70:73], v[102:105], v[62:65]
	v_mfma_f32_16x16x32_bf16 v[58:61], v[78:81], v[102:105], v[58:61]
	v_mfma_f32_16x16x32_bf16 v[54:57], v[70:73], v[110:113], v[54:57]
	v_mfma_f32_16x16x32_bf16 v[50:53], v[78:81], v[110:113], v[50:53]
	v_mfma_f32_16x16x32_bf16 v[46:49], v[70:73], v[118:121], v[46:49]
	v_mfma_f32_16x16x32_bf16 v[42:45], v[78:81], v[118:121], v[42:45]
	v_mfma_f32_16x16x32_bf16 v[38:41], v[70:73], v[126:129], v[38:41]
	v_mfma_f32_16x16x32_bf16 v[34:37], v[78:81], v[126:129], v[34:37]
	v_mfma_f32_16x16x32_bf16 v[30:33], v[82:85], v[98:101], v[30:33]
	v_mfma_f32_16x16x32_bf16 v[26:29], v[90:93], v[98:101], v[26:29]
	v_mfma_f32_16x16x32_bf16 v[22:25], v[82:85], v[106:109], v[22:25]
	v_mfma_f32_16x16x32_bf16 v[18:21], v[90:93], v[106:109], v[18:21]
	v_mfma_f32_16x16x32_bf16 v[14:17], v[82:85], v[114:117], v[14:17]
	v_mfma_f32_16x16x32_bf16 v[10:13], v[90:93], v[114:117], v[10:13]
	v_mfma_f32_16x16x32_bf16 v[6:9], v[82:85], v[122:125], v[6:9]
	v_mfma_f32_16x16x32_bf16 v[2:5], v[90:93], v[122:125], v[2:5]
	v_mfma_f32_16x16x32_bf16 v[30:33], v[86:89], v[102:105], v[30:33]
	v_mfma_f32_16x16x32_bf16 v[26:29], v[94:97], v[102:105], v[26:29]
	v_mfma_f32_16x16x32_bf16 v[22:25], v[86:89], v[110:113], v[22:25]
	v_mfma_f32_16x16x32_bf16 v[18:21], v[94:97], v[110:113], v[18:21]
	v_mfma_f32_16x16x32_bf16 v[14:17], v[86:89], v[118:121], v[14:17]
	v_mfma_f32_16x16x32_bf16 v[10:13], v[94:97], v[118:121], v[10:13]
	v_mfma_f32_16x16x32_bf16 v[6:9], v[86:89], v[126:129], v[6:9]
	v_mfma_f32_16x16x32_bf16 v[2:5], v[94:97], v[126:129], v[2:5]
	s_setprio 0
	s_branch .LBB0_352

; #define PG8_STAGEX(rs, bufoff, soff, voff) do { _Pragma("unroll") for (int _i = 0; _i < 2; ++_i) \
;         __builtin_amdgcn_raw_ptr_buffer_load_lds(rs, (LAS unsigned*)(lds + (bufoff) + ldsw + _i * 8192), 16, (voff)[_i], (soff), 0, 0); } while (0)
; #define PG8_LDA(dst, b, h) do { _Pragma("unroll") for (int m = 0; m < 4; ++m) _Pragma("unroll") for (int k = 0; k < 2; ++k) dst[m][k] = *(const LAS bf16x8*)(lds + PG8_SA(b, h) + aoff + m * 2048 + k * 1024); } while (0)
; #define PG8_LDB(dst, b, h) do { _Pragma("unroll") for (int n = 0; n < 2; ++n) _Pragma("unroll") for (int k = 0; k < 2; ++k) dst[n][k] = *(const LAS bf16x8*)(lds + PG8_SB(b, h) + boff + n * 2048 + k * 1024); } while (0)
; #define PG8_WAIT_V(n) asm volatile("s_waitcnt vmcnt(" #n ")" ::: "memory")
; #define PG8_WAIT_L(n) asm volatile("s_waitcnt lgkmcnt(" #n ")" ::: "memory")
; #define PG8_BAR __builtin_amdgcn_s_barrier()
; #define PG8_SCHED __builtin_amdgcn_sched_barrier(0)
;     ...
;             PG8_LDB(B0, 0, 0); PG8_LDB(B1, 0, 1); PG8_SCHED; PG8_LDA(At, 0, 0); PG8_STAGEX(rsA, PG8_SA(1, 1), a1 + hstepA, voffA);
;             PG8_WAIT_V(8); PG8_WAIT_L(0); PG8_BAR; PG8_MMA(0, 0, At, B0); PG8_MMA(0, 1, At, B1); PG8_BAR; PG8_SCHED;
;             PG8_LDA(At, 0, 1); PG8_STAGEX(rsB, PG8_SB(0, 0), b2, voffB); PG8_STAGEX(rsB, PG8_SB(0, 1), b2 + hstepB, voffB); PG8_STAGEX(rsA, PG8_SA(0, 0), a2, voffA);
;             PG8_WAIT_V(8); PG8_WAIT_L(0); PG8_BAR; PG8_MMA(1, 0, At, B0); PG8_MMA(1, 1, At, B1); PG8_BAR; PG8_SCHED;
.LBB0_437:
	v_add_u32_e32 v142, 0x10000, v220
	v_add_u32_e32 v158, 0x14000, v220
	ds_read_b128 v[130:133], v142
	ds_read_b128 v[134:137], v142 offset:1024
	ds_read_b128 v[138:141], v142 offset:2048
	ds_read_b128 v[142:145], v142 offset:3072
	ds_read_b128 v[146:149], v158
	ds_read_b128 v[150:153], v158 offset:1024
	ds_read_b128 v[154:157], v158 offset:2048
	ds_read_b128 v[158:161], v158 offset:3072
	s_add_i32 s30, s7, 0xfff80080
	s_cmp_eq_u32 s29, 28
	s_cselect_b32 s50, s2, s30
	s_cselect_b32 s31, s5, s28
	s_or_b32 s30, s50, 0x80
	s_mov_b32 m0, s20
	ds_read_b128 v[162:165], v221
	ds_read_b128 v[170:173], v221 offset:1024
	ds_read_b128 v[182:185], v221 offset:2048
	ds_read_b128 v[186:189], v221 offset:3072
	ds_read_b128 v[190:193], v221 offset:4096
	ds_read_b128 v[194:197], v221 offset:5120
	ds_read_b128 v[198:201], v221 offset:6144
	ds_read_b128 v[202:205], v221 offset:7168
	buffer_load_dwordx4 v178, s[76:79], s7 offen lds
	s_mov_b32 m0, s22
	s_nop 0
	buffer_load_dwordx4 v210, s[76:79], s7 offen lds
	s_waitcnt vmcnt(8)
	s_waitcnt lgkmcnt(0)
	s_barrier
	s_setprio 1
	v_mfma_f32_16x16x32_bf16 v[126:129], v[130:133], v[162:165], v[126:129]
	v_mfma_f32_16x16x32_bf16 v[110:113], v[138:141], v[162:165], v[110:113]
	v_mfma_f32_16x16x32_bf16 v[118:121], v[130:133], v[182:185], v[118:121]
	v_mfma_f32_16x16x32_bf16 v[102:105], v[138:141], v[182:185], v[102:105]
	v_mfma_f32_16x16x32_bf16 v[114:117], v[130:133], v[190:193], v[114:117]
	v_mfma_f32_16x16x32_bf16 v[98:101], v[138:141], v[190:193], v[98:101]
	v_mfma_f32_16x16x32_bf16 v[122:125], v[130:133], v[198:201], v[122:125]
	v_mfma_f32_16x16x32_bf16 v[106:109], v[138:141], v[198:201], v[106:109]
	v_mfma_f32_16x16x32_bf16 v[126:129], v[134:137], v[170:173], v[126:129]
	v_mfma_f32_16x16x32_bf16 v[110:113], v[142:145], v[170:173], v[110:113]
	v_mfma_f32_16x16x32_bf16 v[118:121], v[134:137], v[186:189], v[118:121]
	v_mfma_f32_16x16x32_bf16 v[102:105], v[142:145], v[186:189], v[102:105]
	v_mfma_f32_16x16x32_bf16 v[114:117], v[134:137], v[194:197], v[114:117]
	v_mfma_f32_16x16x32_bf16 v[98:101], v[142:145], v[194:197], v[98:101]
	v_mfma_f32_16x16x32_bf16 v[122:125], v[134:137], v[202:205], v[122:125]
	v_mfma_f32_16x16x32_bf16 v[106:109], v[142:145], v[202:205], v[106:109]
	v_mfma_f32_16x16x32_bf16 v[62:65], v[146:149], v[162:165], v[62:65]
	v_mfma_f32_16x16x32_bf16 v[46:49], v[154:157], v[162:165], v[46:49]
	v_mfma_f32_16x16x32_bf16 v[54:57], v[146:149], v[182:185], v[54:57]
	v_mfma_f32_16x16x32_bf16 v[38:41], v[154:157], v[182:185], v[38:41]
	v_mfma_f32_16x16x32_bf16 v[50:53], v[146:149], v[190:193], v[50:53]
	v_mfma_f32_16x16x32_bf16 v[34:37], v[154:157], v[190:193], v[34:37]
	v_mfma_f32_16x16x32_bf16 v[58:61], v[146:149], v[198:201], v[58:61]
	v_mfma_f32_16x16x32_bf16 v[42:45], v[154:157], v[198:201], v[42:45]
	v_mfma_f32_16x16x32_bf16 v[62:65], v[150:153], v[170:173], v[62:65]
	v_mfma_f32_16x16x32_bf16 v[46:49], v[158:161], v[170:173], v[46:49]
	v_mfma_f32_16x16x32_bf16 v[54:57], v[150:153], v[186:189], v[54:57]
	v_mfma_f32_16x16x32_bf16 v[38:41], v[158:161], v[186:189], v[38:41]
	v_mfma_f32_16x16x32_bf16 v[50:53], v[150:153], v[194:197], v[50:53]
	v_mfma_f32_16x16x32_bf16 v[34:37], v[158:161], v[194:197], v[34:37]
	v_mfma_f32_16x16x32_bf16 v[58:61], v[150:153], v[202:205], v[58:61]
	v_mfma_f32_16x16x32_bf16 v[42:45], v[158:161], v[202:205], v[42:45]
	s_setprio 0
	s_barrier
	s_mov_b32 m0, s90
	s_mov_b32 s58, s78
	s_mov_b32 s59, s79
	ds_read_b128 v[162:165], v221 offset:16384
	ds_read_b128 v[170:173], v221 offset:17408
	ds_read_b128 v[182:185], v221 offset:18432
	ds_read_b128 v[186:189], v221 offset:19456
	ds_read_b128 v[190:193], v221 offset:20480
	ds_read_b128 v[194:197], v221 offset:21504
	ds_read_b128 v[198:201], v221 offset:22528
	ds_read_b128 v[202:205], v221 offset:23552
	buffer_load_dwordx4 v179, s[56:59], s31 offen lds
	s_mov_b32 m0, s91
	s_add_i32 s51, s31, 0x80000
	buffer_load_dwordx4 v211, s[56:59], s31 offen lds
	s_mov_b32 m0, s9
	s_nop 0
	buffer_load_dwordx4 v179, s[56:59], s51 offen lds
	s_mov_b32 m0, s10
	s_nop 0
	buffer_load_dwordx4 v211, s[56:59], s51 offen lds
	s_mov_b32 m0, s89
	s_nop 0
	buffer_load_dwordx4 v178, s[76:79], s50 offen lds
	s_mov_b32 m0, s11
	s_nop 0
	buffer_load_dwordx4 v210, s[76:79], s50 offen lds
	s_waitcnt vmcnt(8)
	s_waitcnt lgkmcnt(0)
	s_barrier
	s_setprio 1
	v_mfma_f32_16x16x32_bf16 v[94:97], v[130:133], v[162:165], v[94:97]
	v_mfma_f32_16x16x32_bf16 v[78:81], v[138:141], v[162:165], v[78:81]
	v_mfma_f32_16x16x32_bf16 v[86:89], v[130:133], v[182:185], v[86:89]
	v_mfma_f32_16x16x32_bf16 v[70:73], v[138:141], v[182:185], v[70:73]
	v_mfma_f32_16x16x32_bf16 v[82:85], v[130:133], v[190:193], v[82:85]
	v_mfma_f32_16x16x32_bf16 v[66:69], v[138:141], v[190:193], v[66:69]
	v_mfma_f32_16x16x32_bf16 v[90:93], v[130:133], v[198:201], v[90:93]
	v_mfma_f32_16x16x32_bf16 v[74:77], v[138:141], v[198:201], v[74:77]
	v_mfma_f32_16x16x32_bf16 v[94:97], v[134:137], v[170:173], v[94:97]
	v_mfma_f32_16x16x32_bf16 v[78:81], v[142:145], v[170:173], v[78:81]
	v_mfma_f32_16x16x32_bf16 v[86:89], v[134:137], v[186:189], v[86:89]
	v_mfma_f32_16x16x32_bf16 v[70:73], v[142:145], v[186:189], v[70:73]
	v_mfma_f32_16x16x32_bf16 v[82:85], v[134:137], v[194:197], v[82:85]
	v_mfma_f32_16x16x32_bf16 v[66:69], v[142:145], v[194:197], v[66:69]
	v_mfma_f32_16x16x32_bf16 v[90:93], v[134:137], v[202:205], v[90:93]
	v_mfma_f32_16x16x32_bf16 v[74:77], v[142:145], v[202:205], v[74:77]
	v_mfma_f32_16x16x32_bf16 v[30:33], v[146:149], v[162:165], v[30:33]
	v_mfma_f32_16x16x32_bf16 v[14:17], v[154:157], v[162:165], v[14:17]
	v_mfma_f32_16x16x32_bf16 v[22:25], v[146:149], v[182:185], v[22:25]
	v_mfma_f32_16x16x32_bf16 v[10:13], v[154:157], v[182:185], v[10:13]
	v_mfma_f32_16x16x32_bf16 v[18:21], v[146:149], v[190:193], v[18:21]
	v_mfma_f32_16x16x32_bf16 v[2:5], v[154:157], v[190:193], v[2:5]
	v_mfma_f32_16x16x32_bf16 v[26:29], v[146:149], v[198:201], v[26:29]
	v_mfma_f32_16x16x32_bf16 v[6:9], v[154:157], v[198:201], v[6:9]
	v_mfma_f32_16x16x32_bf16 v[30:33], v[150:153], v[170:173], v[30:33]
	v_mfma_f32_16x16x32_bf16 v[14:17], v[158:161], v[170:173], v[14:17]
	v_mfma_f32_16x16x32_bf16 v[22:25], v[150:153], v[186:189], v[22:25]
	v_mfma_f32_16x16x32_bf16 v[10:13], v[158:161], v[186:189], v[10:13]
	v_mfma_f32_16x16x32_bf16 v[18:21], v[150:153], v[194:197], v[18:21]
	v_mfma_f32_16x16x32_bf16 v[2:5], v[158:161], v[194:197], v[2:5]
	v_mfma_f32_16x16x32_bf16 v[26:29], v[150:153], v[202:205], v[26:29]
	v_mfma_f32_16x16x32_bf16 v[6:9], v[158:161], v[202:205], v[6:9]
	s_setprio 0
	s_barrier
; #define PG8_STAGEX(rs, bufoff, soff, voff) do { _Pragma("unroll") for (int _i = 0; _i < 2; ++_i) \
;         __builtin_amdgcn_raw_ptr_buffer_load_lds(rs, (LAS unsigned*)(lds + (bufoff) + ldsw + _i * 8192), 16, (voff)[_i], (soff), 0, 0); } while (0)
; #define PG8_LDA(dst, b, h) do { _Pragma("unroll") for (int m = 0; m < 4; ++m) _Pragma("unroll") for (int k = 0; k < 2; ++k) dst[m][k] = *(const LAS bf16x8*)(lds + PG8_SA(b, h) + aoff + m * 2048 + k * 1024); } while (0)
; #define PG8_LDB(dst, b, h) do { _Pragma("unroll") for (int n = 0; n < 2; ++n) _Pragma("unroll") for (int k = 0; k < 2; ++k) dst[n][k] = *(const LAS bf16x8*)(lds + PG8_SB(b, h) + boff + n * 2048 + k * 1024); } while (0)
; #define PG8_WAIT_V(n) asm volatile("s_waitcnt vmcnt(" #n ")" ::: "memory")
; #define PG8_WAIT_L(n) asm volatile("s_waitcnt lgkmcnt(" #n ")" ::: "memory")
; #define PG8_BAR __builtin_amdgcn_s_barrier()
; #define PG8_SCHED __builtin_amdgcn_sched_barrier(0)
;     ...
;             PG8_LDB(B0, 1, 0); PG8_LDB(B1, 1, 1); PG8_SCHED; PG8_LDA(At, 1, 0); PG8_STAGEX(rsA, PG8_SA(0, 1), a2 + hstepA, voffA);
;             PG8_WAIT_V(8); PG8_WAIT_L(0); PG8_BAR; PG8_MMA(0, 0, At, B0); PG8_MMA(0, 1, At, B1); PG8_BAR; PG8_SCHED;
;             PG8_LDA(At, 1, 1); PG8_STAGEX(rsB, PG8_SB(1, 0), b3, voffB); PG8_STAGEX(rsB, PG8_SB(1, 1), b3 + hstepB, voffB); PG8_STAGEX(rsA, PG8_SA(1, 0), a3, voffA);
;             PG8_WAIT_V(8); PG8_WAIT_L(0); PG8_BAR; PG8_MMA(1, 0, At, B0); PG8_MMA(1, 1, At, B1); PG8_BAR; PG8_SCHED;
;         }
	v_add_u32_e32 v142, 0x18000, v220
	v_add_u32_e32 v158, 0x1c000, v220
	ds_read_b128 v[130:133], v142
	ds_read_b128 v[134:137], v142 offset:1024
	ds_read_b128 v[138:141], v142 offset:2048
	ds_read_b128 v[142:145], v142 offset:3072
	ds_read_b128 v[146:149], v158
	ds_read_b128 v[150:153], v158 offset:1024
	ds_read_b128 v[154:157], v158 offset:2048
	ds_read_b128 v[158:161], v158 offset:3072
	s_add_i32 s50, s50, 0x80000
	s_mov_b32 m0, s74
	ds_read_b128 v[162:165], v221 offset:32768
	ds_read_b128 v[170:173], v221 offset:33792
	ds_read_b128 v[182:185], v221 offset:34816
	ds_read_b128 v[186:189], v221 offset:35840
	ds_read_b128 v[190:193], v221 offset:36864
	ds_read_b128 v[194:197], v221 offset:37888
	ds_read_b128 v[198:201], v221 offset:38912
	ds_read_b128 v[202:205], v221 offset:39936
	buffer_load_dwordx4 v178, s[76:79], s50 offen lds
	s_mov_b32 m0, s12
	s_nop 0
	buffer_load_dwordx4 v210, s[76:79], s50 offen lds
	s_waitcnt vmcnt(8)
	s_waitcnt lgkmcnt(0)
	s_barrier
	s_setprio 1
	v_mfma_f32_16x16x32_bf16 v[126:129], v[130:133], v[162:165], v[126:129]
	v_mfma_f32_16x16x32_bf16 v[110:113], v[138:141], v[162:165], v[110:113]
	v_mfma_f32_16x16x32_bf16 v[118:121], v[130:133], v[182:185], v[118:121]
	v_mfma_f32_16x16x32_bf16 v[102:105], v[138:141], v[182:185], v[102:105]
	v_mfma_f32_16x16x32_bf16 v[114:117], v[130:133], v[190:193], v[114:117]
	v_mfma_f32_16x16x32_bf16 v[98:101], v[138:141], v[190:193], v[98:101]
	v_mfma_f32_16x16x32_bf16 v[122:125], v[130:133], v[198:201], v[122:125]
	v_mfma_f32_16x16x32_bf16 v[106:109], v[138:141], v[198:201], v[106:109]
	v_mfma_f32_16x16x32_bf16 v[126:129], v[134:137], v[170:173], v[126:129]
	v_mfma_f32_16x16x32_bf16 v[110:113], v[142:145], v[170:173], v[110:113]
	v_mfma_f32_16x16x32_bf16 v[118:121], v[134:137], v[186:189], v[118:121]
	v_mfma_f32_16x16x32_bf16 v[102:105], v[142:145], v[186:189], v[102:105]
	v_mfma_f32_16x16x32_bf16 v[114:117], v[134:137], v[194:197], v[114:117]
	v_mfma_f32_16x16x32_bf16 v[98:101], v[142:145], v[194:197], v[98:101]
	v_mfma_f32_16x16x32_bf16 v[122:125], v[134:137], v[202:205], v[122:125]
	v_mfma_f32_16x16x32_bf16 v[106:109], v[142:145], v[202:205], v[106:109]
	v_mfma_f32_16x16x32_bf16 v[62:65], v[146:149], v[162:165], v[62:65]
	v_mfma_f32_16x16x32_bf16 v[46:49], v[154:157], v[162:165], v[46:49]
	v_mfma_f32_16x16x32_bf16 v[54:57], v[146:149], v[182:185], v[54:57]
	v_mfma_f32_16x16x32_bf16 v[38:41], v[154:157], v[182:185], v[38:41]
	v_mfma_f32_16x16x32_bf16 v[50:53], v[146:149], v[190:193], v[50:53]
	v_mfma_f32_16x16x32_bf16 v[34:37], v[154:157], v[190:193], v[34:37]
	v_mfma_f32_16x16x32_bf16 v[58:61], v[146:149], v[198:201], v[58:61]
	v_mfma_f32_16x16x32_bf16 v[42:45], v[154:157], v[198:201], v[42:45]
	v_mfma_f32_16x16x32_bf16 v[62:65], v[150:153], v[170:173], v[62:65]
	v_mfma_f32_16x16x32_bf16 v[46:49], v[158:161], v[170:173], v[46:49]
	v_mfma_f32_16x16x32_bf16 v[54:57], v[150:153], v[186:189], v[54:57]
	v_mfma_f32_16x16x32_bf16 v[38:41], v[158:161], v[186:189], v[38:41]
	v_mfma_f32_16x16x32_bf16 v[50:53], v[150:153], v[194:197], v[50:53]
	v_mfma_f32_16x16x32_bf16 v[34:37], v[158:161], v[194:197], v[34:37]
	v_mfma_f32_16x16x32_bf16 v[58:61], v[150:153], v[202:205], v[58:61]
	v_mfma_f32_16x16x32_bf16 v[42:45], v[158:161], v[202:205], v[42:45]
	s_setprio 0
	s_barrier
	s_mov_b32 m0, s13
	s_or_b32 s50, s31, 0x80
	ds_read_b128 v[162:165], v221 offset:49152
	ds_read_b128 v[170:173], v221 offset:50176
	ds_read_b128 v[182:185], v221 offset:51200
	ds_read_b128 v[186:189], v221 offset:52224
	ds_read_b128 v[190:193], v221 offset:53248
	ds_read_b128 v[194:197], v221 offset:54272
	ds_read_b128 v[198:201], v221 offset:55296
	ds_read_b128 v[202:205], v221 offset:56320
	buffer_load_dwordx4 v179, s[56:59], s50 offen lds
	s_mov_b32 m0, s14
	s_add_i32 s31, s31, 0x80080
	buffer_load_dwordx4 v211, s[56:59], s50 offen lds
	s_mov_b32 m0, s17
	s_nop 0
	buffer_load_dwordx4 v179, s[56:59], s31 offen lds
	s_mov_b32 m0, s18
	s_nop 0
	buffer_load_dwordx4 v211, s[56:59], s31 offen lds
	s_mov_b32 m0, s15
	s_nop 0
	buffer_load_dwordx4 v178, s[76:79], s30 offen lds
	s_mov_b32 m0, s16
	s_nop 0
	buffer_load_dwordx4 v210, s[76:79], s30 offen lds
	s_waitcnt vmcnt(8)
	s_waitcnt lgkmcnt(0)
	s_barrier
	s_setprio 1
	v_mfma_f32_16x16x32_bf16 v[94:97], v[130:133], v[162:165], v[94:97]
	v_mfma_f32_16x16x32_bf16 v[78:81], v[138:141], v[162:165], v[78:81]
	v_mfma_f32_16x16x32_bf16 v[86:89], v[130:133], v[182:185], v[86:89]
	v_mfma_f32_16x16x32_bf16 v[70:73], v[138:141], v[182:185], v[70:73]
	v_mfma_f32_16x16x32_bf16 v[82:85], v[130:133], v[190:193], v[82:85]
	v_mfma_f32_16x16x32_bf16 v[66:69], v[138:141], v[190:193], v[66:69]
	v_mfma_f32_16x16x32_bf16 v[90:93], v[130:133], v[198:201], v[90:93]
	v_mfma_f32_16x16x32_bf16 v[74:77], v[138:141], v[198:201], v[74:77]
	v_mfma_f32_16x16x32_bf16 v[94:97], v[134:137], v[170:173], v[94:97]
	v_mfma_f32_16x16x32_bf16 v[78:81], v[142:145], v[170:173], v[78:81]
	v_mfma_f32_16x16x32_bf16 v[86:89], v[134:137], v[186:189], v[86:89]
	v_mfma_f32_16x16x32_bf16 v[70:73], v[142:145], v[186:189], v[70:73]
	v_mfma_f32_16x16x32_bf16 v[82:85], v[134:137], v[194:197], v[82:85]
	v_mfma_f32_16x16x32_bf16 v[66:69], v[142:145], v[194:197], v[66:69]
	v_mfma_f32_16x16x32_bf16 v[90:93], v[134:137], v[202:205], v[90:93]
	v_mfma_f32_16x16x32_bf16 v[74:77], v[142:145], v[202:205], v[74:77]
	v_mfma_f32_16x16x32_bf16 v[30:33], v[146:149], v[162:165], v[30:33]
	v_mfma_f32_16x16x32_bf16 v[14:17], v[154:157], v[162:165], v[14:17]
	v_mfma_f32_16x16x32_bf16 v[22:25], v[146:149], v[182:185], v[22:25]
	v_mfma_f32_16x16x32_bf16 v[10:13], v[154:157], v[182:185], v[10:13]
	v_mfma_f32_16x16x32_bf16 v[18:21], v[146:149], v[190:193], v[18:21]
	v_mfma_f32_16x16x32_bf16 v[2:5], v[154:157], v[190:193], v[2:5]
	v_mfma_f32_16x16x32_bf16 v[26:29], v[146:149], v[198:201], v[26:29]
	v_mfma_f32_16x16x32_bf16 v[6:9], v[154:157], v[198:201], v[6:9]
	v_mfma_f32_16x16x32_bf16 v[30:33], v[150:153], v[170:173], v[30:33]
	v_mfma_f32_16x16x32_bf16 v[14:17], v[158:161], v[170:173], v[14:17]
	v_mfma_f32_16x16x32_bf16 v[22:25], v[150:153], v[186:189], v[22:25]
	v_mfma_f32_16x16x32_bf16 v[10:13], v[158:161], v[186:189], v[10:13]
	v_mfma_f32_16x16x32_bf16 v[18:21], v[150:153], v[194:197], v[18:21]
	v_mfma_f32_16x16x32_bf16 v[2:5], v[158:161], v[194:197], v[2:5]
	v_mfma_f32_16x16x32_bf16 v[26:29], v[150:153], v[202:205], v[26:29]
	v_mfma_f32_16x16x32_bf16 v[6:9], v[158:161], v[202:205], v[6:9]
	s_setprio 0
	s_barrier
	s_add_i32 s29, s29, 2
	s_addk_i32 s7, 0x100
	s_addk_i32 s28, 0x100
	s_cmp_gt_u32 s29, 29
	s_cbranch_scc0 .LBB0_437
	s_and_b64 vcc, exec, s[84:85]
	s_cbranch_vccz .LBB0_440
	s_barrier

; #define PG8_STAGEX(rs, bufoff, soff, voff) do { _Pragma("unroll") for (int _i = 0; _i < 2; ++_i) \
;         __builtin_amdgcn_raw_ptr_buffer_load_lds(rs, (LAS unsigned*)(lds + (bufoff) + ldsw + _i * 8192), 16, (voff)[_i], (soff), 0, 0); } while (0)
; #define PG8_LDA(dst, b, h) do { _Pragma("unroll") for (int m = 0; m < 4; ++m) _Pragma("unroll") for (int k = 0; k < 2; ++k) dst[m][k] = *(const LAS bf16x8*)(lds + PG8_SA(b, h) + aoff + m * 2048 + k * 1024); } while (0)
; #define PG8_LDB(dst, b, h) do { _Pragma("unroll") for (int n = 0; n < 2; ++n) _Pragma("unroll") for (int k = 0; k < 2; ++k) dst[n][k] = *(const LAS bf16x8*)(lds + PG8_SB(b, h) + boff + n * 2048 + k * 1024); } while (0)
; #define PG8_WAIT_V(n) asm volatile("s_waitcnt vmcnt(" #n ")" ::: "memory")
; #define PG8_WAIT_L(n) asm volatile("s_waitcnt lgkmcnt(" #n ")" ::: "memory")
; #define PG8_BAR __builtin_amdgcn_s_barrier()
; #define PG8_SCHED __builtin_amdgcn_sched_barrier(0)
;     ...
;                 if (w0) { PG8_LDB(B0, 0, 0); PG8_LDB(B1, 0, 1); PG8_SCHED; PG8_LDA(At, 0, 0); }
;                 PG8_WAIT_L(0); PG8_BAR; if (w0) { PG8_MMA(0, 0, At, B0); PG8_MMA(0, 1, At, B1); } PG8_BAR; PG8_SCHED;
;                 PG8_STAGEX(rsB, PG8_SB(0, 0), b2, voffB); PG8_STAGEX(rsB, PG8_SB(0, 1), b2 + hstepB, voffB); PG8_STAGEX(rsA, PG8_SA(0, 0), a2, voffA);
;                 PG8_WAIT_V(6); PG8_BAR; PG8_BAR; PG8_SCHED;
.LBB0_542:
	v_add_u32_e32 v73, 0x10000, v71
	ds_read_b128 v[74:77], v73
	ds_read_b128 v[78:81], v73 offset:1024
	ds_read_b128 v[82:85], v73 offset:2048
	ds_read_b128 v[86:89], v73 offset:3072
	v_add_u32_e32 v73, 0x14000, v71
	ds_read_b128 v[90:93], v73
	ds_read_b128 v[94:97], v73 offset:1024
	ds_read_b128 v[98:101], v73 offset:2048
	ds_read_b128 v[110:113], v73 offset:3072
	s_cmp_lg_u32 s26, 28
	s_cselect_b32 s27, s25, 0
	s_add_i32 s28, s27, s17
	s_or_b32 s29, s28, 0x80
	s_add_i32 s27, s27, s10
	ds_read_b128 v[114:117], v72
	ds_read_b128 v[118:121], v72 offset:1024
	ds_read_b128 v[122:125], v72 offset:2048
	ds_read_b128 v[126:129], v72 offset:3072
	ds_read_b128 v[130:133], v72 offset:4096
	ds_read_b128 v[134:137], v72 offset:5120
	ds_read_b128 v[138:141], v72 offset:6144
	ds_read_b128 v[142:145], v72 offset:7168
	s_waitcnt lgkmcnt(0)
	s_barrier
	s_setprio 1
	v_mfma_f32_16x16x32_bf16 v[62:65], v[74:77], v[114:117], v[62:65]
	v_mfma_f32_16x16x32_bf16 v[46:49], v[82:85], v[114:117], v[46:49]
	v_mfma_f32_16x16x32_bf16 v[54:57], v[74:77], v[122:125], v[54:57]
	v_mfma_f32_16x16x32_bf16 v[38:41], v[82:85], v[122:125], v[38:41]
	v_mfma_f32_16x16x32_bf16 v[50:53], v[74:77], v[130:133], v[50:53]
	v_mfma_f32_16x16x32_bf16 v[34:37], v[82:85], v[130:133], v[34:37]
	v_mfma_f32_16x16x32_bf16 v[58:61], v[74:77], v[138:141], v[58:61]
	v_mfma_f32_16x16x32_bf16 v[42:45], v[82:85], v[138:141], v[42:45]
	v_mfma_f32_16x16x32_bf16 v[62:65], v[78:81], v[118:121], v[62:65]
	v_mfma_f32_16x16x32_bf16 v[46:49], v[86:89], v[118:121], v[46:49]
	v_mfma_f32_16x16x32_bf16 v[54:57], v[78:81], v[126:129], v[54:57]
	v_mfma_f32_16x16x32_bf16 v[38:41], v[86:89], v[126:129], v[38:41]
	v_mfma_f32_16x16x32_bf16 v[50:53], v[78:81], v[134:137], v[50:53]
	v_mfma_f32_16x16x32_bf16 v[34:37], v[86:89], v[134:137], v[34:37]
	v_mfma_f32_16x16x32_bf16 v[58:61], v[78:81], v[142:145], v[58:61]
	v_mfma_f32_16x16x32_bf16 v[42:45], v[86:89], v[142:145], v[42:45]
	v_mfma_f32_16x16x32_bf16 v[30:33], v[90:93], v[114:117], v[30:33]
	v_mfma_f32_16x16x32_bf16 v[14:17], v[98:101], v[114:117], v[14:17]
	v_mfma_f32_16x16x32_bf16 v[22:25], v[90:93], v[122:125], v[22:25]
	v_mfma_f32_16x16x32_bf16 v[10:13], v[98:101], v[122:125], v[10:13]
	v_mfma_f32_16x16x32_bf16 v[18:21], v[90:93], v[130:133], v[18:21]
	v_mfma_f32_16x16x32_bf16 v[2:5], v[98:101], v[130:133], v[2:5]
	v_mfma_f32_16x16x32_bf16 v[26:29], v[90:93], v[138:141], v[26:29]
	v_mfma_f32_16x16x32_bf16 v[6:9], v[98:101], v[138:141], v[6:9]
	v_mfma_f32_16x16x32_bf16 v[30:33], v[94:97], v[118:121], v[30:33]
	v_mfma_f32_16x16x32_bf16 v[14:17], v[110:113], v[118:121], v[14:17]
	v_mfma_f32_16x16x32_bf16 v[22:25], v[94:97], v[126:129], v[22:25]
	v_mfma_f32_16x16x32_bf16 v[10:13], v[110:113], v[126:129], v[10:13]
	v_mfma_f32_16x16x32_bf16 v[18:21], v[94:97], v[134:137], v[18:21]
	v_mfma_f32_16x16x32_bf16 v[2:5], v[110:113], v[134:137], v[2:5]
	v_mfma_f32_16x16x32_bf16 v[26:29], v[94:97], v[142:145], v[26:29]
	v_mfma_f32_16x16x32_bf16 v[6:9], v[110:113], v[142:145], v[6:9]
	s_setprio 0
	s_barrier
	s_mov_b32 m0, s12
	s_mov_b32 s58, s78
	s_mov_b32 s59, s79
	buffer_load_dwordx4 v67, s[56:59], s27 offen lds
	s_mov_b32 m0, s13
	s_add_i32 s30, s27, 0x80000
	buffer_load_dwordx4 v69, s[56:59], s27 offen lds
	s_mov_b32 m0, s14
	s_nop 0
	buffer_load_dwordx4 v67, s[56:59], s30 offen lds
	s_mov_b32 m0, s15
	s_nop 0
	buffer_load_dwordx4 v69, s[56:59], s30 offen lds
	s_mov_b32 m0, s11
	s_nop 0
	buffer_load_dwordx4 v66, s[76:79], s28 offen lds
	s_mov_b32 m0, s18
	s_nop 0
	buffer_load_dwordx4 v68, s[76:79], s28 offen lds
	s_waitcnt vmcnt(6)
	s_barrier
	s_barrier
; #define PG8_STAGEX(rs, bufoff, soff, voff) do { _Pragma("unroll") for (int _i = 0; _i < 2; ++_i) \
;         __builtin_amdgcn_raw_ptr_buffer_load_lds(rs, (LAS unsigned*)(lds + (bufoff) + ldsw + _i * 8192), 16, (voff)[_i], (soff), 0, 0); } while (0)
; #define PG8_LDA(dst, b, h) do { _Pragma("unroll") for (int m = 0; m < 4; ++m) _Pragma("unroll") for (int k = 0; k < 2; ++k) dst[m][k] = *(const LAS bf16x8*)(lds + PG8_SA(b, h) + aoff + m * 2048 + k * 1024); } while (0)
; #define PG8_LDB(dst, b, h) do { _Pragma("unroll") for (int n = 0; n < 2; ++n) _Pragma("unroll") for (int k = 0; k < 2; ++k) dst[n][k] = *(const LAS bf16x8*)(lds + PG8_SB(b, h) + boff + n * 2048 + k * 1024); } while (0)
; #define PG8_WAIT_V(n) asm volatile("s_waitcnt vmcnt(" #n ")" ::: "memory")
; #define PG8_WAIT_L(n) asm volatile("s_waitcnt lgkmcnt(" #n ")" ::: "memory")
; #define PG8_BAR __builtin_amdgcn_s_barrier()
; #define PG8_SCHED __builtin_amdgcn_sched_barrier(0)
;     ...
;                 if (w0) { PG8_LDB(B0, 1, 0); PG8_LDB(B1, 1, 1); PG8_SCHED; PG8_LDA(At, 1, 0); }
;                 PG8_WAIT_L(0); PG8_BAR; if (w0) { PG8_MMA(0, 0, At, B0); PG8_MMA(0, 1, At, B1); } PG8_BAR; PG8_SCHED;
;                 PG8_STAGEX(rsB, PG8_SB(1, 0), b3, voffB); PG8_STAGEX(rsB, PG8_SB(1, 1), b3 + hstepB, voffB); PG8_STAGEX(rsA, PG8_SA(1, 0), a3, voffA);
;                 PG8_WAIT_V(6); PG8_BAR; PG8_BAR; PG8_SCHED;
;             }
	v_add_u32_e32 v73, 0x18000, v71
	ds_read_b128 v[74:77], v73
	ds_read_b128 v[78:81], v73 offset:1024
	ds_read_b128 v[82:85], v73 offset:2048
	ds_read_b128 v[86:89], v73 offset:3072
	v_add_u32_e32 v73, 0x1c000, v71
	ds_read_b128 v[90:93], v73
	ds_read_b128 v[94:97], v73 offset:1024
	ds_read_b128 v[98:101], v73 offset:2048
	ds_read_b128 v[110:113], v73 offset:3072
	ds_read_b128 v[114:117], v72 offset:32768
	ds_read_b128 v[118:121], v72 offset:33792
	ds_read_b128 v[122:125], v72 offset:34816
	ds_read_b128 v[126:129], v72 offset:35840
	ds_read_b128 v[130:133], v72 offset:36864
	ds_read_b128 v[134:137], v72 offset:37888
	ds_read_b128 v[138:141], v72 offset:38912
	ds_read_b128 v[142:145], v72 offset:39936
	s_waitcnt lgkmcnt(0)
	s_barrier
	s_setprio 1
	v_mfma_f32_16x16x32_bf16 v[62:65], v[74:77], v[114:117], v[62:65]
	v_mfma_f32_16x16x32_bf16 v[46:49], v[82:85], v[114:117], v[46:49]
	v_mfma_f32_16x16x32_bf16 v[54:57], v[74:77], v[122:125], v[54:57]
	v_mfma_f32_16x16x32_bf16 v[38:41], v[82:85], v[122:125], v[38:41]
	v_mfma_f32_16x16x32_bf16 v[50:53], v[74:77], v[130:133], v[50:53]
	v_mfma_f32_16x16x32_bf16 v[34:37], v[82:85], v[130:133], v[34:37]
	v_mfma_f32_16x16x32_bf16 v[58:61], v[74:77], v[138:141], v[58:61]
	v_mfma_f32_16x16x32_bf16 v[42:45], v[82:85], v[138:141], v[42:45]
	v_mfma_f32_16x16x32_bf16 v[62:65], v[78:81], v[118:121], v[62:65]
	v_mfma_f32_16x16x32_bf16 v[46:49], v[86:89], v[118:121], v[46:49]
	v_mfma_f32_16x16x32_bf16 v[54:57], v[78:81], v[126:129], v[54:57]
	v_mfma_f32_16x16x32_bf16 v[38:41], v[86:89], v[126:129], v[38:41]
	v_mfma_f32_16x16x32_bf16 v[50:53], v[78:81], v[134:137], v[50:53]
	v_mfma_f32_16x16x32_bf16 v[34:37], v[86:89], v[134:137], v[34:37]
	v_mfma_f32_16x16x32_bf16 v[58:61], v[78:81], v[142:145], v[58:61]
	v_mfma_f32_16x16x32_bf16 v[42:45], v[86:89], v[142:145], v[42:45]
	v_mfma_f32_16x16x32_bf16 v[30:33], v[90:93], v[114:117], v[30:33]
	s_or_b32 s28, s27, 0x80
	v_mfma_f32_16x16x32_bf16 v[14:17], v[98:101], v[114:117], v[14:17]
	v_mfma_f32_16x16x32_bf16 v[22:25], v[90:93], v[122:125], v[22:25]
	v_mfma_f32_16x16x32_bf16 v[10:13], v[98:101], v[122:125], v[10:13]
	v_mfma_f32_16x16x32_bf16 v[18:21], v[90:93], v[130:133], v[18:21]
	v_mfma_f32_16x16x32_bf16 v[2:5], v[98:101], v[130:133], v[2:5]
	v_mfma_f32_16x16x32_bf16 v[26:29], v[90:93], v[138:141], v[26:29]
	v_mfma_f32_16x16x32_bf16 v[6:9], v[98:101], v[138:141], v[6:9]
	v_mfma_f32_16x16x32_bf16 v[30:33], v[94:97], v[118:121], v[30:33]
	v_mfma_f32_16x16x32_bf16 v[14:17], v[110:113], v[118:121], v[14:17]
	v_mfma_f32_16x16x32_bf16 v[22:25], v[94:97], v[126:129], v[22:25]
	v_mfma_f32_16x16x32_bf16 v[10:13], v[110:113], v[126:129], v[10:13]
	v_mfma_f32_16x16x32_bf16 v[18:21], v[94:97], v[134:137], v[18:21]
	v_mfma_f32_16x16x32_bf16 v[2:5], v[110:113], v[134:137], v[2:5]
	v_mfma_f32_16x16x32_bf16 v[26:29], v[94:97], v[142:145], v[26:29]
	v_mfma_f32_16x16x32_bf16 v[6:9], v[110:113], v[142:145], v[6:9]
	s_setprio 0
	s_barrier
	s_mov_b32 m0, s19
	s_add_i32 s27, s27, 0x80080
	buffer_load_dwordx4 v67, s[56:59], s28 offen lds
	s_mov_b32 m0, s20
	s_nop 0
	buffer_load_dwordx4 v69, s[56:59], s28 offen lds
	s_mov_b32 m0, s23
	s_nop 0
	buffer_load_dwordx4 v67, s[56:59], s27 offen lds
	s_mov_b32 m0, s24
	s_nop 0
	buffer_load_dwordx4 v69, s[56:59], s27 offen lds
	s_mov_b32 m0, s21
	s_nop 0
	buffer_load_dwordx4 v66, s[76:79], s29 offen lds
	s_mov_b32 m0, s22
	s_nop 0
	buffer_load_dwordx4 v68, s[76:79], s29 offen lds
	s_waitcnt vmcnt(6)
	s_barrier
	s_barrier
	s_addk_i32 s25, 0x100
	s_add_i32 s26, s26, 2
	s_cmp_gt_u32 s26, 29
	s_cbranch_scc0 .LBB0_542
	s_cmpk_lt_u32 s1, 0x100
	s_cbranch_scc0 .LBB0_545
	s_barrier

; #define PG8_STAGEX(rs, bufoff, soff, voff) do { _Pragma("unroll") for (int _i = 0; _i < 2; ++_i) \
;         __builtin_amdgcn_raw_ptr_buffer_load_lds(rs, (LAS unsigned*)(lds + (bufoff) + ldsw + _i * 8192), 16, (voff)[_i], (soff), 0, 0); } while (0)
; #define PG8_LDA(dst, b, h) do { _Pragma("unroll") for (int m = 0; m < 4; ++m) _Pragma("unroll") for (int k = 0; k < 2; ++k) dst[m][k] = *(const LAS bf16x8*)(lds + PG8_SA(b, h) + aoff + m * 2048 + k * 1024); } while (0)
; #define PG8_LDB(dst, b, h) do { _Pragma("unroll") for (int n = 0; n < 2; ++n) _Pragma("unroll") for (int k = 0; k < 2; ++k) dst[n][k] = *(const LAS bf16x8*)(lds + PG8_SB(b, h) + boff + n * 2048 + k * 1024); } while (0)
; #define PG8_WAIT_V(n) asm volatile("s_waitcnt vmcnt(" #n ")" ::: "memory")
; #define PG8_WAIT_L(n) asm volatile("s_waitcnt lgkmcnt(" #n ")" ::: "memory")
; #define PG8_BAR __builtin_amdgcn_s_barrier()
; #define PG8_SCHED __builtin_amdgcn_sched_barrier(0)
;     ...
;             PG8_LDB(B0, 0, 0); PG8_LDB(B1, 0, 1); PG8_SCHED; PG8_LDA(At, 0, 0); PG8_STAGEX(rsA, PG8_SA(1, 1), a1 + hstepA, voffA);
;             PG8_WAIT_V(8); PG8_WAIT_L(0); PG8_BAR; PG8_MMA(0, 0, At, B0); PG8_MMA(0, 1, At, B1); PG8_BAR; PG8_SCHED;
;             PG8_LDA(At, 0, 1); PG8_STAGEX(rsB, PG8_SB(0, 0), b2, voffB); PG8_STAGEX(rsB, PG8_SB(0, 1), b2 + hstepB, voffB); PG8_STAGEX(rsA, PG8_SA(0, 0), a2, voffA);
;             PG8_WAIT_V(8); PG8_WAIT_L(0); PG8_BAR; PG8_MMA(1, 0, At, B0); PG8_MMA(1, 1, At, B1); PG8_BAR; PG8_SCHED;
.LBB0_788:
	v_add_u32_e32 v150, 0x10000, v153
	ds_read_b128 v[138:141], v150
	ds_read_b128 v[142:145], v150 offset:1024
	ds_read_b128 v[146:149], v150 offset:2048
	ds_read_b128 v[156:159], v150 offset:3072
	v_add_u32_e32 v150, 0x14000, v153
	ds_read_b128 v[160:163], v150
	ds_read_b128 v[164:167], v150 offset:1024
	ds_read_b128 v[182:185], v150 offset:2048
	ds_read_b128 v[186:189], v150 offset:3072
	s_add_i32 s48, s31, 0xfffc0080
	s_cmp_eq_u32 s55, s47
	s_cselect_b32 s50, s7, s48
	s_cselect_b32 s49, s30, s46
	s_add_i32 s48, s50, 0x80
	s_mov_b32 m0, s35
	ds_read_b128 v[190:193], v154
	ds_read_b128 v[194:197], v154 offset:1024
	ds_read_b128 v[198:201], v154 offset:2048
	ds_read_b128 v[202:205], v154 offset:3072
	ds_read_b128 v[206:209], v154 offset:4096
	ds_read_b128 v[210:213], v154 offset:5120
	ds_read_b128 v[214:217], v154 offset:6144
	ds_read_b128 v[218:221], v154 offset:7168
	buffer_load_dwordx4 v130, s[76:79], s31 offen lds
	s_mov_b32 m0, s82
	s_nop 0
	buffer_load_dwordx4 v134, s[76:79], s31 offen lds
	s_waitcnt vmcnt(8)
	s_waitcnt lgkmcnt(0)
	s_barrier
	s_setprio 1
	v_mfma_f32_16x16x32_bf16 v[126:129], v[190:193], v[138:141], v[126:129]
	v_mfma_f32_16x16x32_bf16 v[62:65], v[190:193], v[146:149], v[62:65]
	v_mfma_f32_16x16x32_bf16 v[118:121], v[198:201], v[138:141], v[118:121]
	v_mfma_f32_16x16x32_bf16 v[54:57], v[198:201], v[146:149], v[54:57]
	v_mfma_f32_16x16x32_bf16 v[110:113], v[206:209], v[138:141], v[110:113]
	v_mfma_f32_16x16x32_bf16 v[46:49], v[206:209], v[146:149], v[46:49]
	v_mfma_f32_16x16x32_bf16 v[102:105], v[214:217], v[138:141], v[102:105]
	v_mfma_f32_16x16x32_bf16 v[38:41], v[214:217], v[146:149], v[38:41]
	v_mfma_f32_16x16x32_bf16 v[126:129], v[194:197], v[142:145], v[126:129]
	v_mfma_f32_16x16x32_bf16 v[62:65], v[194:197], v[156:159], v[62:65]
	v_mfma_f32_16x16x32_bf16 v[118:121], v[202:205], v[142:145], v[118:121]
	v_mfma_f32_16x16x32_bf16 v[54:57], v[202:205], v[156:159], v[54:57]
	v_mfma_f32_16x16x32_bf16 v[110:113], v[210:213], v[142:145], v[110:113]
	v_mfma_f32_16x16x32_bf16 v[46:49], v[210:213], v[156:159], v[46:49]
	v_mfma_f32_16x16x32_bf16 v[102:105], v[218:221], v[142:145], v[102:105]
	v_mfma_f32_16x16x32_bf16 v[38:41], v[218:221], v[156:159], v[38:41]
	v_mfma_f32_16x16x32_bf16 v[122:125], v[190:193], v[160:163], v[122:125]
	v_mfma_f32_16x16x32_bf16 v[58:61], v[190:193], v[182:185], v[58:61]
	v_mfma_f32_16x16x32_bf16 v[114:117], v[198:201], v[160:163], v[114:117]
	v_mfma_f32_16x16x32_bf16 v[50:53], v[198:201], v[182:185], v[50:53]
	v_mfma_f32_16x16x32_bf16 v[106:109], v[206:209], v[160:163], v[106:109]
	v_mfma_f32_16x16x32_bf16 v[42:45], v[206:209], v[182:185], v[42:45]
	v_mfma_f32_16x16x32_bf16 v[98:101], v[214:217], v[160:163], v[98:101]
	v_mfma_f32_16x16x32_bf16 v[34:37], v[214:217], v[182:185], v[34:37]
	v_mfma_f32_16x16x32_bf16 v[122:125], v[194:197], v[164:167], v[122:125]
	v_mfma_f32_16x16x32_bf16 v[58:61], v[194:197], v[186:189], v[58:61]
	v_mfma_f32_16x16x32_bf16 v[114:117], v[202:205], v[164:167], v[114:117]
	v_mfma_f32_16x16x32_bf16 v[50:53], v[202:205], v[186:189], v[50:53]
	v_mfma_f32_16x16x32_bf16 v[106:109], v[210:213], v[164:167], v[106:109]
	v_mfma_f32_16x16x32_bf16 v[42:45], v[210:213], v[186:189], v[42:45]
	v_mfma_f32_16x16x32_bf16 v[98:101], v[218:221], v[164:167], v[98:101]
	v_mfma_f32_16x16x32_bf16 v[34:37], v[218:221], v[186:189], v[34:37]
	s_setprio 0
	s_barrier
	s_mov_b32 m0, s15
	s_mov_b32 s86, s78
	s_mov_b32 s87, s79
	ds_read_b128 v[190:193], v154 offset:16384
	ds_read_b128 v[194:197], v154 offset:17408
	ds_read_b128 v[198:201], v154 offset:18432
	ds_read_b128 v[202:205], v154 offset:19456
	ds_read_b128 v[206:209], v154 offset:20480
	ds_read_b128 v[210:213], v154 offset:21504
	ds_read_b128 v[214:217], v154 offset:22528
	ds_read_b128 v[218:221], v154 offset:23552
	buffer_load_dwordx4 v132, s[84:87], s49 offen lds
	s_mov_b32 m0, s16
	s_add_i32 s51, s49, 0x8000
	buffer_load_dwordx4 v136, s[84:87], s49 offen lds
	s_mov_b32 m0, s17
	s_nop 0
	buffer_load_dwordx4 v132, s[84:87], s51 offen lds
	s_mov_b32 m0, s18
	s_nop 0
	buffer_load_dwordx4 v136, s[84:87], s51 offen lds
	s_mov_b32 m0, s14
	s_nop 0
	buffer_load_dwordx4 v130, s[76:79], s50 offen lds
	s_mov_b32 m0, s19
	s_nop 0
	buffer_load_dwordx4 v134, s[76:79], s50 offen lds
	s_waitcnt vmcnt(8)
	s_waitcnt lgkmcnt(0)
	s_barrier
	s_setprio 1
	v_mfma_f32_16x16x32_bf16 v[94:97], v[190:193], v[138:141], v[94:97]
	v_mfma_f32_16x16x32_bf16 v[30:33], v[190:193], v[146:149], v[30:33]
	v_mfma_f32_16x16x32_bf16 v[86:89], v[198:201], v[138:141], v[86:89]
	v_mfma_f32_16x16x32_bf16 v[22:25], v[198:201], v[146:149], v[22:25]
	v_mfma_f32_16x16x32_bf16 v[78:81], v[206:209], v[138:141], v[78:81]
	v_mfma_f32_16x16x32_bf16 v[14:17], v[206:209], v[146:149], v[14:17]
	v_mfma_f32_16x16x32_bf16 v[70:73], v[214:217], v[138:141], v[70:73]
	v_mfma_f32_16x16x32_bf16 v[6:9], v[214:217], v[146:149], v[6:9]
	v_mfma_f32_16x16x32_bf16 v[94:97], v[194:197], v[142:145], v[94:97]
	v_mfma_f32_16x16x32_bf16 v[30:33], v[194:197], v[156:159], v[30:33]
	v_mfma_f32_16x16x32_bf16 v[86:89], v[202:205], v[142:145], v[86:89]
	v_mfma_f32_16x16x32_bf16 v[22:25], v[202:205], v[156:159], v[22:25]
	v_mfma_f32_16x16x32_bf16 v[78:81], v[210:213], v[142:145], v[78:81]
	v_mfma_f32_16x16x32_bf16 v[14:17], v[210:213], v[156:159], v[14:17]
	v_mfma_f32_16x16x32_bf16 v[70:73], v[218:221], v[142:145], v[70:73]
	v_mfma_f32_16x16x32_bf16 v[6:9], v[218:221], v[156:159], v[6:9]
	v_mfma_f32_16x16x32_bf16 v[90:93], v[190:193], v[160:163], v[90:93]
	v_mfma_f32_16x16x32_bf16 v[26:29], v[190:193], v[182:185], v[26:29]
	v_mfma_f32_16x16x32_bf16 v[82:85], v[198:201], v[160:163], v[82:85]
	v_mfma_f32_16x16x32_bf16 v[18:21], v[198:201], v[182:185], v[18:21]
	v_mfma_f32_16x16x32_bf16 v[74:77], v[206:209], v[160:163], v[74:77]
	v_mfma_f32_16x16x32_bf16 v[10:13], v[206:209], v[182:185], v[10:13]
	v_mfma_f32_16x16x32_bf16 v[66:69], v[214:217], v[160:163], v[66:69]
	v_mfma_f32_16x16x32_bf16 v[2:5], v[214:217], v[182:185], v[2:5]
	v_mfma_f32_16x16x32_bf16 v[90:93], v[194:197], v[164:167], v[90:93]
	v_mfma_f32_16x16x32_bf16 v[26:29], v[194:197], v[186:189], v[26:29]
	v_mfma_f32_16x16x32_bf16 v[82:85], v[202:205], v[164:167], v[82:85]
	v_mfma_f32_16x16x32_bf16 v[18:21], v[202:205], v[186:189], v[18:21]
	v_mfma_f32_16x16x32_bf16 v[74:77], v[210:213], v[164:167], v[74:77]
	v_mfma_f32_16x16x32_bf16 v[10:13], v[210:213], v[186:189], v[10:13]
	v_mfma_f32_16x16x32_bf16 v[66:69], v[218:221], v[164:167], v[66:69]
	v_mfma_f32_16x16x32_bf16 v[2:5], v[218:221], v[186:189], v[2:5]
	s_setprio 0
	s_barrier
; #define PG8_STAGEX(rs, bufoff, soff, voff) do { _Pragma("unroll") for (int _i = 0; _i < 2; ++_i) \
;         __builtin_amdgcn_raw_ptr_buffer_load_lds(rs, (LAS unsigned*)(lds + (bufoff) + ldsw + _i * 8192), 16, (voff)[_i], (soff), 0, 0); } while (0)
; #define PG8_LDA(dst, b, h) do { _Pragma("unroll") for (int m = 0; m < 4; ++m) _Pragma("unroll") for (int k = 0; k < 2; ++k) dst[m][k] = *(const LAS bf16x8*)(lds + PG8_SA(b, h) + aoff + m * 2048 + k * 1024); } while (0)
; #define PG8_LDB(dst, b, h) do { _Pragma("unroll") for (int n = 0; n < 2; ++n) _Pragma("unroll") for (int k = 0; k < 2; ++k) dst[n][k] = *(const LAS bf16x8*)(lds + PG8_SB(b, h) + boff + n * 2048 + k * 1024); } while (0)
; #define PG8_WAIT_V(n) asm volatile("s_waitcnt vmcnt(" #n ")" ::: "memory")
; #define PG8_WAIT_L(n) asm volatile("s_waitcnt lgkmcnt(" #n ")" ::: "memory")
; #define PG8_BAR __builtin_amdgcn_s_barrier()
; #define PG8_SCHED __builtin_amdgcn_sched_barrier(0)
;     ...
;             PG8_LDB(B0, 1, 0); PG8_LDB(B1, 1, 1); PG8_SCHED; PG8_LDA(At, 1, 0); PG8_STAGEX(rsA, PG8_SA(0, 1), a2 + hstepA, voffA);
;             PG8_WAIT_V(8); PG8_WAIT_L(0); PG8_BAR; PG8_MMA(0, 0, At, B0); PG8_MMA(0, 1, At, B1); PG8_BAR; PG8_SCHED;
;             PG8_LDA(At, 1, 1); PG8_STAGEX(rsB, PG8_SB(1, 0), b3, voffB); PG8_STAGEX(rsB, PG8_SB(1, 1), b3 + hstepB, voffB); PG8_STAGEX(rsA, PG8_SA(1, 0), a3, voffA);
;             PG8_WAIT_V(8); PG8_WAIT_L(0); PG8_BAR; PG8_MMA(1, 0, At, B0); PG8_MMA(1, 1, At, B1); PG8_BAR; PG8_SCHED;
;         }
	v_add_u32_e32 v150, 0x18000, v153
	ds_read_b128 v[138:141], v150
	ds_read_b128 v[142:145], v150 offset:1024
	ds_read_b128 v[146:149], v150 offset:2048
	ds_read_b128 v[156:159], v150 offset:3072
	v_add_u32_e32 v150, 0x1c000, v153
	ds_read_b128 v[160:163], v150
	ds_read_b128 v[164:167], v150 offset:1024
	ds_read_b128 v[182:185], v150 offset:2048
	ds_read_b128 v[186:189], v150 offset:3072
	s_add_i32 s50, s50, 0x40000
	s_mov_b32 m0, s20
	ds_read_b128 v[190:193], v154 offset:32768
	ds_read_b128 v[194:197], v154 offset:33792
	ds_read_b128 v[198:201], v154 offset:34816
	ds_read_b128 v[202:205], v154 offset:35840
	ds_read_b128 v[206:209], v154 offset:36864
	ds_read_b128 v[210:213], v154 offset:37888
	ds_read_b128 v[214:217], v154 offset:38912
	ds_read_b128 v[218:221], v154 offset:39936
	buffer_load_dwordx4 v130, s[76:79], s50 offen lds
	s_mov_b32 m0, s21
	s_nop 0
	buffer_load_dwordx4 v134, s[76:79], s50 offen lds
	s_waitcnt vmcnt(8)
	s_waitcnt lgkmcnt(0)
	s_barrier
	s_setprio 1
	v_mfma_f32_16x16x32_bf16 v[126:129], v[190:193], v[138:141], v[126:129]
	v_mfma_f32_16x16x32_bf16 v[62:65], v[190:193], v[146:149], v[62:65]
	v_mfma_f32_16x16x32_bf16 v[118:121], v[198:201], v[138:141], v[118:121]
	v_mfma_f32_16x16x32_bf16 v[54:57], v[198:201], v[146:149], v[54:57]
	v_mfma_f32_16x16x32_bf16 v[110:113], v[206:209], v[138:141], v[110:113]
	v_mfma_f32_16x16x32_bf16 v[46:49], v[206:209], v[146:149], v[46:49]
	v_mfma_f32_16x16x32_bf16 v[102:105], v[214:217], v[138:141], v[102:105]
	v_mfma_f32_16x16x32_bf16 v[38:41], v[214:217], v[146:149], v[38:41]
	v_mfma_f32_16x16x32_bf16 v[126:129], v[194:197], v[142:145], v[126:129]
	v_mfma_f32_16x16x32_bf16 v[62:65], v[194:197], v[156:159], v[62:65]
	v_mfma_f32_16x16x32_bf16 v[118:121], v[202:205], v[142:145], v[118:121]
	v_mfma_f32_16x16x32_bf16 v[54:57], v[202:205], v[156:159], v[54:57]
	v_mfma_f32_16x16x32_bf16 v[110:113], v[210:213], v[142:145], v[110:113]
	v_mfma_f32_16x16x32_bf16 v[46:49], v[210:213], v[156:159], v[46:49]
	v_mfma_f32_16x16x32_bf16 v[102:105], v[218:221], v[142:145], v[102:105]
	v_mfma_f32_16x16x32_bf16 v[38:41], v[218:221], v[156:159], v[38:41]
	v_mfma_f32_16x16x32_bf16 v[122:125], v[190:193], v[160:163], v[122:125]
	v_mfma_f32_16x16x32_bf16 v[58:61], v[190:193], v[182:185], v[58:61]
	v_mfma_f32_16x16x32_bf16 v[114:117], v[198:201], v[160:163], v[114:117]
	v_mfma_f32_16x16x32_bf16 v[50:53], v[198:201], v[182:185], v[50:53]
	v_mfma_f32_16x16x32_bf16 v[106:109], v[206:209], v[160:163], v[106:109]
	v_mfma_f32_16x16x32_bf16 v[42:45], v[206:209], v[182:185], v[42:45]
	v_mfma_f32_16x16x32_bf16 v[98:101], v[214:217], v[160:163], v[98:101]
	v_mfma_f32_16x16x32_bf16 v[34:37], v[214:217], v[182:185], v[34:37]
	v_mfma_f32_16x16x32_bf16 v[122:125], v[194:197], v[164:167], v[122:125]
	v_mfma_f32_16x16x32_bf16 v[58:61], v[194:197], v[186:189], v[58:61]
	v_mfma_f32_16x16x32_bf16 v[114:117], v[202:205], v[164:167], v[114:117]
	v_mfma_f32_16x16x32_bf16 v[50:53], v[202:205], v[186:189], v[50:53]
	v_mfma_f32_16x16x32_bf16 v[106:109], v[210:213], v[164:167], v[106:109]
	v_mfma_f32_16x16x32_bf16 v[42:45], v[210:213], v[186:189], v[42:45]
	v_mfma_f32_16x16x32_bf16 v[98:101], v[218:221], v[164:167], v[98:101]
	v_mfma_f32_16x16x32_bf16 v[34:37], v[218:221], v[186:189], v[34:37]
	s_setprio 0
	s_barrier
	s_mov_b32 m0, s93
	s_or_b32 s50, s49, 0x80
	ds_read_b128 v[190:193], v154 offset:49152
	ds_read_b128 v[194:197], v154 offset:50176
	ds_read_b128 v[198:201], v154 offset:51200
	ds_read_b128 v[202:205], v154 offset:52224
	ds_read_b128 v[206:209], v154 offset:53248
	ds_read_b128 v[210:213], v154 offset:54272
	ds_read_b128 v[214:217], v154 offset:55296
	ds_read_b128 v[218:221], v154 offset:56320
	buffer_load_dwordx4 v132, s[84:87], s50 offen lds
	s_mov_b32 m0, s94
	s_add_i32 s49, s49, 0x8080
	buffer_load_dwordx4 v136, s[84:87], s50 offen lds
	s_mov_b32 m0, s9
	s_nop 0
	buffer_load_dwordx4 v132, s[84:87], s49 offen lds
	s_mov_b32 m0, s54
	s_nop 0
	buffer_load_dwordx4 v136, s[84:87], s49 offen lds
	s_mov_b32 m0, s95
	s_nop 0
	buffer_load_dwordx4 v130, s[76:79], s48 offen lds
	s_mov_b32 m0, s97
	s_nop 0
	buffer_load_dwordx4 v134, s[76:79], s48 offen lds
	s_waitcnt vmcnt(8)
	s_waitcnt lgkmcnt(0)
	s_barrier
	s_setprio 1
	v_mfma_f32_16x16x32_bf16 v[94:97], v[190:193], v[138:141], v[94:97]
	v_mfma_f32_16x16x32_bf16 v[30:33], v[190:193], v[146:149], v[30:33]
	v_mfma_f32_16x16x32_bf16 v[86:89], v[198:201], v[138:141], v[86:89]
	v_mfma_f32_16x16x32_bf16 v[22:25], v[198:201], v[146:149], v[22:25]
	v_mfma_f32_16x16x32_bf16 v[78:81], v[206:209], v[138:141], v[78:81]
	v_mfma_f32_16x16x32_bf16 v[14:17], v[206:209], v[146:149], v[14:17]
	v_mfma_f32_16x16x32_bf16 v[70:73], v[214:217], v[138:141], v[70:73]
	v_mfma_f32_16x16x32_bf16 v[6:9], v[214:217], v[146:149], v[6:9]
	v_mfma_f32_16x16x32_bf16 v[94:97], v[194:197], v[142:145], v[94:97]
	v_mfma_f32_16x16x32_bf16 v[30:33], v[194:197], v[156:159], v[30:33]
	v_mfma_f32_16x16x32_bf16 v[86:89], v[202:205], v[142:145], v[86:89]
	v_mfma_f32_16x16x32_bf16 v[22:25], v[202:205], v[156:159], v[22:25]
	v_mfma_f32_16x16x32_bf16 v[78:81], v[210:213], v[142:145], v[78:81]
	v_mfma_f32_16x16x32_bf16 v[14:17], v[210:213], v[156:159], v[14:17]
	v_mfma_f32_16x16x32_bf16 v[70:73], v[218:221], v[142:145], v[70:73]
	v_mfma_f32_16x16x32_bf16 v[6:9], v[218:221], v[156:159], v[6:9]
	v_mfma_f32_16x16x32_bf16 v[90:93], v[190:193], v[160:163], v[90:93]
	v_mfma_f32_16x16x32_bf16 v[26:29], v[190:193], v[182:185], v[26:29]
	v_mfma_f32_16x16x32_bf16 v[82:85], v[198:201], v[160:163], v[82:85]
	v_mfma_f32_16x16x32_bf16 v[18:21], v[198:201], v[182:185], v[18:21]
	v_mfma_f32_16x16x32_bf16 v[74:77], v[206:209], v[160:163], v[74:77]
	v_mfma_f32_16x16x32_bf16 v[10:13], v[206:209], v[182:185], v[10:13]
	v_mfma_f32_16x16x32_bf16 v[66:69], v[214:217], v[160:163], v[66:69]
	v_mfma_f32_16x16x32_bf16 v[2:5], v[214:217], v[182:185], v[2:5]
	v_mfma_f32_16x16x32_bf16 v[90:93], v[194:197], v[164:167], v[90:93]
	v_mfma_f32_16x16x32_bf16 v[26:29], v[194:197], v[186:189], v[26:29]
	v_mfma_f32_16x16x32_bf16 v[82:85], v[202:205], v[164:167], v[82:85]
	v_mfma_f32_16x16x32_bf16 v[18:21], v[202:205], v[186:189], v[18:21]
	v_mfma_f32_16x16x32_bf16 v[74:77], v[210:213], v[164:167], v[74:77]
	v_mfma_f32_16x16x32_bf16 v[10:13], v[210:213], v[186:189], v[10:13]
	v_mfma_f32_16x16x32_bf16 v[66:69], v[218:221], v[164:167], v[66:69]
	v_mfma_f32_16x16x32_bf16 v[2:5], v[218:221], v[186:189], v[2:5]
	s_setprio 0
	s_barrier
	s_add_i32 s47, s47, 2
	s_addk_i32 s31, 0x100
	s_addk_i32 s46, 0x100
	s_cmp_ge_i32 s47, s34
	s_cbranch_scc0 .LBB0_788
	s_mov_b32 s61, s96
	s_and_b64 vcc, exec, s[62:63]
	s_cbranch_vccz .LBB0_791

; #define PG8_STAGEX(rs, bufoff, soff, voff) do { _Pragma("unroll") for (int _i = 0; _i < 2; ++_i) \
;         __builtin_amdgcn_raw_ptr_buffer_load_lds(rs, (LAS unsigned*)(lds + (bufoff) + ldsw + _i * 8192), 16, (voff)[_i], (soff), 0, 0); } while (0)
; #define PG8_LDA(dst, b, h) do { _Pragma("unroll") for (int m = 0; m < 4; ++m) _Pragma("unroll") for (int k = 0; k < 2; ++k) dst[m][k] = *(const LAS bf16x8*)(lds + PG8_SA(b, h) + aoff + m * 2048 + k * 1024); } while (0)
; #define PG8_LDB(dst, b, h) do { _Pragma("unroll") for (int n = 0; n < 2; ++n) _Pragma("unroll") for (int k = 0; k < 2; ++k) dst[n][k] = *(const LAS bf16x8*)(lds + PG8_SB(b, h) + boff + n * 2048 + k * 1024); } while (0)
; #define PG8_WAIT_V(n) asm volatile("s_waitcnt vmcnt(" #n ")" ::: "memory")
; #define PG8_WAIT_L(n) asm volatile("s_waitcnt lgkmcnt(" #n ")" ::: "memory")
; #define PG8_BAR __builtin_amdgcn_s_barrier()
; #define PG8_SCHED __builtin_amdgcn_sched_barrier(0)
;     ...
;             PG8_LDB(B0, 0, 0); PG8_LDB(B1, 0, 1); PG8_SCHED; PG8_LDA(At, 0, 0); PG8_STAGEX(rsA, PG8_SA(1, 1), a1 + hstepA, voffA);
;             PG8_WAIT_V(8); PG8_WAIT_L(0); PG8_BAR; PG8_MMA(0, 0, At, B0); PG8_MMA(0, 1, At, B1); PG8_BAR; PG8_SCHED;
;             PG8_LDA(At, 0, 1); PG8_STAGEX(rsB, PG8_SB(0, 0), b2, voffB); PG8_STAGEX(rsB, PG8_SB(0, 1), b2 + hstepB, voffB); PG8_STAGEX(rsA, PG8_SA(0, 0), a2, voffA);
;             PG8_WAIT_V(8); PG8_WAIT_L(0); PG8_BAR; PG8_MMA(1, 0, At, B0); PG8_MMA(1, 1, At, B1); PG8_BAR; PG8_SCHED;
.LBB0_1274:
	v_add_u32_e32 v142, 0x10000, v157
	v_add_u32_e32 v159, 0x14000, v157
	ds_read_b128 v[130:133], v142
	ds_read_b128 v[134:137], v142 offset:1024
	ds_read_b128 v[138:141], v142 offset:2048
	ds_read_b128 v[142:145], v142 offset:3072
	ds_read_b128 v[146:149], v159
	ds_read_b128 v[164:167], v159 offset:1024
	ds_read_b128 v[168:171], v159 offset:2048
	ds_read_b128 v[182:185], v159 offset:3072
	s_add_i32 s42, s62, 0xfff80080
	s_cmp_eq_u32 s67, 28
	s_cselect_b32 s70, s30, s42
	s_cselect_b32 s69, s31, s63
	s_or_b32 s68, s70, 0x80
	s_mov_b32 m0, s29
	ds_read_b128 v[186:189], v158
	ds_read_b128 v[190:193], v158 offset:1024
	ds_read_b128 v[194:197], v158 offset:2048
	ds_read_b128 v[198:201], v158 offset:3072
	ds_read_b128 v[202:205], v158 offset:4096
	ds_read_b128 v[206:209], v158 offset:5120
	ds_read_b128 v[210:213], v158 offset:6144
	ds_read_b128 v[214:217], v158 offset:7168
	buffer_load_dwordx4 v150, s[76:79], s62 offen lds
	s_mov_b32 m0, s35
	s_nop 0
	buffer_load_dwordx4 v152, s[76:79], s62 offen lds
	s_waitcnt vmcnt(8)
	s_waitcnt lgkmcnt(0)
	s_barrier
	s_setprio 1
	v_mfma_f32_16x16x32_bf16 v[126:129], v[130:133], v[186:189], v[126:129]
	v_mfma_f32_16x16x32_bf16 v[122:125], v[138:141], v[186:189], v[122:125]
	v_mfma_f32_16x16x32_bf16 v[118:121], v[130:133], v[194:197], v[118:121]
	v_mfma_f32_16x16x32_bf16 v[114:117], v[138:141], v[194:197], v[114:117]
	v_mfma_f32_16x16x32_bf16 v[110:113], v[130:133], v[202:205], v[110:113]
	v_mfma_f32_16x16x32_bf16 v[106:109], v[138:141], v[202:205], v[106:109]
	v_mfma_f32_16x16x32_bf16 v[102:105], v[130:133], v[210:213], v[102:105]
	v_mfma_f32_16x16x32_bf16 v[98:101], v[138:141], v[210:213], v[98:101]
	v_mfma_f32_16x16x32_bf16 v[126:129], v[134:137], v[190:193], v[126:129]
	v_mfma_f32_16x16x32_bf16 v[122:125], v[142:145], v[190:193], v[122:125]
	v_mfma_f32_16x16x32_bf16 v[118:121], v[134:137], v[198:201], v[118:121]
	v_mfma_f32_16x16x32_bf16 v[114:117], v[142:145], v[198:201], v[114:117]
	v_mfma_f32_16x16x32_bf16 v[110:113], v[134:137], v[206:209], v[110:113]
	v_mfma_f32_16x16x32_bf16 v[106:109], v[142:145], v[206:209], v[106:109]
	v_mfma_f32_16x16x32_bf16 v[102:105], v[134:137], v[214:217], v[102:105]
	v_mfma_f32_16x16x32_bf16 v[98:101], v[142:145], v[214:217], v[98:101]
	v_mfma_f32_16x16x32_bf16 v[62:65], v[146:149], v[186:189], v[62:65]
	v_mfma_f32_16x16x32_bf16 v[58:61], v[168:171], v[186:189], v[58:61]
	v_mfma_f32_16x16x32_bf16 v[54:57], v[146:149], v[194:197], v[54:57]
	v_mfma_f32_16x16x32_bf16 v[50:53], v[168:171], v[194:197], v[50:53]
	v_mfma_f32_16x16x32_bf16 v[46:49], v[146:149], v[202:205], v[46:49]
	v_mfma_f32_16x16x32_bf16 v[42:45], v[168:171], v[202:205], v[42:45]
	v_mfma_f32_16x16x32_bf16 v[38:41], v[146:149], v[210:213], v[38:41]
	v_mfma_f32_16x16x32_bf16 v[34:37], v[168:171], v[210:213], v[34:37]
	v_mfma_f32_16x16x32_bf16 v[62:65], v[164:167], v[190:193], v[62:65]
	v_mfma_f32_16x16x32_bf16 v[58:61], v[182:185], v[190:193], v[58:61]
	v_mfma_f32_16x16x32_bf16 v[54:57], v[164:167], v[198:201], v[54:57]
	v_mfma_f32_16x16x32_bf16 v[50:53], v[182:185], v[198:201], v[50:53]
	v_mfma_f32_16x16x32_bf16 v[46:49], v[164:167], v[206:209], v[46:49]
	v_mfma_f32_16x16x32_bf16 v[42:45], v[182:185], v[206:209], v[42:45]
	v_mfma_f32_16x16x32_bf16 v[38:41], v[164:167], v[214:217], v[38:41]
	v_mfma_f32_16x16x32_bf16 v[34:37], v[182:185], v[214:217], v[34:37]
	s_setprio 0
	s_barrier
	s_mov_b32 m0, s16
	s_mov_b32 s42, s78
	s_mov_b32 s43, s79
	ds_read_b128 v[186:189], v158 offset:16384
	ds_read_b128 v[190:193], v158 offset:17408
	ds_read_b128 v[194:197], v158 offset:18432
	ds_read_b128 v[198:201], v158 offset:19456
	ds_read_b128 v[202:205], v158 offset:20480
	ds_read_b128 v[206:209], v158 offset:21504
	ds_read_b128 v[210:213], v158 offset:22528
	ds_read_b128 v[214:217], v158 offset:23552
	buffer_load_dwordx4 v151, s[40:43], s69 offen lds
	s_mov_b32 m0, s17
	s_add_i32 s71, s69, 0x80000
	buffer_load_dwordx4 v153, s[40:43], s69 offen lds
	s_mov_b32 m0, s18
	s_nop 0
	buffer_load_dwordx4 v151, s[40:43], s71 offen lds
	s_mov_b32 m0, s19
	s_nop 0
	buffer_load_dwordx4 v153, s[40:43], s71 offen lds
	s_mov_b32 m0, s15
	s_nop 0
	buffer_load_dwordx4 v150, s[76:79], s70 offen lds
	s_mov_b32 m0, s20
	s_nop 0
	buffer_load_dwordx4 v152, s[76:79], s70 offen lds
	s_waitcnt vmcnt(8)
	s_waitcnt lgkmcnt(0)
	s_barrier
	s_setprio 1
	v_mfma_f32_16x16x32_bf16 v[94:97], v[130:133], v[186:189], v[94:97]
	v_mfma_f32_16x16x32_bf16 v[90:93], v[138:141], v[186:189], v[90:93]
	v_mfma_f32_16x16x32_bf16 v[86:89], v[130:133], v[194:197], v[86:89]
	v_mfma_f32_16x16x32_bf16 v[82:85], v[138:141], v[194:197], v[82:85]
	v_mfma_f32_16x16x32_bf16 v[78:81], v[130:133], v[202:205], v[78:81]
	v_mfma_f32_16x16x32_bf16 v[74:77], v[138:141], v[202:205], v[74:77]
	v_mfma_f32_16x16x32_bf16 v[70:73], v[130:133], v[210:213], v[70:73]
	v_mfma_f32_16x16x32_bf16 v[66:69], v[138:141], v[210:213], v[66:69]
	v_mfma_f32_16x16x32_bf16 v[94:97], v[134:137], v[190:193], v[94:97]
	v_mfma_f32_16x16x32_bf16 v[90:93], v[142:145], v[190:193], v[90:93]
	v_mfma_f32_16x16x32_bf16 v[86:89], v[134:137], v[198:201], v[86:89]
	v_mfma_f32_16x16x32_bf16 v[82:85], v[142:145], v[198:201], v[82:85]
	v_mfma_f32_16x16x32_bf16 v[78:81], v[134:137], v[206:209], v[78:81]
	v_mfma_f32_16x16x32_bf16 v[74:77], v[142:145], v[206:209], v[74:77]
	v_mfma_f32_16x16x32_bf16 v[70:73], v[134:137], v[214:217], v[70:73]
	v_mfma_f32_16x16x32_bf16 v[66:69], v[142:145], v[214:217], v[66:69]
	v_mfma_f32_16x16x32_bf16 v[30:33], v[146:149], v[186:189], v[30:33]
	v_mfma_f32_16x16x32_bf16 v[26:29], v[168:171], v[186:189], v[26:29]
	v_mfma_f32_16x16x32_bf16 v[22:25], v[146:149], v[194:197], v[22:25]
	v_mfma_f32_16x16x32_bf16 v[18:21], v[168:171], v[194:197], v[18:21]
	v_mfma_f32_16x16x32_bf16 v[14:17], v[146:149], v[202:205], v[14:17]
	v_mfma_f32_16x16x32_bf16 v[10:13], v[168:171], v[202:205], v[10:13]
	v_mfma_f32_16x16x32_bf16 v[6:9], v[146:149], v[210:213], v[6:9]
	v_mfma_f32_16x16x32_bf16 v[2:5], v[168:171], v[210:213], v[2:5]
	v_mfma_f32_16x16x32_bf16 v[30:33], v[164:167], v[190:193], v[30:33]
	v_mfma_f32_16x16x32_bf16 v[26:29], v[182:185], v[190:193], v[26:29]
	v_mfma_f32_16x16x32_bf16 v[22:25], v[164:167], v[198:201], v[22:25]
	v_mfma_f32_16x16x32_bf16 v[18:21], v[182:185], v[198:201], v[18:21]
	v_mfma_f32_16x16x32_bf16 v[14:17], v[164:167], v[206:209], v[14:17]
	v_mfma_f32_16x16x32_bf16 v[10:13], v[182:185], v[206:209], v[10:13]
	v_mfma_f32_16x16x32_bf16 v[6:9], v[164:167], v[214:217], v[6:9]
	v_mfma_f32_16x16x32_bf16 v[2:5], v[182:185], v[214:217], v[2:5]
	s_setprio 0
	s_barrier
; #define PG8_STAGEX(rs, bufoff, soff, voff) do { _Pragma("unroll") for (int _i = 0; _i < 2; ++_i) \
;         __builtin_amdgcn_raw_ptr_buffer_load_lds(rs, (LAS unsigned*)(lds + (bufoff) + ldsw + _i * 8192), 16, (voff)[_i], (soff), 0, 0); } while (0)
; #define PG8_LDA(dst, b, h) do { _Pragma("unroll") for (int m = 0; m < 4; ++m) _Pragma("unroll") for (int k = 0; k < 2; ++k) dst[m][k] = *(const LAS bf16x8*)(lds + PG8_SA(b, h) + aoff + m * 2048 + k * 1024); } while (0)
; #define PG8_LDB(dst, b, h) do { _Pragma("unroll") for (int n = 0; n < 2; ++n) _Pragma("unroll") for (int k = 0; k < 2; ++k) dst[n][k] = *(const LAS bf16x8*)(lds + PG8_SB(b, h) + boff + n * 2048 + k * 1024); } while (0)
; #define PG8_WAIT_V(n) asm volatile("s_waitcnt vmcnt(" #n ")" ::: "memory")
; #define PG8_WAIT_L(n) asm volatile("s_waitcnt lgkmcnt(" #n ")" ::: "memory")
; #define PG8_BAR __builtin_amdgcn_s_barrier()
; #define PG8_SCHED __builtin_amdgcn_sched_barrier(0)
;     ...
;             PG8_LDB(B0, 1, 0); PG8_LDB(B1, 1, 1); PG8_SCHED; PG8_LDA(At, 1, 0); PG8_STAGEX(rsA, PG8_SA(0, 1), a2 + hstepA, voffA);
;             PG8_WAIT_V(8); PG8_WAIT_L(0); PG8_BAR; PG8_MMA(0, 0, At, B0); PG8_MMA(0, 1, At, B1); PG8_BAR; PG8_SCHED;
;             PG8_LDA(At, 1, 1); PG8_STAGEX(rsB, PG8_SB(1, 0), b3, voffB); PG8_STAGEX(rsB, PG8_SB(1, 1), b3 + hstepB, voffB); PG8_STAGEX(rsA, PG8_SA(1, 0), a3, voffA);
;             PG8_WAIT_V(8); PG8_WAIT_L(0); PG8_BAR; PG8_MMA(1, 0, At, B0); PG8_MMA(1, 1, At, B1); PG8_BAR; PG8_SCHED;
;         }
	v_add_u32_e32 v142, 0x18000, v157
	v_add_u32_e32 v159, 0x1c000, v157
	ds_read_b128 v[130:133], v142
	ds_read_b128 v[134:137], v142 offset:1024
	ds_read_b128 v[138:141], v142 offset:2048
	ds_read_b128 v[142:145], v142 offset:3072
	ds_read_b128 v[146:149], v159
	ds_read_b128 v[164:167], v159 offset:1024
	ds_read_b128 v[168:171], v159 offset:2048
	ds_read_b128 v[182:185], v159 offset:3072
	s_add_i32 s70, s70, 0x80000
	s_mov_b32 m0, s21
	ds_read_b128 v[186:189], v158 offset:32768
	ds_read_b128 v[190:193], v158 offset:33792
	ds_read_b128 v[194:197], v158 offset:34816
	ds_read_b128 v[198:201], v158 offset:35840
	ds_read_b128 v[202:205], v158 offset:36864
	ds_read_b128 v[206:209], v158 offset:37888
	ds_read_b128 v[210:213], v158 offset:38912
	ds_read_b128 v[214:217], v158 offset:39936
	buffer_load_dwordx4 v150, s[76:79], s70 offen lds
	s_mov_b32 m0, s22
	s_nop 0
	buffer_load_dwordx4 v152, s[76:79], s70 offen lds
	s_waitcnt vmcnt(8)
	s_waitcnt lgkmcnt(0)
	s_barrier
	s_setprio 1
	v_mfma_f32_16x16x32_bf16 v[126:129], v[130:133], v[186:189], v[126:129]
	v_mfma_f32_16x16x32_bf16 v[122:125], v[138:141], v[186:189], v[122:125]
	v_mfma_f32_16x16x32_bf16 v[118:121], v[130:133], v[194:197], v[118:121]
	v_mfma_f32_16x16x32_bf16 v[114:117], v[138:141], v[194:197], v[114:117]
	v_mfma_f32_16x16x32_bf16 v[110:113], v[130:133], v[202:205], v[110:113]
	v_mfma_f32_16x16x32_bf16 v[106:109], v[138:141], v[202:205], v[106:109]
	v_mfma_f32_16x16x32_bf16 v[102:105], v[130:133], v[210:213], v[102:105]
	v_mfma_f32_16x16x32_bf16 v[98:101], v[138:141], v[210:213], v[98:101]
	v_mfma_f32_16x16x32_bf16 v[126:129], v[134:137], v[190:193], v[126:129]
	v_mfma_f32_16x16x32_bf16 v[122:125], v[142:145], v[190:193], v[122:125]
	v_mfma_f32_16x16x32_bf16 v[118:121], v[134:137], v[198:201], v[118:121]
	v_mfma_f32_16x16x32_bf16 v[114:117], v[142:145], v[198:201], v[114:117]
	v_mfma_f32_16x16x32_bf16 v[110:113], v[134:137], v[206:209], v[110:113]
	v_mfma_f32_16x16x32_bf16 v[106:109], v[142:145], v[206:209], v[106:109]
	v_mfma_f32_16x16x32_bf16 v[102:105], v[134:137], v[214:217], v[102:105]
	v_mfma_f32_16x16x32_bf16 v[98:101], v[142:145], v[214:217], v[98:101]
	v_mfma_f32_16x16x32_bf16 v[62:65], v[146:149], v[186:189], v[62:65]
	v_mfma_f32_16x16x32_bf16 v[58:61], v[168:171], v[186:189], v[58:61]
	v_mfma_f32_16x16x32_bf16 v[54:57], v[146:149], v[194:197], v[54:57]
	v_mfma_f32_16x16x32_bf16 v[50:53], v[168:171], v[194:197], v[50:53]
	v_mfma_f32_16x16x32_bf16 v[46:49], v[146:149], v[202:205], v[46:49]
	v_mfma_f32_16x16x32_bf16 v[42:45], v[168:171], v[202:205], v[42:45]
	v_mfma_f32_16x16x32_bf16 v[38:41], v[146:149], v[210:213], v[38:41]
	v_mfma_f32_16x16x32_bf16 v[34:37], v[168:171], v[210:213], v[34:37]
	v_mfma_f32_16x16x32_bf16 v[62:65], v[164:167], v[190:193], v[62:65]
	v_mfma_f32_16x16x32_bf16 v[58:61], v[182:185], v[190:193], v[58:61]
	v_mfma_f32_16x16x32_bf16 v[54:57], v[164:167], v[198:201], v[54:57]
	v_mfma_f32_16x16x32_bf16 v[50:53], v[182:185], v[198:201], v[50:53]
	v_mfma_f32_16x16x32_bf16 v[46:49], v[164:167], v[206:209], v[46:49]
	v_mfma_f32_16x16x32_bf16 v[42:45], v[182:185], v[206:209], v[42:45]
	v_mfma_f32_16x16x32_bf16 v[38:41], v[164:167], v[214:217], v[38:41]
	v_mfma_f32_16x16x32_bf16 v[34:37], v[182:185], v[214:217], v[34:37]
	s_setprio 0
	s_barrier
	s_mov_b32 m0, s23
	s_or_b32 s70, s69, 0x80
	ds_read_b128 v[186:189], v158 offset:49152
	ds_read_b128 v[190:193], v158 offset:50176
	ds_read_b128 v[194:197], v158 offset:51200
	ds_read_b128 v[198:201], v158 offset:52224
	ds_read_b128 v[202:205], v158 offset:53248
	ds_read_b128 v[206:209], v158 offset:54272
	ds_read_b128 v[210:213], v158 offset:55296
	ds_read_b128 v[214:217], v158 offset:56320
	buffer_load_dwordx4 v151, s[40:43], s70 offen lds
	s_mov_b32 m0, s24
	s_add_i32 s69, s69, 0x80080
	buffer_load_dwordx4 v153, s[40:43], s70 offen lds
	s_mov_b32 m0, s27
	s_nop 0
	buffer_load_dwordx4 v151, s[40:43], s69 offen lds
	s_mov_b32 m0, s28
	s_nop 0
	buffer_load_dwordx4 v153, s[40:43], s69 offen lds
	s_mov_b32 m0, s25
	s_nop 0
	buffer_load_dwordx4 v150, s[76:79], s68 offen lds
	s_mov_b32 m0, s26
	s_nop 0
	buffer_load_dwordx4 v152, s[76:79], s68 offen lds
	s_waitcnt vmcnt(8)
	s_waitcnt lgkmcnt(0)
	s_barrier
	s_setprio 1
	v_mfma_f32_16x16x32_bf16 v[94:97], v[130:133], v[186:189], v[94:97]
	v_mfma_f32_16x16x32_bf16 v[90:93], v[138:141], v[186:189], v[90:93]
	v_mfma_f32_16x16x32_bf16 v[86:89], v[130:133], v[194:197], v[86:89]
	v_mfma_f32_16x16x32_bf16 v[82:85], v[138:141], v[194:197], v[82:85]
	v_mfma_f32_16x16x32_bf16 v[78:81], v[130:133], v[202:205], v[78:81]
	v_mfma_f32_16x16x32_bf16 v[74:77], v[138:141], v[202:205], v[74:77]
	v_mfma_f32_16x16x32_bf16 v[70:73], v[130:133], v[210:213], v[70:73]
	v_mfma_f32_16x16x32_bf16 v[66:69], v[138:141], v[210:213], v[66:69]
	v_mfma_f32_16x16x32_bf16 v[94:97], v[134:137], v[190:193], v[94:97]
	v_mfma_f32_16x16x32_bf16 v[90:93], v[142:145], v[190:193], v[90:93]
	v_mfma_f32_16x16x32_bf16 v[86:89], v[134:137], v[198:201], v[86:89]
	v_mfma_f32_16x16x32_bf16 v[82:85], v[142:145], v[198:201], v[82:85]
	v_mfma_f32_16x16x32_bf16 v[78:81], v[134:137], v[206:209], v[78:81]
	v_mfma_f32_16x16x32_bf16 v[74:77], v[142:145], v[206:209], v[74:77]
	v_mfma_f32_16x16x32_bf16 v[70:73], v[134:137], v[214:217], v[70:73]
	v_mfma_f32_16x16x32_bf16 v[66:69], v[142:145], v[214:217], v[66:69]
	v_mfma_f32_16x16x32_bf16 v[30:33], v[146:149], v[186:189], v[30:33]
	v_mfma_f32_16x16x32_bf16 v[26:29], v[168:171], v[186:189], v[26:29]
	v_mfma_f32_16x16x32_bf16 v[22:25], v[146:149], v[194:197], v[22:25]
	v_mfma_f32_16x16x32_bf16 v[18:21], v[168:171], v[194:197], v[18:21]
	v_mfma_f32_16x16x32_bf16 v[14:17], v[146:149], v[202:205], v[14:17]
	v_mfma_f32_16x16x32_bf16 v[10:13], v[168:171], v[202:205], v[10:13]
	v_mfma_f32_16x16x32_bf16 v[6:9], v[146:149], v[210:213], v[6:9]
	v_mfma_f32_16x16x32_bf16 v[2:5], v[168:171], v[210:213], v[2:5]
	v_mfma_f32_16x16x32_bf16 v[30:33], v[164:167], v[190:193], v[30:33]
	v_mfma_f32_16x16x32_bf16 v[26:29], v[182:185], v[190:193], v[26:29]
	v_mfma_f32_16x16x32_bf16 v[22:25], v[164:167], v[198:201], v[22:25]
	v_mfma_f32_16x16x32_bf16 v[18:21], v[182:185], v[198:201], v[18:21]
	v_mfma_f32_16x16x32_bf16 v[14:17], v[164:167], v[206:209], v[14:17]
	v_mfma_f32_16x16x32_bf16 v[10:13], v[182:185], v[206:209], v[10:13]
	v_mfma_f32_16x16x32_bf16 v[6:9], v[164:167], v[214:217], v[6:9]
	v_mfma_f32_16x16x32_bf16 v[2:5], v[182:185], v[214:217], v[2:5]
	s_setprio 0
	s_barrier
	s_add_i32 s67, s67, 2
	s_addk_i32 s62, 0x100
	s_addk_i32 s63, 0x100
	s_cmp_gt_u32 s67, 29
	s_cbranch_scc0 .LBB0_1274
	s_and_b64 vcc, exec, s[50:51]
	s_cbranch_vccz .LBB0_1277
	s_barrier

; #define PG8_STAGEX(rs, bufoff, soff, voff) do { _Pragma("unroll") for (int _i = 0; _i < 2; ++_i) \
;         __builtin_amdgcn_raw_ptr_buffer_load_lds(rs, (LAS unsigned*)(lds + (bufoff) + ldsw + _i * 8192), 16, (voff)[_i], (soff), 0, 0); } while (0)
; #define PG8_LDA(dst, b, h) do { _Pragma("unroll") for (int m = 0; m < 4; ++m) _Pragma("unroll") for (int k = 0; k < 2; ++k) dst[m][k] = *(const LAS bf16x8*)(lds + PG8_SA(b, h) + aoff + m * 2048 + k * 1024); } while (0)
; #define PG8_LDB(dst, b, h) do { _Pragma("unroll") for (int n = 0; n < 2; ++n) _Pragma("unroll") for (int k = 0; k < 2; ++k) dst[n][k] = *(const LAS bf16x8*)(lds + PG8_SB(b, h) + boff + n * 2048 + k * 1024); } while (0)
; #define PG8_WAIT_V(n) asm volatile("s_waitcnt vmcnt(" #n ")" ::: "memory")
; #define PG8_WAIT_L(n) asm volatile("s_waitcnt lgkmcnt(" #n ")" ::: "memory")
; #define PG8_BAR __builtin_amdgcn_s_barrier()
; #define PG8_SCHED __builtin_amdgcn_sched_barrier(0)
;     ...
;                 if (w0) { PG8_LDB(B0, 0, 0); PG8_LDB(B1, 0, 1); PG8_SCHED; PG8_LDA(At, 0, 0); }
;                 PG8_WAIT_L(0); PG8_BAR; if (w0) { PG8_MMA(0, 0, At, B0); PG8_MMA(0, 1, At, B1); } PG8_BAR; PG8_SCHED;
;                 PG8_STAGEX(rsB, PG8_SB(0, 0), b2, voffB); PG8_STAGEX(rsB, PG8_SB(0, 1), b2 + hstepB, voffB); PG8_STAGEX(rsA, PG8_SA(0, 0), a2, voffA);
;                 PG8_WAIT_V(6); PG8_BAR; PG8_BAR; PG8_SCHED;
.LBB0_1287:
	v_add_u32_e32 v86, 0x10000, v72
	v_add_u32_e32 v102, 0x14000, v72
	ds_read_b128 v[74:77], v86
	ds_read_b128 v[78:81], v86 offset:1024
	ds_read_b128 v[82:85], v86 offset:2048
	ds_read_b128 v[86:89], v86 offset:3072
	ds_read_b128 v[90:93], v102
	ds_read_b128 v[94:97], v102 offset:1024
	ds_read_b128 v[98:101], v102 offset:2048
	ds_read_b128 v[102:105], v102 offset:3072
	s_cmp_lg_u32 s29, 28
	s_cselect_b32 s30, s28, 0
	s_add_i32 s31, s30, s19
	s_or_b32 s35, s31, 0x80
	s_add_i32 s30, s30, s13
	ds_read_b128 v[106:109], v73
	ds_read_b128 v[110:113], v73 offset:1024
	ds_read_b128 v[114:117], v73 offset:2048
	ds_read_b128 v[118:121], v73 offset:3072
	ds_read_b128 v[122:125], v73 offset:4096
	ds_read_b128 v[126:129], v73 offset:5120
	ds_read_b128 v[130:133], v73 offset:6144
	ds_read_b128 v[134:137], v73 offset:7168
	s_waitcnt lgkmcnt(0)
	s_barrier
	s_setprio 1
	v_mfma_f32_16x16x32_bf16 v[62:65], v[74:77], v[106:109], v[62:65]
	v_mfma_f32_16x16x32_bf16 v[58:61], v[82:85], v[106:109], v[58:61]
	v_mfma_f32_16x16x32_bf16 v[54:57], v[74:77], v[114:117], v[54:57]
	v_mfma_f32_16x16x32_bf16 v[50:53], v[82:85], v[114:117], v[50:53]
	v_mfma_f32_16x16x32_bf16 v[46:49], v[74:77], v[122:125], v[46:49]
	v_mfma_f32_16x16x32_bf16 v[42:45], v[82:85], v[122:125], v[42:45]
	v_mfma_f32_16x16x32_bf16 v[38:41], v[74:77], v[130:133], v[38:41]
	v_mfma_f32_16x16x32_bf16 v[34:37], v[82:85], v[130:133], v[34:37]
	v_mfma_f32_16x16x32_bf16 v[62:65], v[78:81], v[110:113], v[62:65]
	v_mfma_f32_16x16x32_bf16 v[58:61], v[86:89], v[110:113], v[58:61]
	v_mfma_f32_16x16x32_bf16 v[54:57], v[78:81], v[118:121], v[54:57]
	v_mfma_f32_16x16x32_bf16 v[50:53], v[86:89], v[118:121], v[50:53]
	v_mfma_f32_16x16x32_bf16 v[46:49], v[78:81], v[126:129], v[46:49]
	v_mfma_f32_16x16x32_bf16 v[42:45], v[86:89], v[126:129], v[42:45]
	v_mfma_f32_16x16x32_bf16 v[38:41], v[78:81], v[134:137], v[38:41]
	v_mfma_f32_16x16x32_bf16 v[34:37], v[86:89], v[134:137], v[34:37]
	v_mfma_f32_16x16x32_bf16 v[30:33], v[90:93], v[106:109], v[30:33]
	v_mfma_f32_16x16x32_bf16 v[26:29], v[98:101], v[106:109], v[26:29]
	v_mfma_f32_16x16x32_bf16 v[22:25], v[90:93], v[114:117], v[22:25]
	v_mfma_f32_16x16x32_bf16 v[18:21], v[98:101], v[114:117], v[18:21]
	v_mfma_f32_16x16x32_bf16 v[14:17], v[90:93], v[122:125], v[14:17]
	v_mfma_f32_16x16x32_bf16 v[10:13], v[98:101], v[122:125], v[10:13]
	v_mfma_f32_16x16x32_bf16 v[6:9], v[90:93], v[130:133], v[6:9]
	v_mfma_f32_16x16x32_bf16 v[2:5], v[98:101], v[130:133], v[2:5]
	v_mfma_f32_16x16x32_bf16 v[30:33], v[94:97], v[110:113], v[30:33]
	v_mfma_f32_16x16x32_bf16 v[26:29], v[102:105], v[110:113], v[26:29]
	v_mfma_f32_16x16x32_bf16 v[22:25], v[94:97], v[118:121], v[22:25]
	v_mfma_f32_16x16x32_bf16 v[18:21], v[102:105], v[118:121], v[18:21]
	v_mfma_f32_16x16x32_bf16 v[14:17], v[94:97], v[126:129], v[14:17]
	v_mfma_f32_16x16x32_bf16 v[10:13], v[102:105], v[126:129], v[10:13]
	v_mfma_f32_16x16x32_bf16 v[6:9], v[94:97], v[134:137], v[6:9]
	v_mfma_f32_16x16x32_bf16 v[2:5], v[102:105], v[134:137], v[2:5]
	s_setprio 0
	s_barrier
	s_mov_b32 m0, s15
	s_mov_b32 s42, s78
	s_mov_b32 s43, s79
	buffer_load_dwordx4 v67, s[40:43], s30 offen lds
	s_mov_b32 m0, s16
	s_add_i32 s38, s30, 0x80000
	buffer_load_dwordx4 v69, s[40:43], s30 offen lds
	s_mov_b32 m0, s17
	s_nop 0
	buffer_load_dwordx4 v67, s[40:43], s38 offen lds
	s_mov_b32 m0, s18
	s_nop 0
	buffer_load_dwordx4 v69, s[40:43], s38 offen lds
	s_mov_b32 m0, s14
	s_nop 0
	buffer_load_dwordx4 v66, s[76:79], s31 offen lds
	s_mov_b32 m0, s20
	s_nop 0
	buffer_load_dwordx4 v68, s[76:79], s31 offen lds
	s_waitcnt vmcnt(6)
	s_barrier
	s_barrier
; #define PG8_STAGEX(rs, bufoff, soff, voff) do { _Pragma("unroll") for (int _i = 0; _i < 2; ++_i) \
;         __builtin_amdgcn_raw_ptr_buffer_load_lds(rs, (LAS unsigned*)(lds + (bufoff) + ldsw + _i * 8192), 16, (voff)[_i], (soff), 0, 0); } while (0)
; #define PG8_LDA(dst, b, h) do { _Pragma("unroll") for (int m = 0; m < 4; ++m) _Pragma("unroll") for (int k = 0; k < 2; ++k) dst[m][k] = *(const LAS bf16x8*)(lds + PG8_SA(b, h) + aoff + m * 2048 + k * 1024); } while (0)
; #define PG8_LDB(dst, b, h) do { _Pragma("unroll") for (int n = 0; n < 2; ++n) _Pragma("unroll") for (int k = 0; k < 2; ++k) dst[n][k] = *(const LAS bf16x8*)(lds + PG8_SB(b, h) + boff + n * 2048 + k * 1024); } while (0)
; #define PG8_WAIT_V(n) asm volatile("s_waitcnt vmcnt(" #n ")" ::: "memory")
; #define PG8_WAIT_L(n) asm volatile("s_waitcnt lgkmcnt(" #n ")" ::: "memory")
; #define PG8_BAR __builtin_amdgcn_s_barrier()
; #define PG8_SCHED __builtin_amdgcn_sched_barrier(0)
;     ...
;                 if (w0) { PG8_LDB(B0, 1, 0); PG8_LDB(B1, 1, 1); PG8_SCHED; PG8_LDA(At, 1, 0); }
;                 PG8_WAIT_L(0); PG8_BAR; if (w0) { PG8_MMA(0, 0, At, B0); PG8_MMA(0, 1, At, B1); } PG8_BAR; PG8_SCHED;
;                 PG8_STAGEX(rsB, PG8_SB(1, 0), b3, voffB); PG8_STAGEX(rsB, PG8_SB(1, 1), b3 + hstepB, voffB); PG8_STAGEX(rsA, PG8_SA(1, 0), a3, voffA);
;                 PG8_WAIT_V(6); PG8_BAR; PG8_BAR; PG8_SCHED;
;             }
	v_add_u32_e32 v86, 0x18000, v72
	v_add_u32_e32 v102, 0x1c000, v72
	ds_read_b128 v[74:77], v86
	ds_read_b128 v[78:81], v86 offset:1024
	ds_read_b128 v[82:85], v86 offset:2048
	ds_read_b128 v[86:89], v86 offset:3072
	ds_read_b128 v[90:93], v102
	ds_read_b128 v[94:97], v102 offset:1024
	ds_read_b128 v[98:101], v102 offset:2048
	ds_read_b128 v[102:105], v102 offset:3072
	ds_read_b128 v[106:109], v73 offset:32768
	ds_read_b128 v[110:113], v73 offset:33792
	ds_read_b128 v[114:117], v73 offset:34816
	ds_read_b128 v[118:121], v73 offset:35840
	ds_read_b128 v[122:125], v73 offset:36864
	ds_read_b128 v[126:129], v73 offset:37888
	ds_read_b128 v[130:133], v73 offset:38912
	ds_read_b128 v[134:137], v73 offset:39936
	s_waitcnt lgkmcnt(0)
	s_barrier
	s_setprio 1
	v_mfma_f32_16x16x32_bf16 v[62:65], v[74:77], v[106:109], v[62:65]
	v_mfma_f32_16x16x32_bf16 v[58:61], v[82:85], v[106:109], v[58:61]
	v_mfma_f32_16x16x32_bf16 v[54:57], v[74:77], v[114:117], v[54:57]
	v_mfma_f32_16x16x32_bf16 v[50:53], v[82:85], v[114:117], v[50:53]
	v_mfma_f32_16x16x32_bf16 v[46:49], v[74:77], v[122:125], v[46:49]
	v_mfma_f32_16x16x32_bf16 v[42:45], v[82:85], v[122:125], v[42:45]
	v_mfma_f32_16x16x32_bf16 v[38:41], v[74:77], v[130:133], v[38:41]
	v_mfma_f32_16x16x32_bf16 v[34:37], v[82:85], v[130:133], v[34:37]
	v_mfma_f32_16x16x32_bf16 v[62:65], v[78:81], v[110:113], v[62:65]
	v_mfma_f32_16x16x32_bf16 v[58:61], v[86:89], v[110:113], v[58:61]
	v_mfma_f32_16x16x32_bf16 v[54:57], v[78:81], v[118:121], v[54:57]
	v_mfma_f32_16x16x32_bf16 v[50:53], v[86:89], v[118:121], v[50:53]
	v_mfma_f32_16x16x32_bf16 v[46:49], v[78:81], v[126:129], v[46:49]
	v_mfma_f32_16x16x32_bf16 v[42:45], v[86:89], v[126:129], v[42:45]
	v_mfma_f32_16x16x32_bf16 v[38:41], v[78:81], v[134:137], v[38:41]
	v_mfma_f32_16x16x32_bf16 v[34:37], v[86:89], v[134:137], v[34:37]
	v_mfma_f32_16x16x32_bf16 v[30:33], v[90:93], v[106:109], v[30:33]
	s_or_b32 s31, s30, 0x80
	v_mfma_f32_16x16x32_bf16 v[26:29], v[98:101], v[106:109], v[26:29]
	v_mfma_f32_16x16x32_bf16 v[22:25], v[90:93], v[114:117], v[22:25]
	v_mfma_f32_16x16x32_bf16 v[18:21], v[98:101], v[114:117], v[18:21]
	v_mfma_f32_16x16x32_bf16 v[14:17], v[90:93], v[122:125], v[14:17]
	v_mfma_f32_16x16x32_bf16 v[10:13], v[98:101], v[122:125], v[10:13]
	v_mfma_f32_16x16x32_bf16 v[6:9], v[90:93], v[130:133], v[6:9]
	v_mfma_f32_16x16x32_bf16 v[2:5], v[98:101], v[130:133], v[2:5]
	v_mfma_f32_16x16x32_bf16 v[30:33], v[94:97], v[110:113], v[30:33]
	v_mfma_f32_16x16x32_bf16 v[26:29], v[102:105], v[110:113], v[26:29]
	v_mfma_f32_16x16x32_bf16 v[22:25], v[94:97], v[118:121], v[22:25]
	v_mfma_f32_16x16x32_bf16 v[18:21], v[102:105], v[118:121], v[18:21]
	v_mfma_f32_16x16x32_bf16 v[14:17], v[94:97], v[126:129], v[14:17]
	v_mfma_f32_16x16x32_bf16 v[10:13], v[102:105], v[126:129], v[10:13]
	v_mfma_f32_16x16x32_bf16 v[6:9], v[94:97], v[134:137], v[6:9]
	v_mfma_f32_16x16x32_bf16 v[2:5], v[102:105], v[134:137], v[2:5]
	s_setprio 0
	s_barrier
	s_mov_b32 m0, s22
	s_add_i32 s30, s30, 0x80080
	buffer_load_dwordx4 v67, s[40:43], s31 offen lds
	s_mov_b32 m0, s23
	s_nop 0
	buffer_load_dwordx4 v69, s[40:43], s31 offen lds
	s_mov_b32 m0, s26
	s_nop 0
	buffer_load_dwordx4 v67, s[40:43], s30 offen lds
	s_mov_b32 m0, s27
	s_nop 0
	buffer_load_dwordx4 v69, s[40:43], s30 offen lds
	s_mov_b32 m0, s24
	s_nop 0
	buffer_load_dwordx4 v66, s[76:79], s35 offen lds
	s_mov_b32 m0, s25
	s_nop 0
	buffer_load_dwordx4 v68, s[76:79], s35 offen lds
	s_waitcnt vmcnt(6)
	s_barrier
	s_barrier
	s_addk_i32 s28, 0x100
	s_add_i32 s29, s29, 2
	s_cmp_gt_u32 s29, 29
	s_cbranch_scc0 .LBB0_1287
	s_cmpk_lt_u32 s12, 0x100
	s_cbranch_scc0 .LBB0_1290
	s_barrier

; #define PG8_STAGEX(rs, bufoff, soff, voff) do { _Pragma("unroll") for (int _i = 0; _i < 2; ++_i) \
;         __builtin_amdgcn_raw_ptr_buffer_load_lds(rs, (LAS unsigned*)(lds + (bufoff) + ldsw + _i * 8192), 16, (voff)[_i], (soff), 0, 0); } while (0)
; #define PG8_LDA(dst, b, h) do { _Pragma("unroll") for (int m = 0; m < 4; ++m) _Pragma("unroll") for (int k = 0; k < 2; ++k) dst[m][k] = *(const LAS bf16x8*)(lds + PG8_SA(b, h) + aoff + m * 2048 + k * 1024); } while (0)
; #define PG8_LDB(dst, b, h) do { _Pragma("unroll") for (int n = 0; n < 2; ++n) _Pragma("unroll") for (int k = 0; k < 2; ++k) dst[n][k] = *(const LAS bf16x8*)(lds + PG8_SB(b, h) + boff + n * 2048 + k * 1024); } while (0)
; #define PG8_WAIT_V(n) asm volatile("s_waitcnt vmcnt(" #n ")" ::: "memory")
; #define PG8_WAIT_L(n) asm volatile("s_waitcnt lgkmcnt(" #n ")" ::: "memory")
; #define PG8_BAR __builtin_amdgcn_s_barrier()
; #define PG8_SCHED __builtin_amdgcn_sched_barrier(0)
;     ...
;             PG8_LDB(B0, 0, 0); PG8_LDB(B1, 0, 1); PG8_SCHED; PG8_LDA(At, 0, 0); PG8_STAGEX(rsA, PG8_SA(1, 1), a1 + hstepA, voffA);
;             PG8_WAIT_V(8); PG8_WAIT_L(0); PG8_BAR; PG8_MMA(0, 0, At, B0); PG8_MMA(0, 1, At, B1); PG8_BAR; PG8_SCHED;
;             PG8_LDA(At, 0, 1); PG8_STAGEX(rsB, PG8_SB(0, 0), b2, voffB); PG8_STAGEX(rsB, PG8_SB(0, 1), b2 + hstepB, voffB); PG8_STAGEX(rsA, PG8_SA(0, 0), a2, voffA);
;             PG8_WAIT_V(8); PG8_WAIT_L(0); PG8_BAR; PG8_MMA(1, 0, At, B0); PG8_MMA(1, 1, At, B1); PG8_BAR; PG8_SCHED;
.LBB0_1377:
	v_add_u32_e32 v142, 0x10000, v185
	v_add_u32_e32 v158, 0x14000, v185
	ds_read_b128 v[130:133], v142
	ds_read_b128 v[134:137], v142 offset:1024
	ds_read_b128 v[138:141], v142 offset:2048
	ds_read_b128 v[142:145], v142 offset:3072
	ds_read_b128 v[146:149], v158
	ds_read_b128 v[150:153], v158 offset:1024
	ds_read_b128 v[154:157], v158 offset:2048
	ds_read_b128 v[158:161], v158 offset:3072
	s_add_i32 s50, s43, 0xfff40080
	s_cmp_eq_u32 s60, 12
	s_cselect_b32 s63, s30, s50
	s_cselect_b32 s62, s31, s59
	s_add_i32 s61, s63, 0x80
	s_mov_b32 m0, s23
	ds_read_b128 v[162:165], v186
	ds_read_b128 v[166:169], v186 offset:1024
	ds_read_b128 v[190:193], v186 offset:2048
	ds_read_b128 v[194:197], v186 offset:3072
	ds_read_b128 v[198:201], v186 offset:4096
	ds_read_b128 v[202:205], v186 offset:5120
	ds_read_b128 v[206:209], v186 offset:6144
	ds_read_b128 v[210:213], v186 offset:7168
	buffer_load_dwordx4 v173, s[76:79], s43 offen lds
	s_mov_b32 m0, s24
	s_nop 0
	buffer_load_dwordx4 v178, s[76:79], s43 offen lds
	s_waitcnt vmcnt(8)
	s_waitcnt lgkmcnt(0)
	s_barrier
	s_setprio 1
	v_mfma_f32_16x16x32_bf16 v[126:129], v[130:133], v[162:165], v[126:129]
	v_mfma_f32_16x16x32_bf16 v[122:125], v[138:141], v[162:165], v[122:125]
	v_mfma_f32_16x16x32_bf16 v[118:121], v[130:133], v[190:193], v[118:121]
	v_mfma_f32_16x16x32_bf16 v[114:117], v[138:141], v[190:193], v[114:117]
	v_mfma_f32_16x16x32_bf16 v[110:113], v[130:133], v[198:201], v[110:113]
	v_mfma_f32_16x16x32_bf16 v[106:109], v[138:141], v[198:201], v[106:109]
	v_mfma_f32_16x16x32_bf16 v[102:105], v[130:133], v[206:209], v[102:105]
	v_mfma_f32_16x16x32_bf16 v[98:101], v[138:141], v[206:209], v[98:101]
	v_mfma_f32_16x16x32_bf16 v[126:129], v[134:137], v[166:169], v[126:129]
	v_mfma_f32_16x16x32_bf16 v[122:125], v[142:145], v[166:169], v[122:125]
	v_mfma_f32_16x16x32_bf16 v[118:121], v[134:137], v[194:197], v[118:121]
	v_mfma_f32_16x16x32_bf16 v[114:117], v[142:145], v[194:197], v[114:117]
	v_mfma_f32_16x16x32_bf16 v[110:113], v[134:137], v[202:205], v[110:113]
	v_mfma_f32_16x16x32_bf16 v[106:109], v[142:145], v[202:205], v[106:109]
	v_mfma_f32_16x16x32_bf16 v[102:105], v[134:137], v[210:213], v[102:105]
	v_mfma_f32_16x16x32_bf16 v[98:101], v[142:145], v[210:213], v[98:101]
	v_mfma_f32_16x16x32_bf16 v[94:97], v[146:149], v[162:165], v[94:97]
	v_mfma_f32_16x16x32_bf16 v[90:93], v[154:157], v[162:165], v[90:93]
	v_mfma_f32_16x16x32_bf16 v[86:89], v[146:149], v[190:193], v[86:89]
	v_mfma_f32_16x16x32_bf16 v[82:85], v[154:157], v[190:193], v[82:85]
	v_mfma_f32_16x16x32_bf16 v[78:81], v[146:149], v[198:201], v[78:81]
	v_mfma_f32_16x16x32_bf16 v[74:77], v[154:157], v[198:201], v[74:77]
	v_mfma_f32_16x16x32_bf16 v[70:73], v[146:149], v[206:209], v[70:73]
	v_mfma_f32_16x16x32_bf16 v[66:69], v[154:157], v[206:209], v[66:69]
	v_mfma_f32_16x16x32_bf16 v[94:97], v[150:153], v[166:169], v[94:97]
	v_mfma_f32_16x16x32_bf16 v[90:93], v[158:161], v[166:169], v[90:93]
	v_mfma_f32_16x16x32_bf16 v[86:89], v[150:153], v[194:197], v[86:89]
	v_mfma_f32_16x16x32_bf16 v[82:85], v[158:161], v[194:197], v[82:85]
	v_mfma_f32_16x16x32_bf16 v[78:81], v[150:153], v[202:205], v[78:81]
	v_mfma_f32_16x16x32_bf16 v[74:77], v[158:161], v[202:205], v[74:77]
	v_mfma_f32_16x16x32_bf16 v[70:73], v[150:153], v[210:213], v[70:73]
	v_mfma_f32_16x16x32_bf16 v[66:69], v[158:161], v[210:213], v[66:69]
	s_setprio 0
	s_barrier
	s_mov_b32 m0, s7
	s_mov_b32 s50, s78
	s_mov_b32 s51, s79
	ds_read_b128 v[162:165], v186 offset:16384
	ds_read_b128 v[166:169], v186 offset:17408
	ds_read_b128 v[190:193], v186 offset:18432
	ds_read_b128 v[194:197], v186 offset:19456
	ds_read_b128 v[198:201], v186 offset:20480
	ds_read_b128 v[202:205], v186 offset:21504
	ds_read_b128 v[206:209], v186 offset:22528
	ds_read_b128 v[210:213], v186 offset:23552
	buffer_load_dwordx4 v177, s[48:51], s62 offen lds
	s_mov_b32 m0, s11
	s_add_i32 s64, s62, 0x40000
	buffer_load_dwordx4 v179, s[48:51], s62 offen lds
	s_mov_b32 m0, s12
	s_nop 0
	buffer_load_dwordx4 v177, s[48:51], s64 offen lds
	s_mov_b32 m0, s13
	s_nop 0
	buffer_load_dwordx4 v179, s[48:51], s64 offen lds
	s_mov_b32 m0, s5
	s_nop 0
	buffer_load_dwordx4 v173, s[76:79], s63 offen lds
	s_mov_b32 m0, s14
	s_nop 0
	buffer_load_dwordx4 v178, s[76:79], s63 offen lds
	s_waitcnt vmcnt(8)
	s_waitcnt lgkmcnt(0)
	s_barrier
	s_setprio 1
	v_mfma_f32_16x16x32_bf16 v[62:65], v[130:133], v[162:165], v[62:65]
	v_mfma_f32_16x16x32_bf16 v[58:61], v[138:141], v[162:165], v[58:61]
	v_mfma_f32_16x16x32_bf16 v[54:57], v[130:133], v[190:193], v[54:57]
	v_mfma_f32_16x16x32_bf16 v[50:53], v[138:141], v[190:193], v[50:53]
	v_mfma_f32_16x16x32_bf16 v[46:49], v[130:133], v[198:201], v[46:49]
	v_mfma_f32_16x16x32_bf16 v[42:45], v[138:141], v[198:201], v[42:45]
	v_mfma_f32_16x16x32_bf16 v[38:41], v[130:133], v[206:209], v[38:41]
	v_mfma_f32_16x16x32_bf16 v[34:37], v[138:141], v[206:209], v[34:37]
	v_mfma_f32_16x16x32_bf16 v[62:65], v[134:137], v[166:169], v[62:65]
	v_mfma_f32_16x16x32_bf16 v[58:61], v[142:145], v[166:169], v[58:61]
	v_mfma_f32_16x16x32_bf16 v[54:57], v[134:137], v[194:197], v[54:57]
	v_mfma_f32_16x16x32_bf16 v[50:53], v[142:145], v[194:197], v[50:53]
	v_mfma_f32_16x16x32_bf16 v[46:49], v[134:137], v[202:205], v[46:49]
	v_mfma_f32_16x16x32_bf16 v[42:45], v[142:145], v[202:205], v[42:45]
	v_mfma_f32_16x16x32_bf16 v[38:41], v[134:137], v[210:213], v[38:41]
	v_mfma_f32_16x16x32_bf16 v[34:37], v[142:145], v[210:213], v[34:37]
	v_mfma_f32_16x16x32_bf16 v[30:33], v[146:149], v[162:165], v[30:33]
	v_mfma_f32_16x16x32_bf16 v[26:29], v[154:157], v[162:165], v[26:29]
	v_mfma_f32_16x16x32_bf16 v[22:25], v[146:149], v[190:193], v[22:25]
	v_mfma_f32_16x16x32_bf16 v[18:21], v[154:157], v[190:193], v[18:21]
	v_mfma_f32_16x16x32_bf16 v[14:17], v[146:149], v[198:201], v[14:17]
	v_mfma_f32_16x16x32_bf16 v[10:13], v[154:157], v[198:201], v[10:13]
	v_mfma_f32_16x16x32_bf16 v[6:9], v[146:149], v[206:209], v[6:9]
	v_mfma_f32_16x16x32_bf16 v[2:5], v[154:157], v[206:209], v[2:5]
	v_mfma_f32_16x16x32_bf16 v[30:33], v[150:153], v[166:169], v[30:33]
	v_mfma_f32_16x16x32_bf16 v[26:29], v[158:161], v[166:169], v[26:29]
	v_mfma_f32_16x16x32_bf16 v[22:25], v[150:153], v[194:197], v[22:25]
	v_mfma_f32_16x16x32_bf16 v[18:21], v[158:161], v[194:197], v[18:21]
	v_mfma_f32_16x16x32_bf16 v[14:17], v[150:153], v[202:205], v[14:17]
	v_mfma_f32_16x16x32_bf16 v[10:13], v[158:161], v[202:205], v[10:13]
	v_mfma_f32_16x16x32_bf16 v[6:9], v[150:153], v[210:213], v[6:9]
	v_mfma_f32_16x16x32_bf16 v[2:5], v[158:161], v[210:213], v[2:5]
	s_setprio 0
	s_barrier
; #define PG8_STAGEX(rs, bufoff, soff, voff) do { _Pragma("unroll") for (int _i = 0; _i < 2; ++_i) \
;         __builtin_amdgcn_raw_ptr_buffer_load_lds(rs, (LAS unsigned*)(lds + (bufoff) + ldsw + _i * 8192), 16, (voff)[_i], (soff), 0, 0); } while (0)
; #define PG8_LDA(dst, b, h) do { _Pragma("unroll") for (int m = 0; m < 4; ++m) _Pragma("unroll") for (int k = 0; k < 2; ++k) dst[m][k] = *(const LAS bf16x8*)(lds + PG8_SA(b, h) + aoff + m * 2048 + k * 1024); } while (0)
; #define PG8_LDB(dst, b, h) do { _Pragma("unroll") for (int n = 0; n < 2; ++n) _Pragma("unroll") for (int k = 0; k < 2; ++k) dst[n][k] = *(const LAS bf16x8*)(lds + PG8_SB(b, h) + boff + n * 2048 + k * 1024); } while (0)
; #define PG8_WAIT_V(n) asm volatile("s_waitcnt vmcnt(" #n ")" ::: "memory")
; #define PG8_WAIT_L(n) asm volatile("s_waitcnt lgkmcnt(" #n ")" ::: "memory")
; #define PG8_BAR __builtin_amdgcn_s_barrier()
; #define PG8_SCHED __builtin_amdgcn_sched_barrier(0)
;     ...
;             PG8_LDB(B0, 1, 0); PG8_LDB(B1, 1, 1); PG8_SCHED; PG8_LDA(At, 1, 0); PG8_STAGEX(rsA, PG8_SA(0, 1), a2 + hstepA, voffA);
;             PG8_WAIT_V(8); PG8_WAIT_L(0); PG8_BAR; PG8_MMA(0, 0, At, B0); PG8_MMA(0, 1, At, B1); PG8_BAR; PG8_SCHED;
;             PG8_LDA(At, 1, 1); PG8_STAGEX(rsB, PG8_SB(1, 0), b3, voffB); PG8_STAGEX(rsB, PG8_SB(1, 1), b3 + hstepB, voffB); PG8_STAGEX(rsA, PG8_SA(1, 0), a3, voffA);
;             PG8_WAIT_V(8); PG8_WAIT_L(0); PG8_BAR; PG8_MMA(1, 0, At, B0); PG8_MMA(1, 1, At, B1); PG8_BAR; PG8_SCHED;
;         }
	v_add_u32_e32 v142, 0x18000, v185
	v_add_u32_e32 v158, 0x1c000, v185
	ds_read_b128 v[130:133], v142
	ds_read_b128 v[134:137], v142 offset:1024
	ds_read_b128 v[138:141], v142 offset:2048
	ds_read_b128 v[142:145], v142 offset:3072
	ds_read_b128 v[146:149], v158
	ds_read_b128 v[150:153], v158 offset:1024
	ds_read_b128 v[154:157], v158 offset:2048
	ds_read_b128 v[158:161], v158 offset:3072
	s_add_i32 s63, s63, 0xc0000
	s_mov_b32 m0, s15
	ds_read_b128 v[162:165], v186 offset:32768
	ds_read_b128 v[166:169], v186 offset:33792
	ds_read_b128 v[190:193], v186 offset:34816
	ds_read_b128 v[194:197], v186 offset:35840
	ds_read_b128 v[198:201], v186 offset:36864
	ds_read_b128 v[202:205], v186 offset:37888
	ds_read_b128 v[206:209], v186 offset:38912
	ds_read_b128 v[210:213], v186 offset:39936
	buffer_load_dwordx4 v173, s[76:79], s63 offen lds
	s_mov_b32 m0, s16
	s_nop 0
	buffer_load_dwordx4 v178, s[76:79], s63 offen lds
	s_waitcnt vmcnt(8)
	s_waitcnt lgkmcnt(0)
	s_barrier
	s_setprio 1
	v_mfma_f32_16x16x32_bf16 v[126:129], v[130:133], v[162:165], v[126:129]
	v_mfma_f32_16x16x32_bf16 v[122:125], v[138:141], v[162:165], v[122:125]
	v_mfma_f32_16x16x32_bf16 v[118:121], v[130:133], v[190:193], v[118:121]
	v_mfma_f32_16x16x32_bf16 v[114:117], v[138:141], v[190:193], v[114:117]
	v_mfma_f32_16x16x32_bf16 v[110:113], v[130:133], v[198:201], v[110:113]
	v_mfma_f32_16x16x32_bf16 v[106:109], v[138:141], v[198:201], v[106:109]
	v_mfma_f32_16x16x32_bf16 v[102:105], v[130:133], v[206:209], v[102:105]
	v_mfma_f32_16x16x32_bf16 v[98:101], v[138:141], v[206:209], v[98:101]
	v_mfma_f32_16x16x32_bf16 v[126:129], v[134:137], v[166:169], v[126:129]
	v_mfma_f32_16x16x32_bf16 v[122:125], v[142:145], v[166:169], v[122:125]
	v_mfma_f32_16x16x32_bf16 v[118:121], v[134:137], v[194:197], v[118:121]
	v_mfma_f32_16x16x32_bf16 v[114:117], v[142:145], v[194:197], v[114:117]
	v_mfma_f32_16x16x32_bf16 v[110:113], v[134:137], v[202:205], v[110:113]
	v_mfma_f32_16x16x32_bf16 v[106:109], v[142:145], v[202:205], v[106:109]
	v_mfma_f32_16x16x32_bf16 v[102:105], v[134:137], v[210:213], v[102:105]
	v_mfma_f32_16x16x32_bf16 v[98:101], v[142:145], v[210:213], v[98:101]
	v_mfma_f32_16x16x32_bf16 v[94:97], v[146:149], v[162:165], v[94:97]
	v_mfma_f32_16x16x32_bf16 v[90:93], v[154:157], v[162:165], v[90:93]
	v_mfma_f32_16x16x32_bf16 v[86:89], v[146:149], v[190:193], v[86:89]
	v_mfma_f32_16x16x32_bf16 v[82:85], v[154:157], v[190:193], v[82:85]
	v_mfma_f32_16x16x32_bf16 v[78:81], v[146:149], v[198:201], v[78:81]
	v_mfma_f32_16x16x32_bf16 v[74:77], v[154:157], v[198:201], v[74:77]
	v_mfma_f32_16x16x32_bf16 v[70:73], v[146:149], v[206:209], v[70:73]
	v_mfma_f32_16x16x32_bf16 v[66:69], v[154:157], v[206:209], v[66:69]
	v_mfma_f32_16x16x32_bf16 v[94:97], v[150:153], v[166:169], v[94:97]
	v_mfma_f32_16x16x32_bf16 v[90:93], v[158:161], v[166:169], v[90:93]
	v_mfma_f32_16x16x32_bf16 v[86:89], v[150:153], v[194:197], v[86:89]
	v_mfma_f32_16x16x32_bf16 v[82:85], v[158:161], v[194:197], v[82:85]
	v_mfma_f32_16x16x32_bf16 v[78:81], v[150:153], v[202:205], v[78:81]
	v_mfma_f32_16x16x32_bf16 v[74:77], v[158:161], v[202:205], v[74:77]
	v_mfma_f32_16x16x32_bf16 v[70:73], v[150:153], v[210:213], v[70:73]
	v_mfma_f32_16x16x32_bf16 v[66:69], v[158:161], v[210:213], v[66:69]
	s_setprio 0
	s_barrier
	s_mov_b32 m0, s17
	s_add_i32 s63, s62, 0x80
	ds_read_b128 v[162:165], v186 offset:49152
	ds_read_b128 v[166:169], v186 offset:50176
	ds_read_b128 v[190:193], v186 offset:51200
	ds_read_b128 v[194:197], v186 offset:52224
	ds_read_b128 v[198:201], v186 offset:53248
	ds_read_b128 v[202:205], v186 offset:54272
	ds_read_b128 v[206:209], v186 offset:55296
	ds_read_b128 v[210:213], v186 offset:56320
	buffer_load_dwordx4 v177, s[48:51], s63 offen lds
	s_mov_b32 m0, s18
	s_add_i32 s62, s62, 0x40080
	buffer_load_dwordx4 v179, s[48:51], s63 offen lds
	s_mov_b32 m0, s21
	s_nop 0
	buffer_load_dwordx4 v177, s[48:51], s62 offen lds
	s_mov_b32 m0, s22
	s_nop 0
	buffer_load_dwordx4 v179, s[48:51], s62 offen lds
	s_mov_b32 m0, s19
	s_nop 0
	buffer_load_dwordx4 v173, s[76:79], s61 offen lds
	s_mov_b32 m0, s20
	s_nop 0
	buffer_load_dwordx4 v178, s[76:79], s61 offen lds
	s_waitcnt vmcnt(8)
	s_waitcnt lgkmcnt(0)
	s_barrier
	s_setprio 1
	v_mfma_f32_16x16x32_bf16 v[62:65], v[130:133], v[162:165], v[62:65]
	v_mfma_f32_16x16x32_bf16 v[58:61], v[138:141], v[162:165], v[58:61]
	v_mfma_f32_16x16x32_bf16 v[54:57], v[130:133], v[190:193], v[54:57]
	v_mfma_f32_16x16x32_bf16 v[50:53], v[138:141], v[190:193], v[50:53]
	v_mfma_f32_16x16x32_bf16 v[46:49], v[130:133], v[198:201], v[46:49]
	v_mfma_f32_16x16x32_bf16 v[42:45], v[138:141], v[198:201], v[42:45]
	v_mfma_f32_16x16x32_bf16 v[38:41], v[130:133], v[206:209], v[38:41]
	v_mfma_f32_16x16x32_bf16 v[34:37], v[138:141], v[206:209], v[34:37]
	v_mfma_f32_16x16x32_bf16 v[62:65], v[134:137], v[166:169], v[62:65]
	v_mfma_f32_16x16x32_bf16 v[58:61], v[142:145], v[166:169], v[58:61]
	v_mfma_f32_16x16x32_bf16 v[54:57], v[134:137], v[194:197], v[54:57]
	v_mfma_f32_16x16x32_bf16 v[50:53], v[142:145], v[194:197], v[50:53]
	v_mfma_f32_16x16x32_bf16 v[46:49], v[134:137], v[202:205], v[46:49]
	v_mfma_f32_16x16x32_bf16 v[42:45], v[142:145], v[202:205], v[42:45]
	v_mfma_f32_16x16x32_bf16 v[38:41], v[134:137], v[210:213], v[38:41]
	v_mfma_f32_16x16x32_bf16 v[34:37], v[142:145], v[210:213], v[34:37]
	v_mfma_f32_16x16x32_bf16 v[30:33], v[146:149], v[162:165], v[30:33]
	v_mfma_f32_16x16x32_bf16 v[26:29], v[154:157], v[162:165], v[26:29]
	v_mfma_f32_16x16x32_bf16 v[22:25], v[146:149], v[190:193], v[22:25]
	v_mfma_f32_16x16x32_bf16 v[18:21], v[154:157], v[190:193], v[18:21]
	v_mfma_f32_16x16x32_bf16 v[14:17], v[146:149], v[198:201], v[14:17]
	v_mfma_f32_16x16x32_bf16 v[10:13], v[154:157], v[198:201], v[10:13]
	v_mfma_f32_16x16x32_bf16 v[6:9], v[146:149], v[206:209], v[6:9]
	v_mfma_f32_16x16x32_bf16 v[2:5], v[154:157], v[206:209], v[2:5]
	v_mfma_f32_16x16x32_bf16 v[30:33], v[150:153], v[166:169], v[30:33]
	v_mfma_f32_16x16x32_bf16 v[26:29], v[158:161], v[166:169], v[26:29]
	v_mfma_f32_16x16x32_bf16 v[22:25], v[150:153], v[194:197], v[22:25]
	v_mfma_f32_16x16x32_bf16 v[18:21], v[158:161], v[194:197], v[18:21]
	v_mfma_f32_16x16x32_bf16 v[14:17], v[150:153], v[202:205], v[14:17]
	v_mfma_f32_16x16x32_bf16 v[10:13], v[158:161], v[202:205], v[10:13]
	v_mfma_f32_16x16x32_bf16 v[6:9], v[150:153], v[210:213], v[6:9]
	v_mfma_f32_16x16x32_bf16 v[2:5], v[158:161], v[210:213], v[2:5]
	s_setprio 0
	s_barrier
	s_add_i32 s60, s60, 2
	s_addk_i32 s43, 0x100
	s_addk_i32 s59, 0x100
	s_cmp_gt_u32 s60, 13
	s_cbranch_scc0 .LBB0_1377
	s_and_b64 vcc, exec, s[52:53]
	s_cbranch_vccz .LBB0_1380
	s_barrier

; #define PG8_STAGEX(rs, bufoff, soff, voff) do { _Pragma("unroll") for (int _i = 0; _i < 2; ++_i) \
;         __builtin_amdgcn_raw_ptr_buffer_load_lds(rs, (LAS unsigned*)(lds + (bufoff) + ldsw + _i * 8192), 16, (voff)[_i], (soff), 0, 0); } while (0)
; #define PG8_LDA(dst, b, h) do { _Pragma("unroll") for (int m = 0; m < 4; ++m) _Pragma("unroll") for (int k = 0; k < 2; ++k) dst[m][k] = *(const LAS bf16x8*)(lds + PG8_SA(b, h) + aoff + m * 2048 + k * 1024); } while (0)
; #define PG8_LDB(dst, b, h) do { _Pragma("unroll") for (int n = 0; n < 2; ++n) _Pragma("unroll") for (int k = 0; k < 2; ++k) dst[n][k] = *(const LAS bf16x8*)(lds + PG8_SB(b, h) + boff + n * 2048 + k * 1024); } while (0)
; #define PG8_WAIT_V(n) asm volatile("s_waitcnt vmcnt(" #n ")" ::: "memory")
; #define PG8_WAIT_L(n) asm volatile("s_waitcnt lgkmcnt(" #n ")" ::: "memory")
; #define PG8_BAR __builtin_amdgcn_s_barrier()
; #define PG8_SCHED __builtin_amdgcn_sched_barrier(0)
;     ...
;                 if (w0) { PG8_LDB(B0, 0, 0); PG8_LDB(B1, 0, 1); PG8_SCHED; PG8_LDA(At, 0, 0); }
;                 PG8_WAIT_L(0); PG8_BAR; if (w0) { PG8_MMA(0, 0, At, B0); PG8_MMA(0, 1, At, B1); } PG8_BAR; PG8_SCHED;
;                 PG8_STAGEX(rsB, PG8_SB(0, 0), b2, voffB); PG8_STAGEX(rsB, PG8_SB(0, 1), b2 + hstepB, voffB); PG8_STAGEX(rsA, PG8_SA(0, 0), a2, voffA);
;                 PG8_WAIT_V(6); PG8_BAR; PG8_BAR; PG8_SCHED;
.LBB0_1429:
	v_add_u32_e32 v78, 0x10000, v95
	v_add_u32_e32 v86, 0x14000, v95
	ds_read_b128 v[66:69], v78
	ds_read_b128 v[70:73], v78 offset:1024
	ds_read_b128 v[74:77], v78 offset:2048
	ds_read_b128 v[78:81], v78 offset:3072
	ds_read_b128 v[82:85], v86
	ds_read_b128 v[100:103], v86 offset:1024
	ds_read_b128 v[104:107], v86 offset:2048
	ds_read_b128 v[108:111], v86 offset:3072
	s_cmp_eq_u32 s40, 12
	s_cselect_b32 s41, s38, s39
	s_cselect_b32 s46, s30, s31
	s_add_i32 s47, s41, 0x80
	ds_read_b128 v[112:115], v96
	ds_read_b128 v[116:119], v96 offset:1024
	ds_read_b128 v[120:123], v96 offset:2048
	ds_read_b128 v[124:127], v96 offset:3072
	ds_read_b128 v[128:131], v96 offset:4096
	ds_read_b128 v[132:135], v96 offset:5120
	ds_read_b128 v[136:139], v96 offset:6144
	ds_read_b128 v[140:143], v96 offset:7168
	s_waitcnt lgkmcnt(0)
	s_barrier
	s_setprio 1
	v_mfma_f32_16x16x32_bf16 v[62:65], v[66:69], v[112:115], v[62:65]
	v_mfma_f32_16x16x32_bf16 v[58:61], v[74:77], v[112:115], v[58:61]
	v_mfma_f32_16x16x32_bf16 v[54:57], v[66:69], v[120:123], v[54:57]
	v_mfma_f32_16x16x32_bf16 v[50:53], v[74:77], v[120:123], v[50:53]
	v_mfma_f32_16x16x32_bf16 v[46:49], v[66:69], v[128:131], v[46:49]
	v_mfma_f32_16x16x32_bf16 v[42:45], v[74:77], v[128:131], v[42:45]
	v_mfma_f32_16x16x32_bf16 v[38:41], v[66:69], v[136:139], v[38:41]
	v_mfma_f32_16x16x32_bf16 v[34:37], v[74:77], v[136:139], v[34:37]
	v_mfma_f32_16x16x32_bf16 v[62:65], v[70:73], v[116:119], v[62:65]
	v_mfma_f32_16x16x32_bf16 v[58:61], v[78:81], v[116:119], v[58:61]
	v_mfma_f32_16x16x32_bf16 v[54:57], v[70:73], v[124:127], v[54:57]
	v_mfma_f32_16x16x32_bf16 v[50:53], v[78:81], v[124:127], v[50:53]
	v_mfma_f32_16x16x32_bf16 v[46:49], v[70:73], v[132:135], v[46:49]
	v_mfma_f32_16x16x32_bf16 v[42:45], v[78:81], v[132:135], v[42:45]
	v_mfma_f32_16x16x32_bf16 v[38:41], v[70:73], v[140:143], v[38:41]
	v_mfma_f32_16x16x32_bf16 v[34:37], v[78:81], v[140:143], v[34:37]
	v_mfma_f32_16x16x32_bf16 v[30:33], v[82:85], v[112:115], v[30:33]
	v_mfma_f32_16x16x32_bf16 v[26:29], v[104:107], v[112:115], v[26:29]
	v_mfma_f32_16x16x32_bf16 v[22:25], v[82:85], v[120:123], v[22:25]
	v_mfma_f32_16x16x32_bf16 v[18:21], v[104:107], v[120:123], v[18:21]
	v_mfma_f32_16x16x32_bf16 v[14:17], v[82:85], v[128:131], v[14:17]
	v_mfma_f32_16x16x32_bf16 v[10:13], v[104:107], v[128:131], v[10:13]
	v_mfma_f32_16x16x32_bf16 v[6:9], v[82:85], v[136:139], v[6:9]
	v_mfma_f32_16x16x32_bf16 v[2:5], v[104:107], v[136:139], v[2:5]
	v_mfma_f32_16x16x32_bf16 v[30:33], v[100:103], v[116:119], v[30:33]
	v_mfma_f32_16x16x32_bf16 v[26:29], v[108:111], v[116:119], v[26:29]
	v_mfma_f32_16x16x32_bf16 v[22:25], v[100:103], v[124:127], v[22:25]
	v_mfma_f32_16x16x32_bf16 v[18:21], v[108:111], v[124:127], v[18:21]
	v_mfma_f32_16x16x32_bf16 v[14:17], v[100:103], v[132:135], v[14:17]
	v_mfma_f32_16x16x32_bf16 v[10:13], v[108:111], v[132:135], v[10:13]
	v_mfma_f32_16x16x32_bf16 v[6:9], v[100:103], v[140:143], v[6:9]
	v_mfma_f32_16x16x32_bf16 v[2:5], v[108:111], v[140:143], v[2:5]
	s_setprio 0
	s_barrier
	s_mov_b32 m0, s5
	s_mov_b32 s50, s78
	s_mov_b32 s51, s79
	buffer_load_dwordx4 v89, s[48:51], s46 offen lds
	s_mov_b32 m0, s7
	s_add_i32 s52, s46, 0x40000
	buffer_load_dwordx4 v91, s[48:51], s46 offen lds
	s_mov_b32 m0, s11
	s_nop 0
	buffer_load_dwordx4 v89, s[48:51], s52 offen lds
	s_mov_b32 m0, s12
	s_nop 0
	buffer_load_dwordx4 v91, s[48:51], s52 offen lds
	s_mov_b32 m0, s3
	s_nop 0
	buffer_load_dwordx4 v88, s[76:79], s41 offen lds
	s_mov_b32 m0, s13
	s_nop 0
	buffer_load_dwordx4 v90, s[76:79], s41 offen lds
	s_waitcnt vmcnt(6)
	s_barrier
	s_barrier
; #define PG8_STAGEX(rs, bufoff, soff, voff) do { _Pragma("unroll") for (int _i = 0; _i < 2; ++_i) \
;         __builtin_amdgcn_raw_ptr_buffer_load_lds(rs, (LAS unsigned*)(lds + (bufoff) + ldsw + _i * 8192), 16, (voff)[_i], (soff), 0, 0); } while (0)
; #define PG8_LDA(dst, b, h) do { _Pragma("unroll") for (int m = 0; m < 4; ++m) _Pragma("unroll") for (int k = 0; k < 2; ++k) dst[m][k] = *(const LAS bf16x8*)(lds + PG8_SA(b, h) + aoff + m * 2048 + k * 1024); } while (0)
; #define PG8_LDB(dst, b, h) do { _Pragma("unroll") for (int n = 0; n < 2; ++n) _Pragma("unroll") for (int k = 0; k < 2; ++k) dst[n][k] = *(const LAS bf16x8*)(lds + PG8_SB(b, h) + boff + n * 2048 + k * 1024); } while (0)
; #define PG8_WAIT_V(n) asm volatile("s_waitcnt vmcnt(" #n ")" ::: "memory")
; #define PG8_WAIT_L(n) asm volatile("s_waitcnt lgkmcnt(" #n ")" ::: "memory")
; #define PG8_BAR __builtin_amdgcn_s_barrier()
; #define PG8_SCHED __builtin_amdgcn_sched_barrier(0)
;     ...
;                 if (w0) { PG8_LDB(B0, 1, 0); PG8_LDB(B1, 1, 1); PG8_SCHED; PG8_LDA(At, 1, 0); }
;                 PG8_WAIT_L(0); PG8_BAR; if (w0) { PG8_MMA(0, 0, At, B0); PG8_MMA(0, 1, At, B1); } PG8_BAR; PG8_SCHED;
;                 PG8_STAGEX(rsB, PG8_SB(1, 0), b3, voffB); PG8_STAGEX(rsB, PG8_SB(1, 1), b3 + hstepB, voffB); PG8_STAGEX(rsA, PG8_SA(1, 0), a3, voffA);
;                 PG8_WAIT_V(6); PG8_BAR; PG8_BAR; PG8_SCHED;
;             }
	v_add_u32_e32 v78, 0x18000, v95
	v_add_u32_e32 v86, 0x1c000, v95
	ds_read_b128 v[66:69], v78
	ds_read_b128 v[70:73], v78 offset:1024
	ds_read_b128 v[74:77], v78 offset:2048
	ds_read_b128 v[78:81], v78 offset:3072
	ds_read_b128 v[82:85], v86
	ds_read_b128 v[100:103], v86 offset:1024
	ds_read_b128 v[104:107], v86 offset:2048
	ds_read_b128 v[108:111], v86 offset:3072
	ds_read_b128 v[112:115], v96 offset:32768
	ds_read_b128 v[116:119], v96 offset:33792
	ds_read_b128 v[120:123], v96 offset:34816
	ds_read_b128 v[124:127], v96 offset:35840
	ds_read_b128 v[128:131], v96 offset:36864
	ds_read_b128 v[132:135], v96 offset:37888
	ds_read_b128 v[136:139], v96 offset:38912
	ds_read_b128 v[140:143], v96 offset:39936
	s_waitcnt lgkmcnt(0)
	s_barrier
	s_setprio 1
	v_mfma_f32_16x16x32_bf16 v[62:65], v[66:69], v[112:115], v[62:65]
	v_mfma_f32_16x16x32_bf16 v[58:61], v[74:77], v[112:115], v[58:61]
	v_mfma_f32_16x16x32_bf16 v[54:57], v[66:69], v[120:123], v[54:57]
	v_mfma_f32_16x16x32_bf16 v[50:53], v[74:77], v[120:123], v[50:53]
	v_mfma_f32_16x16x32_bf16 v[46:49], v[66:69], v[128:131], v[46:49]
	v_mfma_f32_16x16x32_bf16 v[42:45], v[74:77], v[128:131], v[42:45]
	v_mfma_f32_16x16x32_bf16 v[38:41], v[66:69], v[136:139], v[38:41]
	v_mfma_f32_16x16x32_bf16 v[34:37], v[74:77], v[136:139], v[34:37]
	v_mfma_f32_16x16x32_bf16 v[62:65], v[70:73], v[116:119], v[62:65]
	v_mfma_f32_16x16x32_bf16 v[58:61], v[78:81], v[116:119], v[58:61]
	v_mfma_f32_16x16x32_bf16 v[54:57], v[70:73], v[124:127], v[54:57]
	v_mfma_f32_16x16x32_bf16 v[50:53], v[78:81], v[124:127], v[50:53]
	v_mfma_f32_16x16x32_bf16 v[46:49], v[70:73], v[132:135], v[46:49]
	v_mfma_f32_16x16x32_bf16 v[42:45], v[78:81], v[132:135], v[42:45]
	v_mfma_f32_16x16x32_bf16 v[38:41], v[70:73], v[140:143], v[38:41]
	v_mfma_f32_16x16x32_bf16 v[34:37], v[78:81], v[140:143], v[34:37]
	v_mfma_f32_16x16x32_bf16 v[30:33], v[82:85], v[112:115], v[30:33]
	s_add_i32 s41, s46, 0x80
	v_mfma_f32_16x16x32_bf16 v[26:29], v[104:107], v[112:115], v[26:29]
	v_mfma_f32_16x16x32_bf16 v[22:25], v[82:85], v[120:123], v[22:25]
	v_mfma_f32_16x16x32_bf16 v[18:21], v[104:107], v[120:123], v[18:21]
	v_mfma_f32_16x16x32_bf16 v[14:17], v[82:85], v[128:131], v[14:17]
	v_mfma_f32_16x16x32_bf16 v[10:13], v[104:107], v[128:131], v[10:13]
	v_mfma_f32_16x16x32_bf16 v[6:9], v[82:85], v[136:139], v[6:9]
	v_mfma_f32_16x16x32_bf16 v[2:5], v[104:107], v[136:139], v[2:5]
	v_mfma_f32_16x16x32_bf16 v[30:33], v[100:103], v[116:119], v[30:33]
	v_mfma_f32_16x16x32_bf16 v[26:29], v[108:111], v[116:119], v[26:29]
	v_mfma_f32_16x16x32_bf16 v[22:25], v[100:103], v[124:127], v[22:25]
	v_mfma_f32_16x16x32_bf16 v[18:21], v[108:111], v[124:127], v[18:21]
	v_mfma_f32_16x16x32_bf16 v[14:17], v[100:103], v[132:135], v[14:17]
	v_mfma_f32_16x16x32_bf16 v[10:13], v[108:111], v[132:135], v[10:13]
	v_mfma_f32_16x16x32_bf16 v[6:9], v[100:103], v[140:143], v[6:9]
	v_mfma_f32_16x16x32_bf16 v[2:5], v[108:111], v[140:143], v[2:5]
	s_setprio 0
	s_barrier
	s_mov_b32 m0, s14
	s_add_i32 s46, s46, 0x40080
	buffer_load_dwordx4 v89, s[48:51], s41 offen lds
	s_mov_b32 m0, s15
	s_nop 0
	buffer_load_dwordx4 v91, s[48:51], s41 offen lds
	s_mov_b32 m0, s18
	s_nop 0
	buffer_load_dwordx4 v89, s[48:51], s46 offen lds
	s_mov_b32 m0, s19
	s_nop 0
	buffer_load_dwordx4 v91, s[48:51], s46 offen lds
	s_mov_b32 m0, s16
	s_nop 0
	buffer_load_dwordx4 v88, s[76:79], s47 offen lds
	s_mov_b32 m0, s17
	s_nop 0
	buffer_load_dwordx4 v90, s[76:79], s47 offen lds
	s_waitcnt vmcnt(6)
	s_barrier
	s_barrier
	s_add_i32 s40, s40, 2
	s_addk_i32 s31, 0x100
	s_addk_i32 s39, 0x100
	s_cmp_gt_u32 s40, 13
	s_cbranch_scc0 .LBB0_1429
	s_and_b64 vcc, exec, s[42:43]
	s_cbranch_vccz .LBB0_1432
	s_barrier

; #define PG8_STAGEX(rs, bufoff, soff, voff) do { _Pragma("unroll") for (int _i = 0; _i < 2; ++_i) \
;         __builtin_amdgcn_raw_ptr_buffer_load_lds(rs, (LAS unsigned*)(lds + (bufoff) + ldsw + _i * 8192), 16, (voff)[_i], (soff), 0, 0); } while (0)
; #define PG8_LDA(dst, b, h) do { _Pragma("unroll") for (int m = 0; m < 4; ++m) _Pragma("unroll") for (int k = 0; k < 2; ++k) dst[m][k] = *(const LAS bf16x8*)(lds + PG8_SA(b, h) + aoff + m * 2048 + k * 1024); } while (0)
; #define PG8_LDB(dst, b, h) do { _Pragma("unroll") for (int n = 0; n < 2; ++n) _Pragma("unroll") for (int k = 0; k < 2; ++k) dst[n][k] = *(const LAS bf16x8*)(lds + PG8_SB(b, h) + boff + n * 2048 + k * 1024); } while (0)
; #define PG8_WAIT_V(n) asm volatile("s_waitcnt vmcnt(" #n ")" ::: "memory")
; #define PG8_WAIT_L(n) asm volatile("s_waitcnt lgkmcnt(" #n ")" ::: "memory")
; #define PG8_BAR __builtin_amdgcn_s_barrier()
; #define PG8_SCHED __builtin_amdgcn_sched_barrier(0)
;     ...
;             PG8_LDB(B0, 0, 0); PG8_LDB(B1, 0, 1); PG8_SCHED; PG8_LDA(At, 0, 0); PG8_STAGEX(rsA, PG8_SA(1, 1), a1 + hstepA, voffA);
;             PG8_WAIT_V(8); PG8_WAIT_L(0); PG8_BAR; PG8_MMA(0, 0, At, B0); PG8_MMA(0, 1, At, B1); PG8_BAR; PG8_SCHED;
;             PG8_LDA(At, 0, 1); PG8_STAGEX(rsB, PG8_SB(0, 0), b2, voffB); PG8_STAGEX(rsB, PG8_SB(0, 1), b2 + hstepB, voffB); PG8_STAGEX(rsA, PG8_SA(0, 0), a2, voffA);
;             PG8_WAIT_V(8); PG8_WAIT_L(0); PG8_BAR; PG8_MMA(1, 0, At, B0); PG8_MMA(1, 1, At, B1); PG8_BAR; PG8_SCHED;
.LBB0_1529:
	v_add_u32_e32 v118, 0x10000, v210
	v_add_u32_e32 v142, 0x14000, v210
	ds_read_b128 v[106:109], v118
	ds_read_b128 v[110:113], v118 offset:1024
	ds_read_b128 v[114:117], v118 offset:2048
	ds_read_b128 v[118:121], v118 offset:3072
	ds_read_b128 v[122:125], v142
	ds_read_b128 v[126:129], v142 offset:1024
	ds_read_b128 v[130:133], v142 offset:2048
	ds_read_b128 v[142:145], v142 offset:3072
	s_add_i32 s46, s59, 0xfff80080
	s_cmp_eq_u32 s64, 28
	s_cselect_b32 s67, s30, s46
	s_cselect_b32 s66, s31, s63
	s_or_b32 s65, s67, 0x80
	s_mov_b32 m0, s76
	ds_read_b128 v[164:167], v211
	ds_read_b128 v[168:171], v211 offset:1024
	ds_read_b128 v[182:185], v211 offset:2048
	ds_read_b128 v[186:189], v211 offset:3072
	ds_read_b128 v[190:193], v211 offset:4096
	ds_read_b128 v[194:197], v211 offset:5120
	ds_read_b128 v[198:201], v211 offset:6144
	ds_read_b128 v[202:205], v211 offset:7168
	buffer_load_dwordx4 v178, s[40:43], s59 offen lds
	s_mov_b32 m0, s77
	s_nop 0
	buffer_load_dwordx4 v206, s[40:43], s59 offen lds
	s_waitcnt vmcnt(8)
	s_waitcnt lgkmcnt(0)
	s_barrier
	s_setprio 1
	v_mfma_f32_16x16x32_bf16 v[158:161], v[106:109], v[164:167], v[158:161]
	v_mfma_f32_16x16x32_bf16 v[154:157], v[114:117], v[164:167], v[154:157]
	v_mfma_f32_16x16x32_bf16 v[150:153], v[106:109], v[182:185], v[150:153]
	v_mfma_f32_16x16x32_bf16 v[146:149], v[114:117], v[182:185], v[146:149]
	v_mfma_f32_16x16x32_bf16 v[138:141], v[106:109], v[190:193], v[138:141]
	v_mfma_f32_16x16x32_bf16 v[134:137], v[114:117], v[190:193], v[134:137]
	v_mfma_f32_16x16x32_bf16 v[102:105], v[106:109], v[198:201], v[102:105]
	v_mfma_f32_16x16x32_bf16 v[98:101], v[114:117], v[198:201], v[98:101]
	v_mfma_f32_16x16x32_bf16 v[158:161], v[110:113], v[168:171], v[158:161]
	v_mfma_f32_16x16x32_bf16 v[154:157], v[118:121], v[168:171], v[154:157]
	v_mfma_f32_16x16x32_bf16 v[150:153], v[110:113], v[186:189], v[150:153]
	v_mfma_f32_16x16x32_bf16 v[146:149], v[118:121], v[186:189], v[146:149]
	v_mfma_f32_16x16x32_bf16 v[138:141], v[110:113], v[194:197], v[138:141]
	v_mfma_f32_16x16x32_bf16 v[134:137], v[118:121], v[194:197], v[134:137]
	v_mfma_f32_16x16x32_bf16 v[102:105], v[110:113], v[202:205], v[102:105]
	v_mfma_f32_16x16x32_bf16 v[98:101], v[118:121], v[202:205], v[98:101]
	v_mfma_f32_16x16x32_bf16 v[62:65], v[122:125], v[164:167], v[62:65]
	v_mfma_f32_16x16x32_bf16 v[58:61], v[130:133], v[164:167], v[58:61]
	v_mfma_f32_16x16x32_bf16 v[54:57], v[122:125], v[182:185], v[54:57]
	v_mfma_f32_16x16x32_bf16 v[50:53], v[130:133], v[182:185], v[50:53]
	v_mfma_f32_16x16x32_bf16 v[46:49], v[122:125], v[190:193], v[46:49]
	v_mfma_f32_16x16x32_bf16 v[42:45], v[130:133], v[190:193], v[42:45]
	v_mfma_f32_16x16x32_bf16 v[38:41], v[122:125], v[198:201], v[38:41]
	v_mfma_f32_16x16x32_bf16 v[34:37], v[130:133], v[198:201], v[34:37]
	v_mfma_f32_16x16x32_bf16 v[62:65], v[126:129], v[168:171], v[62:65]
	v_mfma_f32_16x16x32_bf16 v[58:61], v[142:145], v[168:171], v[58:61]
	v_mfma_f32_16x16x32_bf16 v[54:57], v[126:129], v[186:189], v[54:57]
	v_mfma_f32_16x16x32_bf16 v[50:53], v[142:145], v[186:189], v[50:53]
	v_mfma_f32_16x16x32_bf16 v[46:49], v[126:129], v[194:197], v[46:49]
	v_mfma_f32_16x16x32_bf16 v[42:45], v[142:145], v[194:197], v[42:45]
	v_mfma_f32_16x16x32_bf16 v[38:41], v[126:129], v[202:205], v[38:41]
	v_mfma_f32_16x16x32_bf16 v[34:37], v[142:145], v[202:205], v[34:37]
	s_setprio 0
	s_barrier
	s_mov_b32 m0, s17
	s_mov_b32 s46, s42
	s_mov_b32 s47, s43
	ds_read_b128 v[164:167], v211 offset:16384
	ds_read_b128 v[168:171], v211 offset:17408
	ds_read_b128 v[182:185], v211 offset:18432
	ds_read_b128 v[186:189], v211 offset:19456
	ds_read_b128 v[190:193], v211 offset:20480
	ds_read_b128 v[194:197], v211 offset:21504
	ds_read_b128 v[198:201], v211 offset:22528
	ds_read_b128 v[202:205], v211 offset:23552
	buffer_load_dwordx4 v179, s[44:47], s66 offen lds
	s_mov_b32 m0, s18
	s_add_i32 s68, s66, 0x80000
	buffer_load_dwordx4 v207, s[44:47], s66 offen lds
	s_mov_b32 m0, s19
	s_nop 0
	buffer_load_dwordx4 v179, s[44:47], s68 offen lds
	s_mov_b32 m0, s20
	s_nop 0
	buffer_load_dwordx4 v207, s[44:47], s68 offen lds
	s_mov_b32 m0, s16
	s_nop 0
	buffer_load_dwordx4 v178, s[40:43], s67 offen lds
	s_mov_b32 m0, s21
	s_nop 0
	buffer_load_dwordx4 v206, s[40:43], s67 offen lds
	s_waitcnt vmcnt(8)
	s_waitcnt lgkmcnt(0)
	s_barrier
	s_setprio 1
	v_mfma_f32_16x16x32_bf16 v[94:97], v[106:109], v[164:167], v[94:97]
	v_mfma_f32_16x16x32_bf16 v[90:93], v[114:117], v[164:167], v[90:93]
	v_mfma_f32_16x16x32_bf16 v[86:89], v[106:109], v[182:185], v[86:89]
	v_mfma_f32_16x16x32_bf16 v[82:85], v[114:117], v[182:185], v[82:85]
	v_mfma_f32_16x16x32_bf16 v[78:81], v[106:109], v[190:193], v[78:81]
	v_mfma_f32_16x16x32_bf16 v[74:77], v[114:117], v[190:193], v[74:77]
	v_mfma_f32_16x16x32_bf16 v[70:73], v[106:109], v[198:201], v[70:73]
	v_mfma_f32_16x16x32_bf16 v[66:69], v[114:117], v[198:201], v[66:69]
	v_mfma_f32_16x16x32_bf16 v[94:97], v[110:113], v[168:171], v[94:97]
	v_mfma_f32_16x16x32_bf16 v[90:93], v[118:121], v[168:171], v[90:93]
	v_mfma_f32_16x16x32_bf16 v[86:89], v[110:113], v[186:189], v[86:89]
	v_mfma_f32_16x16x32_bf16 v[82:85], v[118:121], v[186:189], v[82:85]
	v_mfma_f32_16x16x32_bf16 v[78:81], v[110:113], v[194:197], v[78:81]
	v_mfma_f32_16x16x32_bf16 v[74:77], v[118:121], v[194:197], v[74:77]
	v_mfma_f32_16x16x32_bf16 v[70:73], v[110:113], v[202:205], v[70:73]
	v_mfma_f32_16x16x32_bf16 v[66:69], v[118:121], v[202:205], v[66:69]
	v_mfma_f32_16x16x32_bf16 v[30:33], v[122:125], v[164:167], v[30:33]
	v_mfma_f32_16x16x32_bf16 v[26:29], v[130:133], v[164:167], v[26:29]
	v_mfma_f32_16x16x32_bf16 v[22:25], v[122:125], v[182:185], v[22:25]
	v_mfma_f32_16x16x32_bf16 v[18:21], v[130:133], v[182:185], v[18:21]
	v_mfma_f32_16x16x32_bf16 v[14:17], v[122:125], v[190:193], v[14:17]
	v_mfma_f32_16x16x32_bf16 v[10:13], v[130:133], v[190:193], v[10:13]
	v_mfma_f32_16x16x32_bf16 v[6:9], v[122:125], v[198:201], v[6:9]
	v_mfma_f32_16x16x32_bf16 v[2:5], v[130:133], v[198:201], v[2:5]
	v_mfma_f32_16x16x32_bf16 v[30:33], v[126:129], v[168:171], v[30:33]
	v_mfma_f32_16x16x32_bf16 v[26:29], v[142:145], v[168:171], v[26:29]
	v_mfma_f32_16x16x32_bf16 v[22:25], v[126:129], v[186:189], v[22:25]
	v_mfma_f32_16x16x32_bf16 v[18:21], v[142:145], v[186:189], v[18:21]
	v_mfma_f32_16x16x32_bf16 v[14:17], v[126:129], v[194:197], v[14:17]
	v_mfma_f32_16x16x32_bf16 v[10:13], v[142:145], v[194:197], v[10:13]
	v_mfma_f32_16x16x32_bf16 v[6:9], v[126:129], v[202:205], v[6:9]
	v_mfma_f32_16x16x32_bf16 v[2:5], v[142:145], v[202:205], v[2:5]
	s_setprio 0
	s_barrier
; #define PG8_STAGEX(rs, bufoff, soff, voff) do { _Pragma("unroll") for (int _i = 0; _i < 2; ++_i) \
;         __builtin_amdgcn_raw_ptr_buffer_load_lds(rs, (LAS unsigned*)(lds + (bufoff) + ldsw + _i * 8192), 16, (voff)[_i], (soff), 0, 0); } while (0)
; #define PG8_LDA(dst, b, h) do { _Pragma("unroll") for (int m = 0; m < 4; ++m) _Pragma("unroll") for (int k = 0; k < 2; ++k) dst[m][k] = *(const LAS bf16x8*)(lds + PG8_SA(b, h) + aoff + m * 2048 + k * 1024); } while (0)
; #define PG8_LDB(dst, b, h) do { _Pragma("unroll") for (int n = 0; n < 2; ++n) _Pragma("unroll") for (int k = 0; k < 2; ++k) dst[n][k] = *(const LAS bf16x8*)(lds + PG8_SB(b, h) + boff + n * 2048 + k * 1024); } while (0)
; #define PG8_WAIT_V(n) asm volatile("s_waitcnt vmcnt(" #n ")" ::: "memory")
; #define PG8_WAIT_L(n) asm volatile("s_waitcnt lgkmcnt(" #n ")" ::: "memory")
; #define PG8_BAR __builtin_amdgcn_s_barrier()
; #define PG8_SCHED __builtin_amdgcn_sched_barrier(0)
;     ...
;             PG8_LDB(B0, 1, 0); PG8_LDB(B1, 1, 1); PG8_SCHED; PG8_LDA(At, 1, 0); PG8_STAGEX(rsA, PG8_SA(0, 1), a2 + hstepA, voffA);
;             PG8_WAIT_V(8); PG8_WAIT_L(0); PG8_BAR; PG8_MMA(0, 0, At, B0); PG8_MMA(0, 1, At, B1); PG8_BAR; PG8_SCHED;
;             PG8_LDA(At, 1, 1); PG8_STAGEX(rsB, PG8_SB(1, 0), b3, voffB); PG8_STAGEX(rsB, PG8_SB(1, 1), b3 + hstepB, voffB); PG8_STAGEX(rsA, PG8_SA(1, 0), a3, voffA);
;             PG8_WAIT_V(8); PG8_WAIT_L(0); PG8_BAR; PG8_MMA(1, 0, At, B0); PG8_MMA(1, 1, At, B1); PG8_BAR; PG8_SCHED;
;         }
	v_add_u32_e32 v118, 0x18000, v210
	v_add_u32_e32 v142, 0x1c000, v210
	ds_read_b128 v[106:109], v118
	ds_read_b128 v[110:113], v118 offset:1024
	ds_read_b128 v[114:117], v118 offset:2048
	ds_read_b128 v[118:121], v118 offset:3072
	ds_read_b128 v[122:125], v142
	ds_read_b128 v[126:129], v142 offset:1024
	ds_read_b128 v[130:133], v142 offset:2048
	ds_read_b128 v[142:145], v142 offset:3072
	s_add_i32 s67, s67, 0x80000
	s_mov_b32 m0, s22
	ds_read_b128 v[164:167], v211 offset:32768
	ds_read_b128 v[168:171], v211 offset:33792
	ds_read_b128 v[182:185], v211 offset:34816
	ds_read_b128 v[186:189], v211 offset:35840
	ds_read_b128 v[190:193], v211 offset:36864
	ds_read_b128 v[194:197], v211 offset:37888
	ds_read_b128 v[198:201], v211 offset:38912
	ds_read_b128 v[202:205], v211 offset:39936
	buffer_load_dwordx4 v178, s[40:43], s67 offen lds
	s_mov_b32 m0, s23
	s_nop 0
	buffer_load_dwordx4 v206, s[40:43], s67 offen lds
	s_waitcnt vmcnt(8)
	s_waitcnt lgkmcnt(0)
	s_barrier
	s_setprio 1
	v_mfma_f32_16x16x32_bf16 v[158:161], v[106:109], v[164:167], v[158:161]
	v_mfma_f32_16x16x32_bf16 v[154:157], v[114:117], v[164:167], v[154:157]
	v_mfma_f32_16x16x32_bf16 v[150:153], v[106:109], v[182:185], v[150:153]
	v_mfma_f32_16x16x32_bf16 v[146:149], v[114:117], v[182:185], v[146:149]
	v_mfma_f32_16x16x32_bf16 v[138:141], v[106:109], v[190:193], v[138:141]
	v_mfma_f32_16x16x32_bf16 v[134:137], v[114:117], v[190:193], v[134:137]
	v_mfma_f32_16x16x32_bf16 v[102:105], v[106:109], v[198:201], v[102:105]
	v_mfma_f32_16x16x32_bf16 v[98:101], v[114:117], v[198:201], v[98:101]
	v_mfma_f32_16x16x32_bf16 v[158:161], v[110:113], v[168:171], v[158:161]
	v_mfma_f32_16x16x32_bf16 v[154:157], v[118:121], v[168:171], v[154:157]
	v_mfma_f32_16x16x32_bf16 v[150:153], v[110:113], v[186:189], v[150:153]
	v_mfma_f32_16x16x32_bf16 v[146:149], v[118:121], v[186:189], v[146:149]
	v_mfma_f32_16x16x32_bf16 v[138:141], v[110:113], v[194:197], v[138:141]
	v_mfma_f32_16x16x32_bf16 v[134:137], v[118:121], v[194:197], v[134:137]
	v_mfma_f32_16x16x32_bf16 v[102:105], v[110:113], v[202:205], v[102:105]
	v_mfma_f32_16x16x32_bf16 v[98:101], v[118:121], v[202:205], v[98:101]
	v_mfma_f32_16x16x32_bf16 v[62:65], v[122:125], v[164:167], v[62:65]
	v_mfma_f32_16x16x32_bf16 v[58:61], v[130:133], v[164:167], v[58:61]
	v_mfma_f32_16x16x32_bf16 v[54:57], v[122:125], v[182:185], v[54:57]
	v_mfma_f32_16x16x32_bf16 v[50:53], v[130:133], v[182:185], v[50:53]
	v_mfma_f32_16x16x32_bf16 v[46:49], v[122:125], v[190:193], v[46:49]
	v_mfma_f32_16x16x32_bf16 v[42:45], v[130:133], v[190:193], v[42:45]
	v_mfma_f32_16x16x32_bf16 v[38:41], v[122:125], v[198:201], v[38:41]
	v_mfma_f32_16x16x32_bf16 v[34:37], v[130:133], v[198:201], v[34:37]
	v_mfma_f32_16x16x32_bf16 v[62:65], v[126:129], v[168:171], v[62:65]
	v_mfma_f32_16x16x32_bf16 v[58:61], v[142:145], v[168:171], v[58:61]
	v_mfma_f32_16x16x32_bf16 v[54:57], v[126:129], v[186:189], v[54:57]
	v_mfma_f32_16x16x32_bf16 v[50:53], v[142:145], v[186:189], v[50:53]
	v_mfma_f32_16x16x32_bf16 v[46:49], v[126:129], v[194:197], v[46:49]
	v_mfma_f32_16x16x32_bf16 v[42:45], v[142:145], v[194:197], v[42:45]
	v_mfma_f32_16x16x32_bf16 v[38:41], v[126:129], v[202:205], v[38:41]
	v_mfma_f32_16x16x32_bf16 v[34:37], v[142:145], v[202:205], v[34:37]
	s_setprio 0
	s_barrier
	s_mov_b32 m0, s54
	s_or_b32 s67, s66, 0x80
	ds_read_b128 v[164:167], v211 offset:49152
	ds_read_b128 v[168:171], v211 offset:50176
	ds_read_b128 v[182:185], v211 offset:51200
	ds_read_b128 v[186:189], v211 offset:52224
	ds_read_b128 v[190:193], v211 offset:53248
	ds_read_b128 v[194:197], v211 offset:54272
	ds_read_b128 v[198:201], v211 offset:55296
	ds_read_b128 v[202:205], v211 offset:56320
	buffer_load_dwordx4 v179, s[44:47], s67 offen lds
	s_mov_b32 m0, s55
	s_add_i32 s66, s66, 0x80080
	buffer_load_dwordx4 v207, s[44:47], s67 offen lds
	s_mov_b32 m0, s74
	s_nop 0
	buffer_load_dwordx4 v179, s[44:47], s66 offen lds
	s_mov_b32 m0, s75
	s_nop 0
	buffer_load_dwordx4 v207, s[44:47], s66 offen lds
	s_mov_b32 m0, s72
	s_nop 0
	buffer_load_dwordx4 v178, s[40:43], s65 offen lds
	s_mov_b32 m0, s73
	s_nop 0
	buffer_load_dwordx4 v206, s[40:43], s65 offen lds
	s_waitcnt vmcnt(8)
	s_waitcnt lgkmcnt(0)
	s_barrier
	s_setprio 1
	v_mfma_f32_16x16x32_bf16 v[94:97], v[106:109], v[164:167], v[94:97]
	v_mfma_f32_16x16x32_bf16 v[90:93], v[114:117], v[164:167], v[90:93]
	v_mfma_f32_16x16x32_bf16 v[86:89], v[106:109], v[182:185], v[86:89]
	v_mfma_f32_16x16x32_bf16 v[82:85], v[114:117], v[182:185], v[82:85]
	v_mfma_f32_16x16x32_bf16 v[78:81], v[106:109], v[190:193], v[78:81]
	v_mfma_f32_16x16x32_bf16 v[74:77], v[114:117], v[190:193], v[74:77]
	v_mfma_f32_16x16x32_bf16 v[70:73], v[106:109], v[198:201], v[70:73]
	v_mfma_f32_16x16x32_bf16 v[66:69], v[114:117], v[198:201], v[66:69]
	v_mfma_f32_16x16x32_bf16 v[94:97], v[110:113], v[168:171], v[94:97]
	v_mfma_f32_16x16x32_bf16 v[90:93], v[118:121], v[168:171], v[90:93]
	v_mfma_f32_16x16x32_bf16 v[86:89], v[110:113], v[186:189], v[86:89]
	v_mfma_f32_16x16x32_bf16 v[82:85], v[118:121], v[186:189], v[82:85]
	v_mfma_f32_16x16x32_bf16 v[78:81], v[110:113], v[194:197], v[78:81]
	v_mfma_f32_16x16x32_bf16 v[74:77], v[118:121], v[194:197], v[74:77]
	v_mfma_f32_16x16x32_bf16 v[70:73], v[110:113], v[202:205], v[70:73]
	v_mfma_f32_16x16x32_bf16 v[66:69], v[118:121], v[202:205], v[66:69]
	v_mfma_f32_16x16x32_bf16 v[30:33], v[122:125], v[164:167], v[30:33]
	v_mfma_f32_16x16x32_bf16 v[26:29], v[130:133], v[164:167], v[26:29]
	v_mfma_f32_16x16x32_bf16 v[22:25], v[122:125], v[182:185], v[22:25]
	v_mfma_f32_16x16x32_bf16 v[18:21], v[130:133], v[182:185], v[18:21]
	v_mfma_f32_16x16x32_bf16 v[14:17], v[122:125], v[190:193], v[14:17]
	v_mfma_f32_16x16x32_bf16 v[10:13], v[130:133], v[190:193], v[10:13]
	v_mfma_f32_16x16x32_bf16 v[6:9], v[122:125], v[198:201], v[6:9]
	v_mfma_f32_16x16x32_bf16 v[2:5], v[130:133], v[198:201], v[2:5]
	v_mfma_f32_16x16x32_bf16 v[30:33], v[126:129], v[168:171], v[30:33]
	v_mfma_f32_16x16x32_bf16 v[26:29], v[142:145], v[168:171], v[26:29]
	v_mfma_f32_16x16x32_bf16 v[22:25], v[126:129], v[186:189], v[22:25]
	v_mfma_f32_16x16x32_bf16 v[18:21], v[142:145], v[186:189], v[18:21]
	v_mfma_f32_16x16x32_bf16 v[14:17], v[126:129], v[194:197], v[14:17]
	v_mfma_f32_16x16x32_bf16 v[10:13], v[142:145], v[194:197], v[10:13]
	v_mfma_f32_16x16x32_bf16 v[6:9], v[126:129], v[202:205], v[6:9]
	v_mfma_f32_16x16x32_bf16 v[2:5], v[142:145], v[202:205], v[2:5]
	s_setprio 0
	s_barrier
	s_add_i32 s64, s64, 2
	s_addk_i32 s59, 0x100
	s_addk_i32 s63, 0x100
	s_cmp_gt_u32 s64, 29
	s_cbranch_scc0 .LBB0_1529
	s_and_b64 vcc, exec, s[52:53]
	s_cbranch_vccz .LBB0_1532
	s_barrier

; #define PG8_STAGEX(rs, bufoff, soff, voff) do { _Pragma("unroll") for (int _i = 0; _i < 2; ++_i) \
;         __builtin_amdgcn_raw_ptr_buffer_load_lds(rs, (LAS unsigned*)(lds + (bufoff) + ldsw + _i * 8192), 16, (voff)[_i], (soff), 0, 0); } while (0)
; #define PG8_LDA(dst, b, h) do { _Pragma("unroll") for (int m = 0; m < 4; ++m) _Pragma("unroll") for (int k = 0; k < 2; ++k) dst[m][k] = *(const LAS bf16x8*)(lds + PG8_SA(b, h) + aoff + m * 2048 + k * 1024); } while (0)
; #define PG8_LDB(dst, b, h) do { _Pragma("unroll") for (int n = 0; n < 2; ++n) _Pragma("unroll") for (int k = 0; k < 2; ++k) dst[n][k] = *(const LAS bf16x8*)(lds + PG8_SB(b, h) + boff + n * 2048 + k * 1024); } while (0)
; #define PG8_WAIT_V(n) asm volatile("s_waitcnt vmcnt(" #n ")" ::: "memory")
; #define PG8_WAIT_L(n) asm volatile("s_waitcnt lgkmcnt(" #n ")" ::: "memory")
; #define PG8_BAR __builtin_amdgcn_s_barrier()
; #define PG8_SCHED __builtin_amdgcn_sched_barrier(0)
;     ...
;             PG8_LDB(B0, 0, 0); PG8_LDB(B1, 0, 1); PG8_SCHED; PG8_LDA(At, 0, 0); PG8_STAGEX(rsA, PG8_SA(1, 1), a1 + hstepA, voffA);
;             PG8_WAIT_V(8); PG8_WAIT_L(0); PG8_BAR; PG8_MMA(0, 0, At, B0); PG8_MMA(0, 1, At, B1); PG8_BAR; PG8_SCHED;
;             PG8_LDA(At, 0, 1); PG8_STAGEX(rsB, PG8_SB(0, 0), b2, voffB); PG8_STAGEX(rsB, PG8_SB(0, 1), b2 + hstepB, voffB); PG8_STAGEX(rsA, PG8_SA(0, 0), a2, voffA);
;             PG8_WAIT_V(8); PG8_WAIT_L(0); PG8_BAR; PG8_MMA(1, 0, At, B0); PG8_MMA(1, 1, At, B1); PG8_BAR; PG8_SCHED;
.LBB0_1651:
	v_add_u32_e32 v102, 0x10000, v172
	v_add_u32_e32 v146, 0x14000, v172
	ds_read_b128 v[82:85], v102
	ds_read_b128 v[86:89], v102 offset:1024
	ds_read_b128 v[98:101], v102 offset:2048
	ds_read_b128 v[102:105], v102 offset:3072
	ds_read_b128 v[150:153], v146
	ds_read_b128 v[154:157], v146 offset:1024
	ds_read_b128 v[182:185], v146 offset:2048
	ds_read_b128 v[186:189], v146 offset:3072
	s_add_i32 s42, s61, 0xfff80080
	s_cmp_eq_u32 s63, 28
	s_cselect_b32 s66, s30, s42
	s_cselect_b32 s65, s31, s62
	s_or_b32 s64, s66, 0x80
	s_mov_b32 m0, s29
	ds_read_b128 v[190:193], v173
	ds_read_b128 v[194:197], v173 offset:1024
	ds_read_b128 v[198:201], v173 offset:2048
	ds_read_b128 v[202:205], v173 offset:3072
	ds_read_b128 v[206:209], v173 offset:4096
	ds_read_b128 v[210:213], v173 offset:5120
	ds_read_b128 v[214:217], v173 offset:6144
	ds_read_b128 v[218:221], v173 offset:7168
	buffer_load_dwordx4 v159, s[76:79], s61 offen lds
	s_mov_b32 m0, s50
	s_nop 0
	buffer_load_dwordx4 v163, s[76:79], s61 offen lds
	s_waitcnt vmcnt(8)
	s_waitcnt lgkmcnt(0)
	s_barrier
	s_setprio 1
	v_mfma_f32_16x16x32_bf16 v[142:145], v[82:85], v[190:193], v[142:145]
	v_mfma_f32_16x16x32_bf16 v[134:137], v[98:101], v[190:193], v[134:137]
	v_mfma_f32_16x16x32_bf16 v[126:129], v[82:85], v[198:201], v[126:129]
	v_mfma_f32_16x16x32_bf16 v[118:121], v[98:101], v[198:201], v[118:121]
	v_mfma_f32_16x16x32_bf16 v[110:113], v[82:85], v[206:209], v[110:113]
	v_mfma_f32_16x16x32_bf16 v[94:97], v[98:101], v[206:209], v[94:97]
	v_mfma_f32_16x16x32_bf16 v[78:81], v[82:85], v[214:217], v[78:81]
	v_mfma_f32_16x16x32_bf16 v[70:73], v[98:101], v[214:217], v[70:73]
	v_mfma_f32_16x16x32_bf16 v[142:145], v[86:89], v[194:197], v[142:145]
	v_mfma_f32_16x16x32_bf16 v[134:137], v[102:105], v[194:197], v[134:137]
	v_mfma_f32_16x16x32_bf16 v[126:129], v[86:89], v[202:205], v[126:129]
	v_mfma_f32_16x16x32_bf16 v[118:121], v[102:105], v[202:205], v[118:121]
	v_mfma_f32_16x16x32_bf16 v[110:113], v[86:89], v[210:213], v[110:113]
	v_mfma_f32_16x16x32_bf16 v[94:97], v[102:105], v[210:213], v[94:97]
	v_mfma_f32_16x16x32_bf16 v[78:81], v[86:89], v[218:221], v[78:81]
	v_mfma_f32_16x16x32_bf16 v[70:73], v[102:105], v[218:221], v[70:73]
	v_mfma_f32_16x16x32_bf16 v[138:141], v[150:153], v[190:193], v[138:141]
	v_mfma_f32_16x16x32_bf16 v[130:133], v[182:185], v[190:193], v[130:133]
	v_mfma_f32_16x16x32_bf16 v[122:125], v[150:153], v[198:201], v[122:125]
	v_mfma_f32_16x16x32_bf16 v[114:117], v[182:185], v[198:201], v[114:117]
	v_mfma_f32_16x16x32_bf16 v[106:109], v[150:153], v[206:209], v[106:109]
	v_mfma_f32_16x16x32_bf16 v[90:93], v[182:185], v[206:209], v[90:93]
	v_mfma_f32_16x16x32_bf16 v[74:77], v[150:153], v[214:217], v[74:77]
	v_mfma_f32_16x16x32_bf16 v[66:69], v[182:185], v[214:217], v[66:69]
	v_mfma_f32_16x16x32_bf16 v[138:141], v[154:157], v[194:197], v[138:141]
	v_mfma_f32_16x16x32_bf16 v[130:133], v[186:189], v[194:197], v[130:133]
	v_mfma_f32_16x16x32_bf16 v[122:125], v[154:157], v[202:205], v[122:125]
	v_mfma_f32_16x16x32_bf16 v[114:117], v[186:189], v[202:205], v[114:117]
	v_mfma_f32_16x16x32_bf16 v[106:109], v[154:157], v[210:213], v[106:109]
	v_mfma_f32_16x16x32_bf16 v[90:93], v[186:189], v[210:213], v[90:93]
	v_mfma_f32_16x16x32_bf16 v[74:77], v[154:157], v[218:221], v[74:77]
	v_mfma_f32_16x16x32_bf16 v[66:69], v[186:189], v[218:221], v[66:69]
	s_setprio 0
	s_barrier
	s_mov_b32 m0, s16
	s_mov_b32 s42, s78
	s_mov_b32 s43, s79
	ds_read_b128 v[190:193], v173 offset:16384
	ds_read_b128 v[194:197], v173 offset:17408
	ds_read_b128 v[198:201], v173 offset:18432
	ds_read_b128 v[202:205], v173 offset:19456
	ds_read_b128 v[206:209], v173 offset:20480
	ds_read_b128 v[210:213], v173 offset:21504
	ds_read_b128 v[214:217], v173 offset:22528
	ds_read_b128 v[218:221], v173 offset:23552
	buffer_load_dwordx4 v161, s[40:43], s65 offen lds
	s_mov_b32 m0, s17
	s_add_i32 s67, s65, 0x80000
	buffer_load_dwordx4 v165, s[40:43], s65 offen lds
	s_mov_b32 m0, s18
	s_nop 0
	buffer_load_dwordx4 v161, s[40:43], s67 offen lds
	s_mov_b32 m0, s19
	s_nop 0
	buffer_load_dwordx4 v165, s[40:43], s67 offen lds
	s_mov_b32 m0, s15
	s_nop 0
	buffer_load_dwordx4 v159, s[76:79], s66 offen lds
	s_mov_b32 m0, s20
	s_nop 0
	buffer_load_dwordx4 v163, s[76:79], s66 offen lds
	s_waitcnt vmcnt(8)
	s_waitcnt lgkmcnt(0)
	s_barrier
	s_setprio 1
	v_mfma_f32_16x16x32_bf16 v[62:65], v[82:85], v[190:193], v[62:65]
	v_mfma_f32_16x16x32_bf16 v[54:57], v[98:101], v[190:193], v[54:57]
	v_mfma_f32_16x16x32_bf16 v[46:49], v[82:85], v[198:201], v[46:49]
	v_mfma_f32_16x16x32_bf16 v[38:41], v[98:101], v[198:201], v[38:41]
	v_mfma_f32_16x16x32_bf16 v[30:33], v[82:85], v[206:209], v[30:33]
	v_mfma_f32_16x16x32_bf16 v[22:25], v[98:101], v[206:209], v[22:25]
	v_mfma_f32_16x16x32_bf16 v[14:17], v[82:85], v[214:217], v[14:17]
	v_mfma_f32_16x16x32_bf16 v[6:9], v[98:101], v[214:217], v[6:9]
	v_mfma_f32_16x16x32_bf16 v[62:65], v[86:89], v[194:197], v[62:65]
	v_mfma_f32_16x16x32_bf16 v[54:57], v[102:105], v[194:197], v[54:57]
	v_mfma_f32_16x16x32_bf16 v[46:49], v[86:89], v[202:205], v[46:49]
	v_mfma_f32_16x16x32_bf16 v[38:41], v[102:105], v[202:205], v[38:41]
	v_mfma_f32_16x16x32_bf16 v[30:33], v[86:89], v[210:213], v[30:33]
	v_mfma_f32_16x16x32_bf16 v[22:25], v[102:105], v[210:213], v[22:25]
	v_mfma_f32_16x16x32_bf16 v[14:17], v[86:89], v[218:221], v[14:17]
	v_mfma_f32_16x16x32_bf16 v[6:9], v[102:105], v[218:221], v[6:9]
	v_mfma_f32_16x16x32_bf16 v[58:61], v[150:153], v[190:193], v[58:61]
	v_mfma_f32_16x16x32_bf16 v[50:53], v[182:185], v[190:193], v[50:53]
	v_mfma_f32_16x16x32_bf16 v[42:45], v[150:153], v[198:201], v[42:45]
	v_mfma_f32_16x16x32_bf16 v[34:37], v[182:185], v[198:201], v[34:37]
	v_mfma_f32_16x16x32_bf16 v[26:29], v[150:153], v[206:209], v[26:29]
	v_mfma_f32_16x16x32_bf16 v[18:21], v[182:185], v[206:209], v[18:21]
	v_mfma_f32_16x16x32_bf16 v[10:13], v[150:153], v[214:217], v[10:13]
	v_mfma_f32_16x16x32_bf16 v[2:5], v[182:185], v[214:217], v[2:5]
	v_mfma_f32_16x16x32_bf16 v[58:61], v[154:157], v[194:197], v[58:61]
	v_mfma_f32_16x16x32_bf16 v[50:53], v[186:189], v[194:197], v[50:53]
	v_mfma_f32_16x16x32_bf16 v[42:45], v[154:157], v[202:205], v[42:45]
	v_mfma_f32_16x16x32_bf16 v[34:37], v[186:189], v[202:205], v[34:37]
	v_mfma_f32_16x16x32_bf16 v[26:29], v[154:157], v[210:213], v[26:29]
	v_mfma_f32_16x16x32_bf16 v[18:21], v[186:189], v[210:213], v[18:21]
	v_mfma_f32_16x16x32_bf16 v[10:13], v[154:157], v[218:221], v[10:13]
	v_mfma_f32_16x16x32_bf16 v[2:5], v[186:189], v[218:221], v[2:5]
	s_setprio 0
	s_barrier
; #define PG8_STAGEX(rs, bufoff, soff, voff) do { _Pragma("unroll") for (int _i = 0; _i < 2; ++_i) \
;         __builtin_amdgcn_raw_ptr_buffer_load_lds(rs, (LAS unsigned*)(lds + (bufoff) + ldsw + _i * 8192), 16, (voff)[_i], (soff), 0, 0); } while (0)
; #define PG8_LDA(dst, b, h) do { _Pragma("unroll") for (int m = 0; m < 4; ++m) _Pragma("unroll") for (int k = 0; k < 2; ++k) dst[m][k] = *(const LAS bf16x8*)(lds + PG8_SA(b, h) + aoff + m * 2048 + k * 1024); } while (0)
; #define PG8_LDB(dst, b, h) do { _Pragma("unroll") for (int n = 0; n < 2; ++n) _Pragma("unroll") for (int k = 0; k < 2; ++k) dst[n][k] = *(const LAS bf16x8*)(lds + PG8_SB(b, h) + boff + n * 2048 + k * 1024); } while (0)
; #define PG8_WAIT_V(n) asm volatile("s_waitcnt vmcnt(" #n ")" ::: "memory")
; #define PG8_WAIT_L(n) asm volatile("s_waitcnt lgkmcnt(" #n ")" ::: "memory")
; #define PG8_BAR __builtin_amdgcn_s_barrier()
; #define PG8_SCHED __builtin_amdgcn_sched_barrier(0)
;     ...
;             PG8_LDB(B0, 1, 0); PG8_LDB(B1, 1, 1); PG8_SCHED; PG8_LDA(At, 1, 0); PG8_STAGEX(rsA, PG8_SA(0, 1), a2 + hstepA, voffA);
;             PG8_WAIT_V(8); PG8_WAIT_L(0); PG8_BAR; PG8_MMA(0, 0, At, B0); PG8_MMA(0, 1, At, B1); PG8_BAR; PG8_SCHED;
;             PG8_LDA(At, 1, 1); PG8_STAGEX(rsB, PG8_SB(1, 0), b3, voffB); PG8_STAGEX(rsB, PG8_SB(1, 1), b3 + hstepB, voffB); PG8_STAGEX(rsA, PG8_SA(1, 0), a3, voffA);
;             PG8_WAIT_V(8); PG8_WAIT_L(0); PG8_BAR; PG8_MMA(1, 0, At, B0); PG8_MMA(1, 1, At, B1); PG8_BAR; PG8_SCHED;
;         }
	v_add_u32_e32 v102, 0x18000, v172
	v_add_u32_e32 v146, 0x1c000, v172
	ds_read_b128 v[82:85], v102
	ds_read_b128 v[86:89], v102 offset:1024
	ds_read_b128 v[98:101], v102 offset:2048
	ds_read_b128 v[102:105], v102 offset:3072
	ds_read_b128 v[150:153], v146
	ds_read_b128 v[154:157], v146 offset:1024
	ds_read_b128 v[182:185], v146 offset:2048
	ds_read_b128 v[186:189], v146 offset:3072
	s_add_i32 s66, s66, 0x80000
	s_mov_b32 m0, s21
	ds_read_b128 v[190:193], v173 offset:32768
	ds_read_b128 v[194:197], v173 offset:33792
	ds_read_b128 v[198:201], v173 offset:34816
	ds_read_b128 v[202:205], v173 offset:35840
	ds_read_b128 v[206:209], v173 offset:36864
	ds_read_b128 v[210:213], v173 offset:37888
	ds_read_b128 v[214:217], v173 offset:38912
	ds_read_b128 v[218:221], v173 offset:39936
	buffer_load_dwordx4 v159, s[76:79], s66 offen lds
	s_mov_b32 m0, s22
	s_nop 0
	buffer_load_dwordx4 v163, s[76:79], s66 offen lds
	s_waitcnt vmcnt(8)
	s_waitcnt lgkmcnt(0)
	s_barrier
	s_setprio 1
	v_mfma_f32_16x16x32_bf16 v[142:145], v[82:85], v[190:193], v[142:145]
	v_mfma_f32_16x16x32_bf16 v[134:137], v[98:101], v[190:193], v[134:137]
	v_mfma_f32_16x16x32_bf16 v[126:129], v[82:85], v[198:201], v[126:129]
	v_mfma_f32_16x16x32_bf16 v[118:121], v[98:101], v[198:201], v[118:121]
	v_mfma_f32_16x16x32_bf16 v[110:113], v[82:85], v[206:209], v[110:113]
	v_mfma_f32_16x16x32_bf16 v[94:97], v[98:101], v[206:209], v[94:97]
	v_mfma_f32_16x16x32_bf16 v[78:81], v[82:85], v[214:217], v[78:81]
	v_mfma_f32_16x16x32_bf16 v[70:73], v[98:101], v[214:217], v[70:73]
	v_mfma_f32_16x16x32_bf16 v[142:145], v[86:89], v[194:197], v[142:145]
	v_mfma_f32_16x16x32_bf16 v[134:137], v[102:105], v[194:197], v[134:137]
	v_mfma_f32_16x16x32_bf16 v[126:129], v[86:89], v[202:205], v[126:129]
	v_mfma_f32_16x16x32_bf16 v[118:121], v[102:105], v[202:205], v[118:121]
	v_mfma_f32_16x16x32_bf16 v[110:113], v[86:89], v[210:213], v[110:113]
	v_mfma_f32_16x16x32_bf16 v[94:97], v[102:105], v[210:213], v[94:97]
	v_mfma_f32_16x16x32_bf16 v[78:81], v[86:89], v[218:221], v[78:81]
	v_mfma_f32_16x16x32_bf16 v[70:73], v[102:105], v[218:221], v[70:73]
	v_mfma_f32_16x16x32_bf16 v[138:141], v[150:153], v[190:193], v[138:141]
	v_mfma_f32_16x16x32_bf16 v[130:133], v[182:185], v[190:193], v[130:133]
	v_mfma_f32_16x16x32_bf16 v[122:125], v[150:153], v[198:201], v[122:125]
	v_mfma_f32_16x16x32_bf16 v[114:117], v[182:185], v[198:201], v[114:117]
	v_mfma_f32_16x16x32_bf16 v[106:109], v[150:153], v[206:209], v[106:109]
	v_mfma_f32_16x16x32_bf16 v[90:93], v[182:185], v[206:209], v[90:93]
	v_mfma_f32_16x16x32_bf16 v[74:77], v[150:153], v[214:217], v[74:77]
	v_mfma_f32_16x16x32_bf16 v[66:69], v[182:185], v[214:217], v[66:69]
	v_mfma_f32_16x16x32_bf16 v[138:141], v[154:157], v[194:197], v[138:141]
	v_mfma_f32_16x16x32_bf16 v[130:133], v[186:189], v[194:197], v[130:133]
	v_mfma_f32_16x16x32_bf16 v[122:125], v[154:157], v[202:205], v[122:125]
	v_mfma_f32_16x16x32_bf16 v[114:117], v[186:189], v[202:205], v[114:117]
	v_mfma_f32_16x16x32_bf16 v[106:109], v[154:157], v[210:213], v[106:109]
	v_mfma_f32_16x16x32_bf16 v[90:93], v[186:189], v[210:213], v[90:93]
	v_mfma_f32_16x16x32_bf16 v[74:77], v[154:157], v[218:221], v[74:77]
	v_mfma_f32_16x16x32_bf16 v[66:69], v[186:189], v[218:221], v[66:69]
	s_setprio 0
	s_barrier
	s_mov_b32 m0, s23
	s_or_b32 s66, s65, 0x80
	ds_read_b128 v[190:193], v173 offset:49152
	ds_read_b128 v[194:197], v173 offset:50176
	ds_read_b128 v[198:201], v173 offset:51200
	ds_read_b128 v[202:205], v173 offset:52224
	ds_read_b128 v[206:209], v173 offset:53248
	ds_read_b128 v[210:213], v173 offset:54272
	ds_read_b128 v[214:217], v173 offset:55296
	ds_read_b128 v[218:221], v173 offset:56320
	buffer_load_dwordx4 v161, s[40:43], s66 offen lds
	s_mov_b32 m0, s24
	s_add_i32 s65, s65, 0x80080
	buffer_load_dwordx4 v165, s[40:43], s66 offen lds
	s_mov_b32 m0, s27
	s_nop 0
	buffer_load_dwordx4 v161, s[40:43], s65 offen lds
	s_mov_b32 m0, s28
	s_nop 0
	buffer_load_dwordx4 v165, s[40:43], s65 offen lds
	s_mov_b32 m0, s25
	s_nop 0
	buffer_load_dwordx4 v159, s[76:79], s64 offen lds
	s_mov_b32 m0, s26
	s_nop 0
	buffer_load_dwordx4 v163, s[76:79], s64 offen lds
	s_waitcnt vmcnt(8)
	s_waitcnt lgkmcnt(0)
	s_barrier
	s_setprio 1
	v_mfma_f32_16x16x32_bf16 v[62:65], v[82:85], v[190:193], v[62:65]
	v_mfma_f32_16x16x32_bf16 v[54:57], v[98:101], v[190:193], v[54:57]
	v_mfma_f32_16x16x32_bf16 v[46:49], v[82:85], v[198:201], v[46:49]
	v_mfma_f32_16x16x32_bf16 v[38:41], v[98:101], v[198:201], v[38:41]
	v_mfma_f32_16x16x32_bf16 v[30:33], v[82:85], v[206:209], v[30:33]
	v_mfma_f32_16x16x32_bf16 v[22:25], v[98:101], v[206:209], v[22:25]
	v_mfma_f32_16x16x32_bf16 v[14:17], v[82:85], v[214:217], v[14:17]
	v_mfma_f32_16x16x32_bf16 v[6:9], v[98:101], v[214:217], v[6:9]
	v_mfma_f32_16x16x32_bf16 v[62:65], v[86:89], v[194:197], v[62:65]
	v_mfma_f32_16x16x32_bf16 v[54:57], v[102:105], v[194:197], v[54:57]
	v_mfma_f32_16x16x32_bf16 v[46:49], v[86:89], v[202:205], v[46:49]
	v_mfma_f32_16x16x32_bf16 v[38:41], v[102:105], v[202:205], v[38:41]
	v_mfma_f32_16x16x32_bf16 v[30:33], v[86:89], v[210:213], v[30:33]
	v_mfma_f32_16x16x32_bf16 v[22:25], v[102:105], v[210:213], v[22:25]
	v_mfma_f32_16x16x32_bf16 v[14:17], v[86:89], v[218:221], v[14:17]
	v_mfma_f32_16x16x32_bf16 v[6:9], v[102:105], v[218:221], v[6:9]
	v_mfma_f32_16x16x32_bf16 v[58:61], v[150:153], v[190:193], v[58:61]
	v_mfma_f32_16x16x32_bf16 v[50:53], v[182:185], v[190:193], v[50:53]
	v_mfma_f32_16x16x32_bf16 v[42:45], v[150:153], v[198:201], v[42:45]
	v_mfma_f32_16x16x32_bf16 v[34:37], v[182:185], v[198:201], v[34:37]
	v_mfma_f32_16x16x32_bf16 v[26:29], v[150:153], v[206:209], v[26:29]
	v_mfma_f32_16x16x32_bf16 v[18:21], v[182:185], v[206:209], v[18:21]
	v_mfma_f32_16x16x32_bf16 v[10:13], v[150:153], v[214:217], v[10:13]
	v_mfma_f32_16x16x32_bf16 v[2:5], v[182:185], v[214:217], v[2:5]
	v_mfma_f32_16x16x32_bf16 v[58:61], v[154:157], v[194:197], v[58:61]
	v_mfma_f32_16x16x32_bf16 v[50:53], v[186:189], v[194:197], v[50:53]
	v_mfma_f32_16x16x32_bf16 v[42:45], v[154:157], v[202:205], v[42:45]
	v_mfma_f32_16x16x32_bf16 v[34:37], v[186:189], v[202:205], v[34:37]
	v_mfma_f32_16x16x32_bf16 v[26:29], v[154:157], v[210:213], v[26:29]
	v_mfma_f32_16x16x32_bf16 v[18:21], v[186:189], v[210:213], v[18:21]
	v_mfma_f32_16x16x32_bf16 v[10:13], v[154:157], v[218:221], v[10:13]
	v_mfma_f32_16x16x32_bf16 v[2:5], v[186:189], v[218:221], v[2:5]
	s_setprio 0
	s_barrier
	s_add_i32 s63, s63, 2
	s_addk_i32 s61, 0x100
	s_addk_i32 s62, 0x100
	s_cmp_gt_u32 s63, 29
	s_cbranch_scc0 .LBB0_1651
	s_and_b64 vcc, exec, s[48:49]
	s_cbranch_vccz .LBB0_1654
	s_barrier

; #define PG8_STAGEX(rs, bufoff, soff, voff) do { _Pragma("unroll") for (int _i = 0; _i < 2; ++_i) \
;         __builtin_amdgcn_raw_ptr_buffer_load_lds(rs, (LAS unsigned*)(lds + (bufoff) + ldsw + _i * 8192), 16, (voff)[_i], (soff), 0, 0); } while (0)
; #define PG8_LDA(dst, b, h) do { _Pragma("unroll") for (int m = 0; m < 4; ++m) _Pragma("unroll") for (int k = 0; k < 2; ++k) dst[m][k] = *(const LAS bf16x8*)(lds + PG8_SA(b, h) + aoff + m * 2048 + k * 1024); } while (0)
; #define PG8_LDB(dst, b, h) do { _Pragma("unroll") for (int n = 0; n < 2; ++n) _Pragma("unroll") for (int k = 0; k < 2; ++k) dst[n][k] = *(const LAS bf16x8*)(lds + PG8_SB(b, h) + boff + n * 2048 + k * 1024); } while (0)
; #define PG8_WAIT_V(n) asm volatile("s_waitcnt vmcnt(" #n ")" ::: "memory")
; #define PG8_WAIT_L(n) asm volatile("s_waitcnt lgkmcnt(" #n ")" ::: "memory")
; #define PG8_BAR __builtin_amdgcn_s_barrier()
; #define PG8_SCHED __builtin_amdgcn_sched_barrier(0)
;     ...
;                 if (w0) { PG8_LDB(B0, 0, 0); PG8_LDB(B1, 0, 1); PG8_SCHED; PG8_LDA(At, 0, 0); }
;                 PG8_WAIT_L(0); PG8_BAR; if (w0) { PG8_MMA(0, 0, At, B0); PG8_MMA(0, 1, At, B1); } PG8_BAR; PG8_SCHED;
;                 PG8_STAGEX(rsB, PG8_SB(0, 0), b2, voffB); PG8_STAGEX(rsB, PG8_SB(0, 1), b2 + hstepB, voffB); PG8_STAGEX(rsA, PG8_SA(0, 0), a2, voffA);
;                 PG8_WAIT_V(6); PG8_BAR; PG8_BAR; PG8_SCHED;
.LBB0_1668:
	v_add_u32_e32 v86, 0x10000, v72
	v_add_u32_e32 v102, 0x14000, v72
	ds_read_b128 v[74:77], v86
	ds_read_b128 v[78:81], v86 offset:1024
	ds_read_b128 v[82:85], v86 offset:2048
	ds_read_b128 v[86:89], v86 offset:3072
	ds_read_b128 v[90:93], v102
	ds_read_b128 v[94:97], v102 offset:1024
	ds_read_b128 v[98:101], v102 offset:2048
	ds_read_b128 v[102:105], v102 offset:3072
	s_cmp_lg_u32 s27, 28
	s_cselect_b32 s28, s26, 0
	s_add_i32 s29, s28, s17
	s_or_b32 s30, s29, 0x80
	s_add_i32 s28, s28, s10
	ds_read_b128 v[106:109], v73
	ds_read_b128 v[110:113], v73 offset:1024
	ds_read_b128 v[114:117], v73 offset:2048
	ds_read_b128 v[118:121], v73 offset:3072
	ds_read_b128 v[122:125], v73 offset:4096
	ds_read_b128 v[126:129], v73 offset:5120
	ds_read_b128 v[130:133], v73 offset:6144
	ds_read_b128 v[134:137], v73 offset:7168
	s_waitcnt lgkmcnt(0)
	s_barrier
	s_setprio 1
	v_mfma_f32_16x16x32_bf16 v[62:65], v[74:77], v[106:109], v[62:65]
	v_mfma_f32_16x16x32_bf16 v[58:61], v[82:85], v[106:109], v[58:61]
	v_mfma_f32_16x16x32_bf16 v[54:57], v[74:77], v[114:117], v[54:57]
	v_mfma_f32_16x16x32_bf16 v[38:41], v[82:85], v[114:117], v[38:41]
	v_mfma_f32_16x16x32_bf16 v[30:33], v[74:77], v[122:125], v[30:33]
	v_mfma_f32_16x16x32_bf16 v[22:25], v[82:85], v[122:125], v[22:25]
	v_mfma_f32_16x16x32_bf16 v[14:17], v[74:77], v[130:133], v[14:17]
	v_mfma_f32_16x16x32_bf16 v[6:9], v[82:85], v[130:133], v[6:9]
	v_mfma_f32_16x16x32_bf16 v[62:65], v[78:81], v[110:113], v[62:65]
	v_mfma_f32_16x16x32_bf16 v[58:61], v[86:89], v[110:113], v[58:61]
	v_mfma_f32_16x16x32_bf16 v[54:57], v[78:81], v[118:121], v[54:57]
	v_mfma_f32_16x16x32_bf16 v[38:41], v[86:89], v[118:121], v[38:41]
	v_mfma_f32_16x16x32_bf16 v[30:33], v[78:81], v[126:129], v[30:33]
	v_mfma_f32_16x16x32_bf16 v[22:25], v[86:89], v[126:129], v[22:25]
	v_mfma_f32_16x16x32_bf16 v[14:17], v[78:81], v[134:137], v[14:17]
	v_mfma_f32_16x16x32_bf16 v[6:9], v[86:89], v[134:137], v[6:9]
	v_mfma_f32_16x16x32_bf16 v[50:53], v[90:93], v[106:109], v[50:53]
	v_mfma_f32_16x16x32_bf16 v[46:49], v[98:101], v[106:109], v[46:49]
	v_mfma_f32_16x16x32_bf16 v[42:45], v[90:93], v[114:117], v[42:45]
	v_mfma_f32_16x16x32_bf16 v[34:37], v[98:101], v[114:117], v[34:37]
	v_mfma_f32_16x16x32_bf16 v[26:29], v[90:93], v[122:125], v[26:29]
	v_mfma_f32_16x16x32_bf16 v[18:21], v[98:101], v[122:125], v[18:21]
	v_mfma_f32_16x16x32_bf16 v[10:13], v[90:93], v[130:133], v[10:13]
	v_mfma_f32_16x16x32_bf16 v[2:5], v[98:101], v[130:133], v[2:5]
	v_mfma_f32_16x16x32_bf16 v[50:53], v[94:97], v[110:113], v[50:53]
	v_mfma_f32_16x16x32_bf16 v[46:49], v[102:105], v[110:113], v[46:49]
	v_mfma_f32_16x16x32_bf16 v[42:45], v[94:97], v[118:121], v[42:45]
	v_mfma_f32_16x16x32_bf16 v[34:37], v[102:105], v[118:121], v[34:37]
	v_mfma_f32_16x16x32_bf16 v[26:29], v[94:97], v[126:129], v[26:29]
	v_mfma_f32_16x16x32_bf16 v[18:21], v[102:105], v[126:129], v[18:21]
	v_mfma_f32_16x16x32_bf16 v[10:13], v[94:97], v[134:137], v[10:13]
	v_mfma_f32_16x16x32_bf16 v[2:5], v[102:105], v[134:137], v[2:5]
	s_setprio 0
	s_barrier
	s_mov_b32 m0, s13
	s_mov_b32 s42, s78
	s_mov_b32 s43, s79
	buffer_load_dwordx4 v67, s[40:43], s28 offen lds
	s_mov_b32 m0, s14
	s_add_i32 s31, s28, 0x80000
	buffer_load_dwordx4 v69, s[40:43], s28 offen lds
	s_mov_b32 m0, s15
	s_nop 0
	buffer_load_dwordx4 v67, s[40:43], s31 offen lds
	s_mov_b32 m0, s16
	s_nop 0
	buffer_load_dwordx4 v69, s[40:43], s31 offen lds
	s_mov_b32 m0, s12
	s_nop 0
	buffer_load_dwordx4 v66, s[76:79], s29 offen lds
	s_mov_b32 m0, s18
	s_nop 0
	buffer_load_dwordx4 v68, s[76:79], s29 offen lds
	s_waitcnt vmcnt(6)
	s_barrier
	s_barrier
; #define PG8_STAGEX(rs, bufoff, soff, voff) do { _Pragma("unroll") for (int _i = 0; _i < 2; ++_i) \
;         __builtin_amdgcn_raw_ptr_buffer_load_lds(rs, (LAS unsigned*)(lds + (bufoff) + ldsw + _i * 8192), 16, (voff)[_i], (soff), 0, 0); } while (0)
; #define PG8_LDA(dst, b, h) do { _Pragma("unroll") for (int m = 0; m < 4; ++m) _Pragma("unroll") for (int k = 0; k < 2; ++k) dst[m][k] = *(const LAS bf16x8*)(lds + PG8_SA(b, h) + aoff + m * 2048 + k * 1024); } while (0)
; #define PG8_LDB(dst, b, h) do { _Pragma("unroll") for (int n = 0; n < 2; ++n) _Pragma("unroll") for (int k = 0; k < 2; ++k) dst[n][k] = *(const LAS bf16x8*)(lds + PG8_SB(b, h) + boff + n * 2048 + k * 1024); } while (0)
; #define PG8_WAIT_V(n) asm volatile("s_waitcnt vmcnt(" #n ")" ::: "memory")
; #define PG8_WAIT_L(n) asm volatile("s_waitcnt lgkmcnt(" #n ")" ::: "memory")
; #define PG8_BAR __builtin_amdgcn_s_barrier()
; #define PG8_SCHED __builtin_amdgcn_sched_barrier(0)
;     ...
;                 if (w0) { PG8_LDB(B0, 1, 0); PG8_LDB(B1, 1, 1); PG8_SCHED; PG8_LDA(At, 1, 0); }
;                 PG8_WAIT_L(0); PG8_BAR; if (w0) { PG8_MMA(0, 0, At, B0); PG8_MMA(0, 1, At, B1); } PG8_BAR; PG8_SCHED;
;                 PG8_STAGEX(rsB, PG8_SB(1, 0), b3, voffB); PG8_STAGEX(rsB, PG8_SB(1, 1), b3 + hstepB, voffB); PG8_STAGEX(rsA, PG8_SA(1, 0), a3, voffA);
;                 PG8_WAIT_V(6); PG8_BAR; PG8_BAR; PG8_SCHED;
;             }
	v_add_u32_e32 v86, 0x18000, v72
	v_add_u32_e32 v102, 0x1c000, v72
	ds_read_b128 v[74:77], v86
	ds_read_b128 v[78:81], v86 offset:1024
	ds_read_b128 v[82:85], v86 offset:2048
	ds_read_b128 v[86:89], v86 offset:3072
	ds_read_b128 v[90:93], v102
	ds_read_b128 v[94:97], v102 offset:1024
	ds_read_b128 v[98:101], v102 offset:2048
	ds_read_b128 v[102:105], v102 offset:3072
	ds_read_b128 v[106:109], v73 offset:32768
	ds_read_b128 v[110:113], v73 offset:33792
	ds_read_b128 v[114:117], v73 offset:34816
	ds_read_b128 v[118:121], v73 offset:35840
	ds_read_b128 v[122:125], v73 offset:36864
	ds_read_b128 v[126:129], v73 offset:37888
	ds_read_b128 v[130:133], v73 offset:38912
	ds_read_b128 v[134:137], v73 offset:39936
	s_waitcnt lgkmcnt(0)
	s_barrier
	s_setprio 1
	v_mfma_f32_16x16x32_bf16 v[62:65], v[74:77], v[106:109], v[62:65]
	v_mfma_f32_16x16x32_bf16 v[58:61], v[82:85], v[106:109], v[58:61]
	v_mfma_f32_16x16x32_bf16 v[54:57], v[74:77], v[114:117], v[54:57]
	v_mfma_f32_16x16x32_bf16 v[38:41], v[82:85], v[114:117], v[38:41]
	v_mfma_f32_16x16x32_bf16 v[30:33], v[74:77], v[122:125], v[30:33]
	v_mfma_f32_16x16x32_bf16 v[22:25], v[82:85], v[122:125], v[22:25]
	v_mfma_f32_16x16x32_bf16 v[14:17], v[74:77], v[130:133], v[14:17]
	v_mfma_f32_16x16x32_bf16 v[6:9], v[82:85], v[130:133], v[6:9]
	v_mfma_f32_16x16x32_bf16 v[62:65], v[78:81], v[110:113], v[62:65]
	v_mfma_f32_16x16x32_bf16 v[58:61], v[86:89], v[110:113], v[58:61]
	v_mfma_f32_16x16x32_bf16 v[54:57], v[78:81], v[118:121], v[54:57]
	v_mfma_f32_16x16x32_bf16 v[38:41], v[86:89], v[118:121], v[38:41]
	v_mfma_f32_16x16x32_bf16 v[30:33], v[78:81], v[126:129], v[30:33]
	v_mfma_f32_16x16x32_bf16 v[22:25], v[86:89], v[126:129], v[22:25]
	v_mfma_f32_16x16x32_bf16 v[14:17], v[78:81], v[134:137], v[14:17]
	v_mfma_f32_16x16x32_bf16 v[6:9], v[86:89], v[134:137], v[6:9]
	v_mfma_f32_16x16x32_bf16 v[50:53], v[90:93], v[106:109], v[50:53]
	s_or_b32 s29, s28, 0x80
	v_mfma_f32_16x16x32_bf16 v[46:49], v[98:101], v[106:109], v[46:49]
	v_mfma_f32_16x16x32_bf16 v[42:45], v[90:93], v[114:117], v[42:45]
	v_mfma_f32_16x16x32_bf16 v[34:37], v[98:101], v[114:117], v[34:37]
	v_mfma_f32_16x16x32_bf16 v[26:29], v[90:93], v[122:125], v[26:29]
	v_mfma_f32_16x16x32_bf16 v[18:21], v[98:101], v[122:125], v[18:21]
	v_mfma_f32_16x16x32_bf16 v[10:13], v[90:93], v[130:133], v[10:13]
	v_mfma_f32_16x16x32_bf16 v[2:5], v[98:101], v[130:133], v[2:5]
	v_mfma_f32_16x16x32_bf16 v[50:53], v[94:97], v[110:113], v[50:53]
	v_mfma_f32_16x16x32_bf16 v[46:49], v[102:105], v[110:113], v[46:49]
	v_mfma_f32_16x16x32_bf16 v[42:45], v[94:97], v[118:121], v[42:45]
	v_mfma_f32_16x16x32_bf16 v[34:37], v[102:105], v[118:121], v[34:37]
	v_mfma_f32_16x16x32_bf16 v[26:29], v[94:97], v[126:129], v[26:29]
	v_mfma_f32_16x16x32_bf16 v[18:21], v[102:105], v[126:129], v[18:21]
	v_mfma_f32_16x16x32_bf16 v[10:13], v[94:97], v[134:137], v[10:13]
	v_mfma_f32_16x16x32_bf16 v[2:5], v[102:105], v[134:137], v[2:5]
	s_setprio 0
	s_barrier
	s_mov_b32 m0, s20
	s_add_i32 s28, s28, 0x80080
	buffer_load_dwordx4 v67, s[40:43], s29 offen lds
	s_mov_b32 m0, s21
	s_nop 0
	buffer_load_dwordx4 v69, s[40:43], s29 offen lds
	s_mov_b32 m0, s24
	s_nop 0
	buffer_load_dwordx4 v67, s[40:43], s28 offen lds
	s_mov_b32 m0, s25
	s_nop 0
	buffer_load_dwordx4 v69, s[40:43], s28 offen lds
	s_mov_b32 m0, s22
	s_nop 0
	buffer_load_dwordx4 v66, s[76:79], s30 offen lds
	s_mov_b32 m0, s23
	s_nop 0
	buffer_load_dwordx4 v68, s[76:79], s30 offen lds
	s_waitcnt vmcnt(6)
	s_barrier
	s_barrier
	s_addk_i32 s26, 0x100
	s_add_i32 s27, s27, 2
	s_cmp_gt_u32 s27, 29
	s_cbranch_scc0 .LBB0_1668
	s_cmpk_lt_u32 s11, 0x100
	s_cbranch_scc0 .LBB0_1671
	s_barrier

; #define PG8_STAGEX(rs, bufoff, soff, voff) do { _Pragma("unroll") for (int _i = 0; _i < 2; ++_i) \
;         __builtin_amdgcn_raw_ptr_buffer_load_lds(rs, (LAS unsigned*)(lds + (bufoff) + ldsw + _i * 8192), 16, (voff)[_i], (soff), 0, 0); } while (0)
; #define PG8_LDA(dst, b, h) do { _Pragma("unroll") for (int m = 0; m < 4; ++m) _Pragma("unroll") for (int k = 0; k < 2; ++k) dst[m][k] = *(const LAS bf16x8*)(lds + PG8_SA(b, h) + aoff + m * 2048 + k * 1024); } while (0)
; #define PG8_LDB(dst, b, h) do { _Pragma("unroll") for (int n = 0; n < 2; ++n) _Pragma("unroll") for (int k = 0; k < 2; ++k) dst[n][k] = *(const LAS bf16x8*)(lds + PG8_SB(b, h) + boff + n * 2048 + k * 1024); } while (0)
; #define PG8_WAIT_V(n) asm volatile("s_waitcnt vmcnt(" #n ")" ::: "memory")
; #define PG8_WAIT_L(n) asm volatile("s_waitcnt lgkmcnt(" #n ")" ::: "memory")
; #define PG8_BAR __builtin_amdgcn_s_barrier()
; #define PG8_SCHED __builtin_amdgcn_sched_barrier(0)
;     ...
;             PG8_LDB(B0, 0, 0); PG8_LDB(B1, 0, 1); PG8_SCHED; PG8_LDA(At, 0, 0); PG8_STAGEX(rsA, PG8_SA(1, 1), a1 + hstepA, voffA);
;             PG8_WAIT_V(8); PG8_WAIT_L(0); PG8_BAR; PG8_MMA(0, 0, At, B0); PG8_MMA(0, 1, At, B1); PG8_BAR; PG8_SCHED;
;             PG8_LDA(At, 0, 1); PG8_STAGEX(rsB, PG8_SB(0, 0), b2, voffB); PG8_STAGEX(rsB, PG8_SB(0, 1), b2 + hstepB, voffB); PG8_STAGEX(rsA, PG8_SA(0, 0), a2, voffA);
;             PG8_WAIT_V(8); PG8_WAIT_L(0); PG8_BAR; PG8_MMA(1, 0, At, B0); PG8_MMA(1, 1, At, B1); PG8_BAR; PG8_SCHED;
.LBB0_1750:
	v_add_u32_e32 v70, 0x10000, v241
	ds_read_b128 v[134:137], v70
	ds_read_b128 v[138:141], v70 offset:1024
	ds_read_b128 v[142:145], v70 offset:2048
	ds_read_b128 v[146:149], v70 offset:3072
	v_add_u32_e32 v70, 0x14000, v241
	ds_read_b128 v[150:153], v70
	ds_read_b128 v[154:157], v70 offset:1024
	ds_read_b128 v[158:161], v70 offset:2048
	ds_read_b128 v[162:165], v70 offset:3072
	s_add_i32 s46, s40, 0xffea8080
	s_cmpk_eq_i32 s60, 0x52
	s_cselect_b32 s63, s30, s46
	s_cselect_b32 s62, s31, s41
	s_or_b32 s61, s63, 0x80
	s_mov_b32 m0, s72
	ds_read_b128 v[166:169], v242
	ds_read_b128 v[170:173], v242 offset:1024
	ds_read_b128 v[184:187], v242 offset:2048
	ds_read_b128 v[188:191], v242 offset:3072
	ds_read_b128 v[192:195], v242 offset:4096
	ds_read_b128 v[196:199], v242 offset:5120
	ds_read_b128 v[200:203], v242 offset:6144
	ds_read_b128 v[204:207], v242 offset:7168
	buffer_load_dwordx4 v178, s[76:79], s40 offen lds
	s_mov_b32 m0, s73
	s_nop 0
	buffer_load_dwordx4 v237, s[76:79], s40 offen lds
	s_waitcnt vmcnt(8)
	s_waitcnt lgkmcnt(0)
	s_barrier
	s_setprio 1
	v_mfma_f32_16x16x32_bf16 v[130:133], v[134:137], v[166:169], v[130:133]
	v_mfma_f32_16x16x32_bf16 v[126:129], v[142:145], v[166:169], v[126:129]
	v_mfma_f32_16x16x32_bf16 v[122:125], v[134:137], v[184:187], v[122:125]
	v_mfma_f32_16x16x32_bf16 v[118:121], v[142:145], v[184:187], v[118:121]
	v_mfma_f32_16x16x32_bf16 v[114:117], v[134:137], v[192:195], v[114:117]
	v_mfma_f32_16x16x32_bf16 v[110:113], v[142:145], v[192:195], v[110:113]
	v_mfma_f32_16x16x32_bf16 v[106:109], v[134:137], v[200:203], v[106:109]
	v_mfma_f32_16x16x32_bf16 v[102:105], v[142:145], v[200:203], v[102:105]
	v_mfma_f32_16x16x32_bf16 v[130:133], v[138:141], v[170:173], v[130:133]
	v_mfma_f32_16x16x32_bf16 v[126:129], v[146:149], v[170:173], v[126:129]
	v_mfma_f32_16x16x32_bf16 v[122:125], v[138:141], v[188:191], v[122:125]
	v_mfma_f32_16x16x32_bf16 v[118:121], v[146:149], v[188:191], v[118:121]
	v_mfma_f32_16x16x32_bf16 v[114:117], v[138:141], v[196:199], v[114:117]
	v_mfma_f32_16x16x32_bf16 v[110:113], v[146:149], v[196:199], v[110:113]
	v_mfma_f32_16x16x32_bf16 v[106:109], v[138:141], v[204:207], v[106:109]
	v_mfma_f32_16x16x32_bf16 v[102:105], v[146:149], v[204:207], v[102:105]
	v_mfma_f32_16x16x32_bf16 v[62:65], v[150:153], v[166:169], v[62:65]
	v_mfma_f32_16x16x32_bf16 v[58:61], v[158:161], v[166:169], v[58:61]
	v_mfma_f32_16x16x32_bf16 v[54:57], v[150:153], v[184:187], v[54:57]
	v_mfma_f32_16x16x32_bf16 v[50:53], v[158:161], v[184:187], v[50:53]
	v_mfma_f32_16x16x32_bf16 v[46:49], v[150:153], v[192:195], v[46:49]
	v_mfma_f32_16x16x32_bf16 v[42:45], v[158:161], v[192:195], v[42:45]
	v_mfma_f32_16x16x32_bf16 v[38:41], v[150:153], v[200:203], v[38:41]
	v_mfma_f32_16x16x32_bf16 v[34:37], v[158:161], v[200:203], v[34:37]
	v_mfma_f32_16x16x32_bf16 v[62:65], v[154:157], v[170:173], v[62:65]
	v_mfma_f32_16x16x32_bf16 v[58:61], v[162:165], v[170:173], v[58:61]
	v_mfma_f32_16x16x32_bf16 v[54:57], v[154:157], v[188:191], v[54:57]
	v_mfma_f32_16x16x32_bf16 v[50:53], v[162:165], v[188:191], v[50:53]
	v_mfma_f32_16x16x32_bf16 v[46:49], v[154:157], v[196:199], v[46:49]
	v_mfma_f32_16x16x32_bf16 v[42:45], v[162:165], v[196:199], v[42:45]
	v_mfma_f32_16x16x32_bf16 v[38:41], v[154:157], v[204:207], v[38:41]
	v_mfma_f32_16x16x32_bf16 v[34:37], v[162:165], v[204:207], v[34:37]
	s_setprio 0
	s_barrier
	s_mov_b32 m0, s17
	s_mov_b32 s46, s78
	s_mov_b32 s47, s79
	ds_read_b128 v[166:169], v242 offset:16384
	ds_read_b128 v[170:173], v242 offset:17408
	ds_read_b128 v[184:187], v242 offset:18432
	ds_read_b128 v[188:191], v242 offset:19456
	ds_read_b128 v[192:195], v242 offset:20480
	ds_read_b128 v[196:199], v242 offset:21504
	ds_read_b128 v[200:203], v242 offset:22528
	ds_read_b128 v[204:207], v242 offset:23552
	buffer_load_dwordx4 v179, s[44:47], s62 offen lds
	s_mov_b32 m0, s18
	s_add_i32 s64, s62, 0x158000
	buffer_load_dwordx4 v238, s[44:47], s62 offen lds
	s_mov_b32 m0, s19
	s_nop 0
	buffer_load_dwordx4 v179, s[44:47], s64 offen lds
	s_mov_b32 m0, s20
	s_nop 0
	buffer_load_dwordx4 v238, s[44:47], s64 offen lds
	s_mov_b32 m0, s16
	s_nop 0
	buffer_load_dwordx4 v178, s[76:79], s63 offen lds
	s_mov_b32 m0, s21
	s_nop 0
	buffer_load_dwordx4 v237, s[76:79], s63 offen lds
	s_waitcnt vmcnt(8)
	s_waitcnt lgkmcnt(0)
	s_barrier
	s_setprio 1
	v_mfma_f32_16x16x32_bf16 v[98:101], v[134:137], v[166:169], v[98:101]
	v_mfma_f32_16x16x32_bf16 v[94:97], v[142:145], v[166:169], v[94:97]
	v_mfma_f32_16x16x32_bf16 v[90:93], v[134:137], v[184:187], v[90:93]
	v_mfma_f32_16x16x32_bf16 v[86:89], v[142:145], v[184:187], v[86:89]
	v_mfma_f32_16x16x32_bf16 v[82:85], v[134:137], v[192:195], v[82:85]
	v_mfma_f32_16x16x32_bf16 v[76:79], v[142:145], v[192:195], v[78:81]
	v_mfma_f32_16x16x32_bf16 v[70:73], v[134:137], v[200:203], v[72:75]
	v_mfma_f32_16x16x32_bf16 v[66:69], v[142:145], v[200:203], v[66:69]
	v_mfma_f32_16x16x32_bf16 v[98:101], v[138:141], v[170:173], v[98:101]
	v_mfma_f32_16x16x32_bf16 v[94:97], v[146:149], v[170:173], v[94:97]
	v_mfma_f32_16x16x32_bf16 v[90:93], v[138:141], v[188:191], v[90:93]
	v_mfma_f32_16x16x32_bf16 v[86:89], v[146:149], v[188:191], v[86:89]
	v_mfma_f32_16x16x32_bf16 v[82:85], v[138:141], v[196:199], v[82:85]
	v_mfma_f32_16x16x32_bf16 v[76:79], v[146:149], v[196:199], v[76:79]
	v_mfma_f32_16x16x32_bf16 v[70:73], v[138:141], v[204:207], v[70:73]
	v_mfma_f32_16x16x32_bf16 v[66:69], v[146:149], v[204:207], v[66:69]
	v_mfma_f32_16x16x32_bf16 v[30:33], v[150:153], v[166:169], v[30:33]
	v_mfma_f32_16x16x32_bf16 v[26:29], v[158:161], v[166:169], v[26:29]
	v_mfma_f32_16x16x32_bf16 v[22:25], v[150:153], v[184:187], v[22:25]
	v_mfma_f32_16x16x32_bf16 v[18:21], v[158:161], v[184:187], v[18:21]
	v_mfma_f32_16x16x32_bf16 v[14:17], v[150:153], v[192:195], v[14:17]
	v_mfma_f32_16x16x32_bf16 v[10:13], v[158:161], v[192:195], v[10:13]
	v_mfma_f32_16x16x32_bf16 v[6:9], v[150:153], v[200:203], v[6:9]
	v_mfma_f32_16x16x32_bf16 v[2:5], v[158:161], v[200:203], v[2:5]
	v_mfma_f32_16x16x32_bf16 v[30:33], v[154:157], v[170:173], v[30:33]
	v_mfma_f32_16x16x32_bf16 v[26:29], v[162:165], v[170:173], v[26:29]
	v_mfma_f32_16x16x32_bf16 v[22:25], v[154:157], v[188:191], v[22:25]
	v_mfma_f32_16x16x32_bf16 v[18:21], v[162:165], v[188:191], v[18:21]
	v_mfma_f32_16x16x32_bf16 v[14:17], v[154:157], v[196:199], v[14:17]
	v_mfma_f32_16x16x32_bf16 v[10:13], v[162:165], v[196:199], v[10:13]
	v_mfma_f32_16x16x32_bf16 v[6:9], v[154:157], v[204:207], v[6:9]
	v_mfma_f32_16x16x32_bf16 v[2:5], v[162:165], v[204:207], v[2:5]
	s_setprio 0
	s_barrier
; #define PG8_STAGEX(rs, bufoff, soff, voff) do { _Pragma("unroll") for (int _i = 0; _i < 2; ++_i) \
;         __builtin_amdgcn_raw_ptr_buffer_load_lds(rs, (LAS unsigned*)(lds + (bufoff) + ldsw + _i * 8192), 16, (voff)[_i], (soff), 0, 0); } while (0)
; #define PG8_LDA(dst, b, h) do { _Pragma("unroll") for (int m = 0; m < 4; ++m) _Pragma("unroll") for (int k = 0; k < 2; ++k) dst[m][k] = *(const LAS bf16x8*)(lds + PG8_SA(b, h) + aoff + m * 2048 + k * 1024); } while (0)
; #define PG8_LDB(dst, b, h) do { _Pragma("unroll") for (int n = 0; n < 2; ++n) _Pragma("unroll") for (int k = 0; k < 2; ++k) dst[n][k] = *(const LAS bf16x8*)(lds + PG8_SB(b, h) + boff + n * 2048 + k * 1024); } while (0)
; #define PG8_WAIT_V(n) asm volatile("s_waitcnt vmcnt(" #n ")" ::: "memory")
; #define PG8_WAIT_L(n) asm volatile("s_waitcnt lgkmcnt(" #n ")" ::: "memory")
; #define PG8_BAR __builtin_amdgcn_s_barrier()
; #define PG8_SCHED __builtin_amdgcn_sched_barrier(0)
;     ...
;             PG8_LDB(B0, 1, 0); PG8_LDB(B1, 1, 1); PG8_SCHED; PG8_LDA(At, 1, 0); PG8_STAGEX(rsA, PG8_SA(0, 1), a2 + hstepA, voffA);
;             PG8_WAIT_V(8); PG8_WAIT_L(0); PG8_BAR; PG8_MMA(0, 0, At, B0); PG8_MMA(0, 1, At, B1); PG8_BAR; PG8_SCHED;
;             PG8_LDA(At, 1, 1); PG8_STAGEX(rsB, PG8_SB(1, 0), b3, voffB); PG8_STAGEX(rsB, PG8_SB(1, 1), b3 + hstepB, voffB); PG8_STAGEX(rsA, PG8_SA(1, 0), a3, voffA);
;             PG8_WAIT_V(8); PG8_WAIT_L(0); PG8_BAR; PG8_MMA(1, 0, At, B0); PG8_MMA(1, 1, At, B1); PG8_BAR; PG8_SCHED;
;         }
	v_add_u32_e32 v74, 0x18000, v241
	ds_read_b128 v[134:137], v74
	ds_read_b128 v[138:141], v74 offset:1024
	ds_read_b128 v[142:145], v74 offset:2048
	ds_read_b128 v[146:149], v74 offset:3072
	v_add_u32_e32 v74, 0x1c000, v241
	ds_read_b128 v[150:153], v74
	ds_read_b128 v[154:157], v74 offset:1024
	ds_read_b128 v[158:161], v74 offset:2048
	ds_read_b128 v[162:165], v74 offset:3072
	s_add_i32 s63, s63, 0x158000
	s_mov_b32 m0, s22
	ds_read_b128 v[166:169], v242 offset:32768
	ds_read_b128 v[170:173], v242 offset:33792
	ds_read_b128 v[184:187], v242 offset:34816
	ds_read_b128 v[188:191], v242 offset:35840
	ds_read_b128 v[192:195], v242 offset:36864
	ds_read_b128 v[196:199], v242 offset:37888
	ds_read_b128 v[200:203], v242 offset:38912
	ds_read_b128 v[204:207], v242 offset:39936
	buffer_load_dwordx4 v178, s[76:79], s63 offen lds
	s_mov_b32 m0, s23
	s_nop 0
	buffer_load_dwordx4 v237, s[76:79], s63 offen lds
	s_waitcnt vmcnt(8)
	s_waitcnt lgkmcnt(0)
	s_barrier
	s_setprio 1
	v_mfma_f32_16x16x32_bf16 v[130:133], v[134:137], v[166:169], v[130:133]
	v_mfma_f32_16x16x32_bf16 v[126:129], v[142:145], v[166:169], v[126:129]
	v_mfma_f32_16x16x32_bf16 v[122:125], v[134:137], v[184:187], v[122:125]
	v_mfma_f32_16x16x32_bf16 v[118:121], v[142:145], v[184:187], v[118:121]
	v_mfma_f32_16x16x32_bf16 v[114:117], v[134:137], v[192:195], v[114:117]
	v_mfma_f32_16x16x32_bf16 v[110:113], v[142:145], v[192:195], v[110:113]
	v_mfma_f32_16x16x32_bf16 v[106:109], v[134:137], v[200:203], v[106:109]
	v_mfma_f32_16x16x32_bf16 v[102:105], v[142:145], v[200:203], v[102:105]
	v_mfma_f32_16x16x32_bf16 v[130:133], v[138:141], v[170:173], v[130:133]
	v_mfma_f32_16x16x32_bf16 v[126:129], v[146:149], v[170:173], v[126:129]
	v_mfma_f32_16x16x32_bf16 v[122:125], v[138:141], v[188:191], v[122:125]
	v_mfma_f32_16x16x32_bf16 v[118:121], v[146:149], v[188:191], v[118:121]
	v_mfma_f32_16x16x32_bf16 v[114:117], v[138:141], v[196:199], v[114:117]
	v_mfma_f32_16x16x32_bf16 v[110:113], v[146:149], v[196:199], v[110:113]
	v_mfma_f32_16x16x32_bf16 v[106:109], v[138:141], v[204:207], v[106:109]
	v_mfma_f32_16x16x32_bf16 v[102:105], v[146:149], v[204:207], v[102:105]
	v_mfma_f32_16x16x32_bf16 v[62:65], v[150:153], v[166:169], v[62:65]
	v_mfma_f32_16x16x32_bf16 v[58:61], v[158:161], v[166:169], v[58:61]
	v_mfma_f32_16x16x32_bf16 v[54:57], v[150:153], v[184:187], v[54:57]
	v_mfma_f32_16x16x32_bf16 v[50:53], v[158:161], v[184:187], v[50:53]
	v_mfma_f32_16x16x32_bf16 v[46:49], v[150:153], v[192:195], v[46:49]
	v_mfma_f32_16x16x32_bf16 v[42:45], v[158:161], v[192:195], v[42:45]
	v_mfma_f32_16x16x32_bf16 v[38:41], v[150:153], v[200:203], v[38:41]
	v_mfma_f32_16x16x32_bf16 v[34:37], v[158:161], v[200:203], v[34:37]
	v_mfma_f32_16x16x32_bf16 v[62:65], v[154:157], v[170:173], v[62:65]
	v_mfma_f32_16x16x32_bf16 v[58:61], v[162:165], v[170:173], v[58:61]
	v_mfma_f32_16x16x32_bf16 v[54:57], v[154:157], v[188:191], v[54:57]
	v_mfma_f32_16x16x32_bf16 v[50:53], v[162:165], v[188:191], v[50:53]
	v_mfma_f32_16x16x32_bf16 v[46:49], v[154:157], v[196:199], v[46:49]
	v_mfma_f32_16x16x32_bf16 v[42:45], v[162:165], v[196:199], v[42:45]
	v_mfma_f32_16x16x32_bf16 v[38:41], v[154:157], v[204:207], v[38:41]
	v_mfma_f32_16x16x32_bf16 v[34:37], v[162:165], v[204:207], v[34:37]
	s_setprio 0
	s_barrier
	s_mov_b32 m0, s54
	s_or_b32 s63, s62, 0x80
	ds_read_b128 v[166:169], v242 offset:49152
	ds_read_b128 v[170:173], v242 offset:50176
	ds_read_b128 v[184:187], v242 offset:51200
	ds_read_b128 v[188:191], v242 offset:52224
	ds_read_b128 v[192:195], v242 offset:53248
	ds_read_b128 v[196:199], v242 offset:54272
	ds_read_b128 v[200:203], v242 offset:55296
	ds_read_b128 v[204:207], v242 offset:56320
	buffer_load_dwordx4 v179, s[44:47], s63 offen lds
	s_mov_b32 m0, s55
	s_add_i32 s62, s62, 0x158080
	buffer_load_dwordx4 v238, s[44:47], s63 offen lds
	s_mov_b32 m0, s70
	s_nop 0
	buffer_load_dwordx4 v179, s[44:47], s62 offen lds
	s_mov_b32 m0, s71
	s_nop 0
	buffer_load_dwordx4 v238, s[44:47], s62 offen lds
	s_mov_b32 m0, s68
	s_nop 0
	buffer_load_dwordx4 v178, s[76:79], s61 offen lds
	s_mov_b32 m0, s69
	s_nop 0
	buffer_load_dwordx4 v237, s[76:79], s61 offen lds
	s_waitcnt vmcnt(8)
	s_waitcnt lgkmcnt(0)
	s_barrier
	s_setprio 1
	v_mfma_f32_16x16x32_bf16 v[98:101], v[134:137], v[166:169], v[98:101]
	v_mfma_f32_16x16x32_bf16 v[94:97], v[142:145], v[166:169], v[94:97]
	v_mfma_f32_16x16x32_bf16 v[90:93], v[134:137], v[184:187], v[90:93]
	v_mfma_f32_16x16x32_bf16 v[86:89], v[142:145], v[184:187], v[86:89]
	v_mfma_f32_16x16x32_bf16 v[80:83], v[134:137], v[192:195], v[82:85]
	v_mfma_f32_16x16x32_bf16 v[74:77], v[142:145], v[192:195], v[76:79]
	v_mfma_f32_16x16x32_bf16 v[70:73], v[134:137], v[200:203], v[70:73]
	v_mfma_f32_16x16x32_bf16 v[66:69], v[142:145], v[200:203], v[66:69]
	v_mfma_f32_16x16x32_bf16 v[98:101], v[138:141], v[170:173], v[98:101]
	v_mfma_f32_16x16x32_bf16 v[94:97], v[146:149], v[170:173], v[94:97]
	v_mfma_f32_16x16x32_bf16 v[90:93], v[138:141], v[188:191], v[90:93]
	v_mfma_f32_16x16x32_bf16 v[86:89], v[146:149], v[188:191], v[86:89]
	v_mfma_f32_16x16x32_bf16 v[82:85], v[138:141], v[196:199], v[80:83]
	v_mfma_f32_16x16x32_bf16 v[78:81], v[146:149], v[196:199], v[74:77]
	v_mfma_f32_16x16x32_bf16 v[72:75], v[138:141], v[204:207], v[70:73]
	v_mfma_f32_16x16x32_bf16 v[66:69], v[146:149], v[204:207], v[66:69]
	v_mfma_f32_16x16x32_bf16 v[30:33], v[150:153], v[166:169], v[30:33]
	v_mfma_f32_16x16x32_bf16 v[26:29], v[158:161], v[166:169], v[26:29]
	v_mfma_f32_16x16x32_bf16 v[22:25], v[150:153], v[184:187], v[22:25]
	v_mfma_f32_16x16x32_bf16 v[18:21], v[158:161], v[184:187], v[18:21]
	v_mfma_f32_16x16x32_bf16 v[14:17], v[150:153], v[192:195], v[14:17]
	v_mfma_f32_16x16x32_bf16 v[10:13], v[158:161], v[192:195], v[10:13]
	v_mfma_f32_16x16x32_bf16 v[6:9], v[150:153], v[200:203], v[6:9]
	v_mfma_f32_16x16x32_bf16 v[2:5], v[158:161], v[200:203], v[2:5]
	v_mfma_f32_16x16x32_bf16 v[30:33], v[154:157], v[170:173], v[30:33]
	v_mfma_f32_16x16x32_bf16 v[26:29], v[162:165], v[170:173], v[26:29]
	v_mfma_f32_16x16x32_bf16 v[22:25], v[154:157], v[188:191], v[22:25]
	v_mfma_f32_16x16x32_bf16 v[18:21], v[162:165], v[188:191], v[18:21]
	v_mfma_f32_16x16x32_bf16 v[14:17], v[154:157], v[196:199], v[14:17]
	v_mfma_f32_16x16x32_bf16 v[10:13], v[162:165], v[196:199], v[10:13]
	v_mfma_f32_16x16x32_bf16 v[6:9], v[154:157], v[204:207], v[6:9]
	v_mfma_f32_16x16x32_bf16 v[2:5], v[162:165], v[204:207], v[2:5]
	s_setprio 0
	s_barrier
	s_add_i32 s60, s60, 2
	s_addk_i32 s40, 0x100
	s_addk_i32 s41, 0x100
	s_cmpk_gt_u32 s60, 0x53
	s_cbranch_scc0 .LBB0_1750
	s_and_b64 vcc, exec, s[50:51]
	s_cbranch_vccz .LBB0_1753
	s_barrier
